# lever 2 load-segment de-serialisation: in all GEMM K-loops the loop-invariant-address ds_read_b128 (A fragments) issue first in each load segment, ahead of the SALU/VALU address block (on top of v7)
# speedup vs baseline: 1.0022x; 1.0019x over previous
; #define PG8_STAGE(bufoff, gbase, voff) do { _Pragma("unroll") for (int _i = 0; _i < 2; ++_i) \
;         __builtin_amdgcn_global_load_lds((const unsigned*)((const char*)(gbase) + (voff)[_i]), (PG8_LAS unsigned*)(lds + (bufoff) + ldsw + _i * 8192), 16, 0, 0); } while (0)
; #define PG8_LDA(dst, b, h) do { _Pragma("unroll") for (int m = 0; m < 4; ++m) _Pragma("unroll") for (int k = 0; k < 2; ++k) dst[m][k] = *(const PG8_LAS bf16x8*)(lds + PG8_SA(b, h) + aoff + m * 2048 + k * 1024); } while (0)
; #define PG8_LDB(dst, b, h) do { _Pragma("unroll") for (int n = 0; n < 2; ++n) _Pragma("unroll") for (int k = 0; k < 2; ++k) dst[n][k] = *(const PG8_LAS bf16x8*)(lds + PG8_SB(b, h) + boff + n * 2048 + k * 1024); } while (0)
; #define PG8_MMA(ai, bj, At, Bt) do { __builtin_amdgcn_s_setprio(1); _Pragma("unroll") for (int m = 0; m < 4; ++m) _Pragma("unroll") for (int n = 0; n < 2; ++n) _Pragma("unroll") for (int k = 0; k < 2; ++k) \
;         acc[ai][bj][m][n] = __builtin_amdgcn_mfma_f32_16x16x32_bf16(Bt[n][k], At[m][k], acc[ai][bj][m][n], 0, 0, 0); __builtin_amdgcn_s_setprio(0); } while (0)
; #define PG8_WAIT_V(n) asm volatile("s_waitcnt vmcnt(" #n ")" ::: "memory")
; #define PG8_WAIT_L(n) asm volatile("s_waitcnt lgkmcnt(" #n ")" ::: "memory")
; #define PG8_BAR __builtin_amdgcn_s_barrier()
; #define PG8_SCHED __builtin_amdgcn_sched_barrier(0)
; template <class Epi, class Sched, bool ALIGN_EPI = false, bool SP2 = false>
; __device__ __forceinline__ void gemm_phase(PG8_LAS unsigned char* lds, const Gemm g, const Sched S, const Epi E) {
;     ...
;         for (int t = 0; t < nt; t += 2) {
;             const bool last = (t == nt - 2);
;             const char* a1 = cA + (size_t)(t + 1) * kstep;
;             const char* a2 = last ? nA : cA + (size_t)(t + 2) * kstep; const char* b2 = last ? nB : cB + (size_t)(t + 2) * kstep;
;             const char* a3 = a2 + kstep; const char* b3 = b2 + kstep;
;             if (last && has_next) S.a_ready(nxt);
;             if constexpr (SP2) {
;             PG8_LDB(B0, 0, 0); PG8_LDB(B1, 0, 1); PG8_SCHED; PG8_LDA(At, 0, 0); PG8_STAGE(PG8_SA(1, 1), a1 + hstep, voffA);
;             PG8_WAIT_V(8); PG8_WAIT_L(0); PG8_BAR; PG8_MMA(0, 0, At, B0); PG8_MMA(0, 1, At, B1); PG8_BAR; PG8_SCHED;
;             PG8_LDA(At, 0, 1); PG8_STAGE(PG8_SB(0, 0), b2, voffB); PG8_STAGE(PG8_SB(0, 1), b2 + hstep, voffB); PG8_STAGE(PG8_SA(0, 0), a2, voffA);
.LBB0_193:
	ds_read_b128 v[184:187], v145
	ds_read_b128 v[188:191], v145 offset:1024
	ds_read_b128 v[192:195], v145 offset:2048
	ds_read_b128 v[196:199], v145 offset:3072
	ds_read_b128 v[200:203], v145 offset:4096
	ds_read_b128 v[224:227], v145 offset:5120
	ds_read_b128 v[228:231], v145 offset:6144
	ds_read_b128 v[232:235], v145 offset:7168
	s_add_u32 s25, s56, 0xfff80080
	s_addc_u32 s26, s57, -1
	s_add_i32 s27, 0, 0x10000
	s_cmp_eq_u32 s24, 28
	s_cselect_b32 s65, s45, s26
	s_cselect_b32 s64, vcc_lo, s25
	v_add_u32_e32 v140, s27, v143
	s_cselect_b32 s59, s43, s15
	s_cselect_b32 s58, vcc_hi, s14
	s_add_i32 s25, 0, 0x14000
	ds_read_b128 v[146:149], v140
	ds_read_b128 v[150:153], v140 offset:1024
	ds_read_b128 v[154:157], v140 offset:2048
	ds_read_b128 v[158:161], v140 offset:3072
	v_add_u32_e32 v140, s25, v143
	ds_read_b128 v[168:171], v140
	ds_read_b128 v[172:175], v140 offset:1024
	ds_read_b128 v[176:179], v140 offset:2048
	ds_read_b128 v[180:183], v140 offset:3072
	v_lshl_add_u64 v[140:141], s[56:57], 0, v[136:137]
	s_add_i32 m0, s75, 0xc000
	s_nop 0
	global_load_lds_dwordx4 v[140:141], off
	v_lshl_add_u64 v[140:141], s[56:57], 0, v[138:139]
	s_add_i32 m0, s75, 0xe000
	s_nop 0
	global_load_lds_dwordx4 v[140:141], off
	s_waitcnt vmcnt(8)
	s_waitcnt lgkmcnt(0)
	s_barrier
	s_setprio 1
	v_mfma_f32_16x16x32_bf16 v[126:129], v[146:149], v[184:187], v[126:129]
	v_mfma_f32_16x16x32_bf16 v[126:129], v[150:153], v[188:191], v[126:129]
	v_mfma_f32_16x16x32_bf16 v[118:121], v[154:157], v[184:187], v[118:121]
	v_mfma_f32_16x16x32_bf16 v[118:121], v[158:161], v[188:191], v[118:121]
	v_mfma_f32_16x16x32_bf16 v[110:113], v[146:149], v[192:195], v[110:113]
	v_mfma_f32_16x16x32_bf16 v[110:113], v[150:153], v[196:199], v[110:113]
	v_mfma_f32_16x16x32_bf16 v[102:105], v[154:157], v[192:195], v[102:105]
	v_mfma_f32_16x16x32_bf16 v[102:105], v[158:161], v[196:199], v[102:105]
	v_mfma_f32_16x16x32_bf16 v[94:97], v[146:149], v[200:203], v[94:97]
	v_mfma_f32_16x16x32_bf16 v[94:97], v[150:153], v[224:227], v[94:97]
	v_mfma_f32_16x16x32_bf16 v[86:89], v[154:157], v[200:203], v[86:89]
	v_mfma_f32_16x16x32_bf16 v[86:89], v[158:161], v[224:227], v[86:89]
	v_mfma_f32_16x16x32_bf16 v[78:81], v[146:149], v[228:231], v[78:81]
	v_mfma_f32_16x16x32_bf16 v[78:81], v[150:153], v[232:235], v[78:81]
	v_mfma_f32_16x16x32_bf16 v[70:73], v[154:157], v[228:231], v[70:73]
	v_mfma_f32_16x16x32_bf16 v[70:73], v[158:161], v[232:235], v[70:73]
	v_mfma_f32_16x16x32_bf16 v[122:125], v[168:171], v[184:187], v[122:125]
	v_mfma_f32_16x16x32_bf16 v[122:125], v[172:175], v[188:191], v[122:125]
	v_mfma_f32_16x16x32_bf16 v[114:117], v[176:179], v[184:187], v[114:117]
	v_mfma_f32_16x16x32_bf16 v[114:117], v[180:183], v[188:191], v[114:117]
	v_mfma_f32_16x16x32_bf16 v[106:109], v[168:171], v[192:195], v[106:109]
	v_mfma_f32_16x16x32_bf16 v[106:109], v[172:175], v[196:199], v[106:109]
	v_mfma_f32_16x16x32_bf16 v[98:101], v[176:179], v[192:195], v[98:101]
	v_mfma_f32_16x16x32_bf16 v[98:101], v[180:183], v[196:199], v[98:101]
	v_mfma_f32_16x16x32_bf16 v[90:93], v[168:171], v[200:203], v[90:93]
	v_mfma_f32_16x16x32_bf16 v[90:93], v[172:175], v[224:227], v[90:93]
	v_mfma_f32_16x16x32_bf16 v[82:85], v[176:179], v[200:203], v[82:85]
	v_mfma_f32_16x16x32_bf16 v[82:85], v[180:183], v[224:227], v[82:85]
	v_mfma_f32_16x16x32_bf16 v[74:77], v[168:171], v[228:231], v[74:77]
	v_mfma_f32_16x16x32_bf16 v[74:77], v[172:175], v[232:235], v[74:77]
	v_mfma_f32_16x16x32_bf16 v[66:69], v[176:179], v[228:231], v[66:69]
	v_mfma_f32_16x16x32_bf16 v[66:69], v[180:183], v[232:235], v[66:69]
	s_setprio 0
	s_barrier
	ds_read_b128 v[184:187], v145 offset:16384
	ds_read_b128 v[188:191], v145 offset:17408
	ds_read_b128 v[192:195], v145 offset:18432
	ds_read_b128 v[196:199], v145 offset:19456
	ds_read_b128 v[200:203], v145 offset:20480
	ds_read_b128 v[224:227], v145 offset:21504
	ds_read_b128 v[228:231], v145 offset:22528
	ds_read_b128 v[232:235], v145 offset:23552
	s_add_i32 s26, s27, s74
	v_lshl_add_u64 v[140:141], s[58:59], 0, v[0:1]
	s_mov_b32 m0, s26
	s_nop 0
	global_load_lds_dwordx4 v[140:141], off
	s_add_i32 m0, s26, 0x2000
	s_add_u32 s26, s58, 0x80000
	v_lshl_add_u64 v[236:237], s[58:59], 0, v[130:131]
	s_addc_u32 s27, s59, 0
	s_add_i32 s25, s25, s74
	global_load_lds_dwordx4 v[236:237], off
	v_lshl_add_u64 v[238:239], s[26:27], 0, v[0:1]
	s_mov_b32 m0, s25
	v_lshl_add_u64 v[240:241], s[64:65], 0, v[132:133]
	global_load_lds_dwordx4 v[238:239], off
	v_lshl_add_u64 v[238:239], s[26:27], 0, v[130:131]
	s_add_i32 m0, s25, 0x2000
	s_nop 0
	global_load_lds_dwordx4 v[238:239], off
	v_lshl_add_u64 v[238:239], s[64:65], 0, v[134:135]
	s_mov_b32 m0, s75
	s_nop 0
	global_load_lds_dwordx4 v[238:239], off
	s_mov_b32 m0, s21
	s_nop 0
	global_load_lds_dwordx4 v[240:241], off
	s_waitcnt vmcnt(8)
	s_waitcnt lgkmcnt(0)
	s_barrier
; #define PG8_STAGE(bufoff, gbase, voff) do { _Pragma("unroll") for (int _i = 0; _i < 2; ++_i) \
;         __builtin_amdgcn_global_load_lds((const unsigned*)((const char*)(gbase) + (voff)[_i]), (PG8_LAS unsigned*)(lds + (bufoff) + ldsw + _i * 8192), 16, 0, 0); } while (0)
; #define PG8_LDA(dst, b, h) do { _Pragma("unroll") for (int m = 0; m < 4; ++m) _Pragma("unroll") for (int k = 0; k < 2; ++k) dst[m][k] = *(const PG8_LAS bf16x8*)(lds + PG8_SA(b, h) + aoff + m * 2048 + k * 1024); } while (0)
; #define PG8_LDB(dst, b, h) do { _Pragma("unroll") for (int n = 0; n < 2; ++n) _Pragma("unroll") for (int k = 0; k < 2; ++k) dst[n][k] = *(const PG8_LAS bf16x8*)(lds + PG8_SB(b, h) + boff + n * 2048 + k * 1024); } while (0)
; #define PG8_MMA(ai, bj, At, Bt) do { __builtin_amdgcn_s_setprio(1); _Pragma("unroll") for (int m = 0; m < 4; ++m) _Pragma("unroll") for (int n = 0; n < 2; ++n) _Pragma("unroll") for (int k = 0; k < 2; ++k) \
;         acc[ai][bj][m][n] = __builtin_amdgcn_mfma_f32_16x16x32_bf16(Bt[n][k], At[m][k], acc[ai][bj][m][n], 0, 0, 0); __builtin_amdgcn_s_setprio(0); } while (0)
; #define PG8_WAIT_V(n) asm volatile("s_waitcnt vmcnt(" #n ")" ::: "memory")
; #define PG8_WAIT_L(n) asm volatile("s_waitcnt lgkmcnt(" #n ")" ::: "memory")
; #define PG8_BAR __builtin_amdgcn_s_barrier()
; #define PG8_SCHED __builtin_amdgcn_sched_barrier(0)
; template <class Epi, class Sched, bool ALIGN_EPI = false, bool SP2 = false>
; __device__ __forceinline__ void gemm_phase(PG8_LAS unsigned char* lds, const Gemm g, const Sched S, const Epi E) {
;     ...
;             PG8_WAIT_V(8); PG8_WAIT_L(0); PG8_BAR; PG8_MMA(1, 0, At, B0); PG8_MMA(1, 1, At, B1); PG8_BAR; PG8_SCHED;
;             PG8_LDB(B0, 1, 0); PG8_LDB(B1, 1, 1); PG8_SCHED; PG8_LDA(At, 1, 0); PG8_STAGE(PG8_SA(0, 1), a2 + hstep, voffA);
;             PG8_WAIT_V(8); PG8_WAIT_L(0); PG8_BAR; PG8_MMA(0, 0, At, B0); PG8_MMA(0, 1, At, B1); PG8_BAR; PG8_SCHED;
	s_setprio 1
	v_mfma_f32_16x16x32_bf16 v[62:65], v[146:149], v[184:187], v[62:65]
	v_mfma_f32_16x16x32_bf16 v[62:65], v[150:153], v[188:191], v[62:65]
	v_mfma_f32_16x16x32_bf16 v[54:57], v[154:157], v[184:187], v[54:57]
	v_mfma_f32_16x16x32_bf16 v[54:57], v[158:161], v[188:191], v[54:57]
	v_mfma_f32_16x16x32_bf16 v[46:49], v[146:149], v[192:195], v[46:49]
	v_mfma_f32_16x16x32_bf16 v[46:49], v[150:153], v[196:199], v[46:49]
	v_mfma_f32_16x16x32_bf16 v[38:41], v[154:157], v[192:195], v[38:41]
	v_mfma_f32_16x16x32_bf16 v[38:41], v[158:161], v[196:199], v[38:41]
	v_mfma_f32_16x16x32_bf16 v[30:33], v[146:149], v[200:203], v[30:33]
	v_mfma_f32_16x16x32_bf16 v[30:33], v[150:153], v[224:227], v[30:33]
	v_mfma_f32_16x16x32_bf16 v[22:25], v[154:157], v[200:203], v[22:25]
	v_mfma_f32_16x16x32_bf16 v[22:25], v[158:161], v[224:227], v[22:25]
	v_mfma_f32_16x16x32_bf16 v[14:17], v[146:149], v[228:231], v[14:17]
	v_mfma_f32_16x16x32_bf16 v[14:17], v[150:153], v[232:235], v[14:17]
	v_mfma_f32_16x16x32_bf16 v[6:9], v[154:157], v[228:231], v[6:9]
	v_mfma_f32_16x16x32_bf16 v[6:9], v[158:161], v[232:235], v[6:9]
	v_mfma_f32_16x16x32_bf16 v[58:61], v[168:171], v[184:187], v[58:61]
	v_mfma_f32_16x16x32_bf16 v[58:61], v[172:175], v[188:191], v[58:61]
	v_mfma_f32_16x16x32_bf16 v[50:53], v[176:179], v[184:187], v[50:53]
	v_mfma_f32_16x16x32_bf16 v[50:53], v[180:183], v[188:191], v[50:53]
	v_mfma_f32_16x16x32_bf16 v[42:45], v[168:171], v[192:195], v[42:45]
	v_mfma_f32_16x16x32_bf16 v[42:45], v[172:175], v[196:199], v[42:45]
	v_mfma_f32_16x16x32_bf16 v[34:37], v[176:179], v[192:195], v[34:37]
	v_mfma_f32_16x16x32_bf16 v[34:37], v[180:183], v[196:199], v[34:37]
	v_mfma_f32_16x16x32_bf16 v[26:29], v[168:171], v[200:203], v[26:29]
	v_mfma_f32_16x16x32_bf16 v[26:29], v[172:175], v[224:227], v[26:29]
	v_mfma_f32_16x16x32_bf16 v[18:21], v[176:179], v[200:203], v[18:21]
	v_mfma_f32_16x16x32_bf16 v[18:21], v[180:183], v[224:227], v[18:21]
	v_mfma_f32_16x16x32_bf16 v[10:13], v[168:171], v[228:231], v[10:13]
	v_mfma_f32_16x16x32_bf16 v[10:13], v[172:175], v[232:235], v[10:13]
	v_mfma_f32_16x16x32_bf16 v[2:5], v[176:179], v[228:231], v[2:5]
	v_mfma_f32_16x16x32_bf16 v[2:5], v[180:183], v[232:235], v[2:5]
	s_setprio 0
	s_barrier
	ds_read_b128 v[184:187], v145 offset:32768
	ds_read_b128 v[188:191], v145 offset:33792
	ds_read_b128 v[192:195], v145 offset:34816
	ds_read_b128 v[196:199], v145 offset:35840
	ds_read_b128 v[200:203], v145 offset:36864
	ds_read_b128 v[224:227], v145 offset:37888
	ds_read_b128 v[228:231], v145 offset:38912
	ds_read_b128 v[232:235], v145 offset:39936
	s_add_i32 s25, 0, 0x18000
	s_add_i32 s30, 0, 0x1c000
	v_add_u32_e32 v158, s25, v143
	v_add_u32_e32 v167, s30, v143
	ds_read_b128 v[146:149], v158
	ds_read_b128 v[150:153], v158 offset:1024
	ds_read_b128 v[154:157], v158 offset:2048
	ds_read_b128 v[158:161], v158 offset:3072
	ds_read_b128 v[168:171], v167
	ds_read_b128 v[172:175], v167 offset:1024
	ds_read_b128 v[176:179], v167 offset:2048
	ds_read_b128 v[180:183], v167 offset:3072
	s_add_u32 s26, s64, 0x80000
	s_addc_u32 s27, s65, 0
	s_mov_b32 m0, s47
	v_lshl_add_u64 v[242:243], s[26:27], 0, v[134:135]
	global_load_lds_dwordx4 v[242:243], off
	v_lshl_add_u64 v[242:243], s[26:27], 0, v[132:133]
	s_mov_b32 m0, s77
	s_nop 0
	global_load_lds_dwordx4 v[242:243], off
	s_waitcnt vmcnt(8)
	s_waitcnt lgkmcnt(0)
	s_barrier
	s_setprio 1
	v_mfma_f32_16x16x32_bf16 v[126:129], v[146:149], v[184:187], v[126:129]
	v_mfma_f32_16x16x32_bf16 v[126:129], v[150:153], v[188:191], v[126:129]
	v_mfma_f32_16x16x32_bf16 v[118:121], v[154:157], v[184:187], v[118:121]
	v_mfma_f32_16x16x32_bf16 v[118:121], v[158:161], v[188:191], v[118:121]
	v_mfma_f32_16x16x32_bf16 v[110:113], v[146:149], v[192:195], v[110:113]
	v_mfma_f32_16x16x32_bf16 v[110:113], v[150:153], v[196:199], v[110:113]
	v_mfma_f32_16x16x32_bf16 v[102:105], v[154:157], v[192:195], v[102:105]
	v_mfma_f32_16x16x32_bf16 v[102:105], v[158:161], v[196:199], v[102:105]
	v_mfma_f32_16x16x32_bf16 v[94:97], v[146:149], v[200:203], v[94:97]
	v_mfma_f32_16x16x32_bf16 v[94:97], v[150:153], v[224:227], v[94:97]
	v_mfma_f32_16x16x32_bf16 v[86:89], v[154:157], v[200:203], v[86:89]
	v_mfma_f32_16x16x32_bf16 v[86:89], v[158:161], v[224:227], v[86:89]
	v_mfma_f32_16x16x32_bf16 v[78:81], v[146:149], v[228:231], v[78:81]
	v_mfma_f32_16x16x32_bf16 v[78:81], v[150:153], v[232:235], v[78:81]
	v_mfma_f32_16x16x32_bf16 v[70:73], v[154:157], v[228:231], v[70:73]
	v_mfma_f32_16x16x32_bf16 v[70:73], v[158:161], v[232:235], v[70:73]
	v_mfma_f32_16x16x32_bf16 v[122:125], v[168:171], v[184:187], v[122:125]
	v_mfma_f32_16x16x32_bf16 v[122:125], v[172:175], v[188:191], v[122:125]
	v_mfma_f32_16x16x32_bf16 v[114:117], v[176:179], v[184:187], v[114:117]
	v_mfma_f32_16x16x32_bf16 v[114:117], v[180:183], v[188:191], v[114:117]
	v_mfma_f32_16x16x32_bf16 v[106:109], v[168:171], v[192:195], v[106:109]
	v_mfma_f32_16x16x32_bf16 v[106:109], v[172:175], v[196:199], v[106:109]
	v_mfma_f32_16x16x32_bf16 v[98:101], v[176:179], v[192:195], v[98:101]
	v_mfma_f32_16x16x32_bf16 v[98:101], v[180:183], v[196:199], v[98:101]
	v_mfma_f32_16x16x32_bf16 v[90:93], v[168:171], v[200:203], v[90:93]
	v_mfma_f32_16x16x32_bf16 v[90:93], v[172:175], v[224:227], v[90:93]
	v_mfma_f32_16x16x32_bf16 v[82:85], v[176:179], v[200:203], v[82:85]
	v_mfma_f32_16x16x32_bf16 v[82:85], v[180:183], v[224:227], v[82:85]
	v_mfma_f32_16x16x32_bf16 v[74:77], v[168:171], v[228:231], v[74:77]
	v_mfma_f32_16x16x32_bf16 v[74:77], v[172:175], v[232:235], v[74:77]
	v_mfma_f32_16x16x32_bf16 v[66:69], v[176:179], v[228:231], v[66:69]
	v_mfma_f32_16x16x32_bf16 v[66:69], v[180:183], v[232:235], v[66:69]
	s_setprio 0
	s_barrier
; #define PG8_STAGE(bufoff, gbase, voff) do { _Pragma("unroll") for (int _i = 0; _i < 2; ++_i) \
;         __builtin_amdgcn_global_load_lds((const unsigned*)((const char*)(gbase) + (voff)[_i]), (PG8_LAS unsigned*)(lds + (bufoff) + ldsw + _i * 8192), 16, 0, 0); } while (0)
; #define PG8_LDA(dst, b, h) do { _Pragma("unroll") for (int m = 0; m < 4; ++m) _Pragma("unroll") for (int k = 0; k < 2; ++k) dst[m][k] = *(const PG8_LAS bf16x8*)(lds + PG8_SA(b, h) + aoff + m * 2048 + k * 1024); } while (0)
; #define PG8_MMA(ai, bj, At, Bt) do { __builtin_amdgcn_s_setprio(1); _Pragma("unroll") for (int m = 0; m < 4; ++m) _Pragma("unroll") for (int n = 0; n < 2; ++n) _Pragma("unroll") for (int k = 0; k < 2; ++k) \
;         acc[ai][bj][m][n] = __builtin_amdgcn_mfma_f32_16x16x32_bf16(Bt[n][k], At[m][k], acc[ai][bj][m][n], 0, 0, 0); __builtin_amdgcn_s_setprio(0); } while (0)
; #define PG8_WAIT_V(n) asm volatile("s_waitcnt vmcnt(" #n ")" ::: "memory")
; #define PG8_WAIT_L(n) asm volatile("s_waitcnt lgkmcnt(" #n ")" ::: "memory")
; #define PG8_BAR __builtin_amdgcn_s_barrier()
; #define PG8_SCHED __builtin_amdgcn_sched_barrier(0)
; template <class Epi, class Sched, bool ALIGN_EPI = false, bool SP2 = false>
; __device__ __forceinline__ void gemm_phase(PG8_LAS unsigned char* lds, const Gemm g, const Sched S, const Epi E) {
;     ...
;         for (int t = 0; t < nt; t += 2) {
;             const bool last = (t == nt - 2);
;             const char* a1 = cA + (size_t)(t + 1) * kstep;
;             const char* a2 = last ? nA : cA + (size_t)(t + 2) * kstep; const char* b2 = last ? nB : cB + (size_t)(t + 2) * kstep;
;             const char* a3 = a2 + kstep; const char* b3 = b2 + kstep;
;             if (last && has_next) S.a_ready(nxt);
;     ...
;             PG8_LDA(At, 1, 1); PG8_STAGE(PG8_SB(1, 0), b3, voffB); PG8_STAGE(PG8_SB(1, 1), b3 + hstep, voffB); PG8_STAGE(PG8_SA(1, 0), a3, voffA);
;             PG8_WAIT_V(8); PG8_WAIT_L(0); PG8_BAR; PG8_MMA(1, 0, At, B0); PG8_MMA(1, 1, At, B1); PG8_BAR; PG8_SCHED;
	ds_read_b128 v[184:187], v145 offset:49152
	ds_read_b128 v[188:191], v145 offset:50176
	ds_read_b128 v[192:195], v145 offset:51200
	ds_read_b128 v[196:199], v145 offset:52224
	ds_read_b128 v[200:203], v145 offset:53248
	ds_read_b128 v[224:227], v145 offset:54272
	ds_read_b128 v[228:231], v145 offset:55296
	ds_read_b128 v[232:235], v145 offset:56320
	s_add_i32 s25, s25, s74
	v_lshl_add_u64 v[140:141], v[140:141], 0, s[28:29]
	s_mov_b32 m0, s25
	s_nop 0
	global_load_lds_dwordx4 v[140:141], off
	s_add_i32 m0, s25, 0x2000
	s_add_u32 s26, s58, 0x80080
	v_lshl_add_u64 v[140:141], v[236:237], 0, s[28:29]
	s_addc_u32 s27, s59, 0
	s_add_i32 s25, s30, s74
	global_load_lds_dwordx4 v[140:141], off
	v_lshl_add_u64 v[140:141], s[26:27], 0, v[0:1]
	s_mov_b32 m0, s25
	s_nop 0
	global_load_lds_dwordx4 v[140:141], off
	v_lshl_add_u64 v[140:141], s[26:27], 0, v[130:131]
	s_add_i32 m0, s25, 0x2000
	s_nop 0
	global_load_lds_dwordx4 v[140:141], off
	v_lshl_add_u64 v[140:141], v[238:239], 0, s[28:29]
	s_mov_b32 m0, s62
	s_nop 0
	global_load_lds_dwordx4 v[140:141], off
	v_lshl_add_u64 v[140:141], v[240:241], 0, s[28:29]
	s_mov_b32 m0, s63
	s_nop 0
	global_load_lds_dwordx4 v[140:141], off
	s_waitcnt vmcnt(8)
	s_waitcnt lgkmcnt(0)
	s_barrier
	s_setprio 1
	v_mfma_f32_16x16x32_bf16 v[62:65], v[146:149], v[184:187], v[62:65]
	v_mfma_f32_16x16x32_bf16 v[62:65], v[150:153], v[188:191], v[62:65]
	v_mfma_f32_16x16x32_bf16 v[54:57], v[154:157], v[184:187], v[54:57]
	v_mfma_f32_16x16x32_bf16 v[54:57], v[158:161], v[188:191], v[54:57]
	v_mfma_f32_16x16x32_bf16 v[46:49], v[146:149], v[192:195], v[46:49]
	v_mfma_f32_16x16x32_bf16 v[46:49], v[150:153], v[196:199], v[46:49]
	v_mfma_f32_16x16x32_bf16 v[38:41], v[154:157], v[192:195], v[38:41]
	v_mfma_f32_16x16x32_bf16 v[38:41], v[158:161], v[196:199], v[38:41]
	v_mfma_f32_16x16x32_bf16 v[30:33], v[146:149], v[200:203], v[30:33]
	v_mfma_f32_16x16x32_bf16 v[30:33], v[150:153], v[224:227], v[30:33]
	v_mfma_f32_16x16x32_bf16 v[22:25], v[154:157], v[200:203], v[22:25]
	v_mfma_f32_16x16x32_bf16 v[22:25], v[158:161], v[224:227], v[22:25]
	v_mfma_f32_16x16x32_bf16 v[14:17], v[146:149], v[228:231], v[14:17]
	v_mfma_f32_16x16x32_bf16 v[14:17], v[150:153], v[232:235], v[14:17]
	v_mfma_f32_16x16x32_bf16 v[6:9], v[154:157], v[228:231], v[6:9]
	v_mfma_f32_16x16x32_bf16 v[6:9], v[158:161], v[232:235], v[6:9]
	v_mfma_f32_16x16x32_bf16 v[58:61], v[168:171], v[184:187], v[58:61]
	v_mfma_f32_16x16x32_bf16 v[58:61], v[172:175], v[188:191], v[58:61]
	v_mfma_f32_16x16x32_bf16 v[50:53], v[176:179], v[184:187], v[50:53]
	v_mfma_f32_16x16x32_bf16 v[50:53], v[180:183], v[188:191], v[50:53]
	v_mfma_f32_16x16x32_bf16 v[42:45], v[168:171], v[192:195], v[42:45]
	v_mfma_f32_16x16x32_bf16 v[42:45], v[172:175], v[196:199], v[42:45]
	v_mfma_f32_16x16x32_bf16 v[34:37], v[176:179], v[192:195], v[34:37]
	v_mfma_f32_16x16x32_bf16 v[34:37], v[180:183], v[196:199], v[34:37]
	v_mfma_f32_16x16x32_bf16 v[26:29], v[168:171], v[200:203], v[26:29]
	v_mfma_f32_16x16x32_bf16 v[26:29], v[172:175], v[224:227], v[26:29]
	v_mfma_f32_16x16x32_bf16 v[18:21], v[176:179], v[200:203], v[18:21]
	v_mfma_f32_16x16x32_bf16 v[18:21], v[180:183], v[224:227], v[18:21]
	v_mfma_f32_16x16x32_bf16 v[10:13], v[168:171], v[228:231], v[10:13]
	v_mfma_f32_16x16x32_bf16 v[10:13], v[172:175], v[232:235], v[10:13]
	v_mfma_f32_16x16x32_bf16 v[2:5], v[176:179], v[228:231], v[2:5]
	v_mfma_f32_16x16x32_bf16 v[2:5], v[180:183], v[232:235], v[2:5]
	s_setprio 0
	s_barrier
	s_add_i32 s24, s24, 2
	s_add_u32 s56, s56, 0x100
	s_addc_u32 s57, s57, 0
	s_add_u32 s14, s14, 0x100
	s_addc_u32 s15, s15, 0
	s_cmp_gt_u32 s24, 29
	s_cbranch_scc0 .LBB0_193
	s_and_b64 vcc, exec, s[40:41]
	s_cbranch_vccz .LBB0_196
	s_barrier

; #define PG8_STAGE(bufoff, gbase, voff) do { _Pragma("unroll") for (int _i = 0; _i < 2; ++_i) \
;         __builtin_amdgcn_global_load_lds((const unsigned*)((const char*)(gbase) + (voff)[_i]), (PG8_LAS unsigned*)(lds + (bufoff) + ldsw + _i * 8192), 16, 0, 0); } while (0)
; #define PG8_LDA(dst, b, h) do { _Pragma("unroll") for (int m = 0; m < 4; ++m) _Pragma("unroll") for (int k = 0; k < 2; ++k) dst[m][k] = *(const PG8_LAS bf16x8*)(lds + PG8_SA(b, h) + aoff + m * 2048 + k * 1024); } while (0)
; #define PG8_LDB(dst, b, h) do { _Pragma("unroll") for (int n = 0; n < 2; ++n) _Pragma("unroll") for (int k = 0; k < 2; ++k) dst[n][k] = *(const PG8_LAS bf16x8*)(lds + PG8_SB(b, h) + boff + n * 2048 + k * 1024); } while (0)
; #define PG8_MMA(ai, bj, At, Bt) do { __builtin_amdgcn_s_setprio(1); _Pragma("unroll") for (int m = 0; m < 4; ++m) _Pragma("unroll") for (int n = 0; n < 2; ++n) _Pragma("unroll") for (int k = 0; k < 2; ++k) \
;         acc[ai][bj][m][n] = __builtin_amdgcn_mfma_f32_16x16x32_bf16(Bt[n][k], At[m][k], acc[ai][bj][m][n], 0, 0, 0); __builtin_amdgcn_s_setprio(0); } while (0)
; #define PG8_WAIT_V(n) asm volatile("s_waitcnt vmcnt(" #n ")" ::: "memory")
; #define PG8_WAIT_L(n) asm volatile("s_waitcnt lgkmcnt(" #n ")" ::: "memory")
; #define PG8_BAR __builtin_amdgcn_s_barrier()
; #define PG8_SCHED __builtin_amdgcn_sched_barrier(0)
; template <class Epi, class Sched, bool ALIGN_EPI = false, bool SP2 = false>
; __device__ __forceinline__ void gemm_phase(PG8_LAS unsigned char* lds, const Gemm g, const Sched S, const Epi E) {
;     ...
;         for (int t = 0; t < nt; t += 2) {
;             const bool last = (t == nt - 2);
;             const char* a1 = cA + (size_t)(t + 1) * kstep;
;             const char* a2 = last ? nA : cA + (size_t)(t + 2) * kstep; const char* b2 = last ? nB : cB + (size_t)(t + 2) * kstep;
;             const char* a3 = a2 + kstep; const char* b3 = b2 + kstep;
;             if (last && has_next) S.a_ready(nxt);
;             if constexpr (SP2) {
;             PG8_LDB(B0, 0, 0); PG8_LDB(B1, 0, 1); PG8_SCHED; PG8_LDA(At, 0, 0); PG8_STAGE(PG8_SA(1, 1), a1 + hstep, voffA);
;             PG8_WAIT_V(8); PG8_WAIT_L(0); PG8_BAR; PG8_MMA(0, 0, At, B0); PG8_MMA(0, 1, At, B1); PG8_BAR; PG8_SCHED;
;             PG8_LDA(At, 0, 1); PG8_STAGE(PG8_SB(0, 0), b2, voffB); PG8_STAGE(PG8_SB(0, 1), b2 + hstep, voffB); PG8_STAGE(PG8_SA(0, 0), a2, voffA);
.LBB0_272:
	ds_read_b128 v[180:183], v145
	ds_read_b128 v[184:187], v145 offset:1024
	ds_read_b128 v[188:191], v145 offset:2048
	ds_read_b128 v[192:195], v145 offset:3072
	ds_read_b128 v[196:199], v145 offset:4096
	ds_read_b128 v[200:203], v145 offset:5120
	ds_read_b128 v[224:227], v145 offset:6144
	ds_read_b128 v[228:231], v145 offset:7168
	s_add_u32 s52, s50, 0x100
	s_addc_u32 s53, s51, 0
	s_add_i32 s24, 0, 0x10000
	s_cmpk_eq_i32 s15, 0x54
	s_cselect_b32 s59, s1, s53
	s_cselect_b32 s58, s0, s52
	v_add_u32_e32 v140, s24, v143
	s_cselect_b32 s57, s45, s14
	s_cselect_b32 s56, s44, s5
	s_add_i32 s26, 0, 0x14000
	ds_read_b128 v[136:139], v140
	ds_read_b128 v[146:149], v140 offset:1024
	ds_read_b128 v[150:153], v140 offset:2048
	ds_read_b128 v[154:157], v140 offset:3072
	v_add_u32_e32 v140, s26, v143
	ds_read_b128 v[158:161], v140
	ds_read_b128 v[168:171], v140 offset:1024
	ds_read_b128 v[172:175], v140 offset:2048
	ds_read_b128 v[176:179], v140 offset:3072
	v_lshl_add_u64 v[140:141], s[50:51], 0, v[132:133]
	s_add_i32 m0, s47, 0xc000
	s_nop 0
	global_load_lds_dwordx4 v[140:141], off
	v_lshl_add_u64 v[140:141], s[50:51], 0, v[134:135]
	s_add_i32 m0, s47, 0xe000
	s_nop 0
	global_load_lds_dwordx4 v[140:141], off
	s_waitcnt vmcnt(8)
	s_waitcnt lgkmcnt(0)
	s_barrier
	s_setprio 1
	v_mfma_f32_16x16x32_bf16 v[126:129], v[136:139], v[180:183], v[126:129]
	v_mfma_f32_16x16x32_bf16 v[126:129], v[146:149], v[184:187], v[126:129]
	v_mfma_f32_16x16x32_bf16 v[122:125], v[150:153], v[180:183], v[122:125]
	v_mfma_f32_16x16x32_bf16 v[122:125], v[154:157], v[184:187], v[122:125]
	v_mfma_f32_16x16x32_bf16 v[110:113], v[136:139], v[188:191], v[110:113]
	v_mfma_f32_16x16x32_bf16 v[110:113], v[146:149], v[192:195], v[110:113]
	v_mfma_f32_16x16x32_bf16 v[106:109], v[150:153], v[188:191], v[106:109]
	v_mfma_f32_16x16x32_bf16 v[106:109], v[154:157], v[192:195], v[106:109]
	v_mfma_f32_16x16x32_bf16 v[94:97], v[136:139], v[196:199], v[94:97]
	v_mfma_f32_16x16x32_bf16 v[94:97], v[146:149], v[200:203], v[94:97]
	v_mfma_f32_16x16x32_bf16 v[90:93], v[150:153], v[196:199], v[90:93]
	v_mfma_f32_16x16x32_bf16 v[90:93], v[154:157], v[200:203], v[90:93]
	v_mfma_f32_16x16x32_bf16 v[78:81], v[136:139], v[224:227], v[78:81]
	v_mfma_f32_16x16x32_bf16 v[78:81], v[146:149], v[228:231], v[78:81]
	v_mfma_f32_16x16x32_bf16 v[74:77], v[150:153], v[224:227], v[74:77]
	v_mfma_f32_16x16x32_bf16 v[74:77], v[154:157], v[228:231], v[74:77]
	v_mfma_f32_16x16x32_bf16 v[118:121], v[158:161], v[180:183], v[118:121]
	v_mfma_f32_16x16x32_bf16 v[118:121], v[168:171], v[184:187], v[118:121]
	v_mfma_f32_16x16x32_bf16 v[114:117], v[172:175], v[180:183], v[114:117]
	v_mfma_f32_16x16x32_bf16 v[114:117], v[176:179], v[184:187], v[114:117]
	v_mfma_f32_16x16x32_bf16 v[102:105], v[158:161], v[188:191], v[102:105]
	v_mfma_f32_16x16x32_bf16 v[102:105], v[168:171], v[192:195], v[102:105]
	v_mfma_f32_16x16x32_bf16 v[98:101], v[172:175], v[188:191], v[98:101]
	v_mfma_f32_16x16x32_bf16 v[98:101], v[176:179], v[192:195], v[98:101]
	v_mfma_f32_16x16x32_bf16 v[86:89], v[158:161], v[196:199], v[86:89]
	v_mfma_f32_16x16x32_bf16 v[86:89], v[168:171], v[200:203], v[86:89]
	v_mfma_f32_16x16x32_bf16 v[82:85], v[172:175], v[196:199], v[82:85]
	v_mfma_f32_16x16x32_bf16 v[82:85], v[176:179], v[200:203], v[82:85]
	v_mfma_f32_16x16x32_bf16 v[70:73], v[158:161], v[224:227], v[70:73]
	v_mfma_f32_16x16x32_bf16 v[70:73], v[168:171], v[228:231], v[70:73]
	v_mfma_f32_16x16x32_bf16 v[66:69], v[172:175], v[224:227], v[66:69]
	v_mfma_f32_16x16x32_bf16 v[66:69], v[176:179], v[228:231], v[66:69]
	s_setprio 0
	s_barrier
	ds_read_b128 v[180:183], v145 offset:16384
	ds_read_b128 v[184:187], v145 offset:17408
	ds_read_b128 v[188:191], v145 offset:18432
	ds_read_b128 v[192:195], v145 offset:19456
	ds_read_b128 v[196:199], v145 offset:20480
	ds_read_b128 v[200:203], v145 offset:21504
	ds_read_b128 v[224:227], v145 offset:22528
	ds_read_b128 v[228:231], v145 offset:23552
	s_add_i32 s24, s24, s22
	v_lshl_add_u64 v[140:141], s[56:57], 0, v[0:1]
	s_mov_b32 m0, s24
	s_nop 0
	global_load_lds_dwordx4 v[140:141], off
	s_add_i32 m0, s24, 0x2000
	s_add_u32 s24, s56, 0x160000
	v_lshl_add_u64 v[232:233], s[56:57], 0, v[130:131]
	s_addc_u32 s25, s57, 0
	s_add_i32 s26, s26, s22
	global_load_lds_dwordx4 v[232:233], off
	v_lshl_add_u64 v[234:235], s[24:25], 0, v[0:1]
	s_mov_b32 m0, s26
	v_lshl_add_u64 v[236:237], s[58:59], 0, v[130:131]
	global_load_lds_dwordx4 v[234:235], off
	v_lshl_add_u64 v[234:235], s[24:25], 0, v[130:131]
	s_add_i32 m0, s26, 0x2000
	s_nop 0
	global_load_lds_dwordx4 v[234:235], off
	v_lshl_add_u64 v[234:235], s[58:59], 0, v[0:1]
	s_mov_b32 m0, s47
	s_nop 0
	global_load_lds_dwordx4 v[234:235], off
	s_mov_b32 m0, s62
	s_nop 0
	global_load_lds_dwordx4 v[236:237], off
	s_waitcnt vmcnt(8)
	s_waitcnt lgkmcnt(0)
	s_barrier
; #define PG8_STAGE(bufoff, gbase, voff) do { _Pragma("unroll") for (int _i = 0; _i < 2; ++_i) \
;         __builtin_amdgcn_global_load_lds((const unsigned*)((const char*)(gbase) + (voff)[_i]), (PG8_LAS unsigned*)(lds + (bufoff) + ldsw + _i * 8192), 16, 0, 0); } while (0)
; #define PG8_LDA(dst, b, h) do { _Pragma("unroll") for (int m = 0; m < 4; ++m) _Pragma("unroll") for (int k = 0; k < 2; ++k) dst[m][k] = *(const PG8_LAS bf16x8*)(lds + PG8_SA(b, h) + aoff + m * 2048 + k * 1024); } while (0)
; #define PG8_LDB(dst, b, h) do { _Pragma("unroll") for (int n = 0; n < 2; ++n) _Pragma("unroll") for (int k = 0; k < 2; ++k) dst[n][k] = *(const PG8_LAS bf16x8*)(lds + PG8_SB(b, h) + boff + n * 2048 + k * 1024); } while (0)
; #define PG8_MMA(ai, bj, At, Bt) do { __builtin_amdgcn_s_setprio(1); _Pragma("unroll") for (int m = 0; m < 4; ++m) _Pragma("unroll") for (int n = 0; n < 2; ++n) _Pragma("unroll") for (int k = 0; k < 2; ++k) \
;         acc[ai][bj][m][n] = __builtin_amdgcn_mfma_f32_16x16x32_bf16(Bt[n][k], At[m][k], acc[ai][bj][m][n], 0, 0, 0); __builtin_amdgcn_s_setprio(0); } while (0)
; #define PG8_WAIT_V(n) asm volatile("s_waitcnt vmcnt(" #n ")" ::: "memory")
; #define PG8_WAIT_L(n) asm volatile("s_waitcnt lgkmcnt(" #n ")" ::: "memory")
; #define PG8_BAR __builtin_amdgcn_s_barrier()
; #define PG8_SCHED __builtin_amdgcn_sched_barrier(0)
; template <class Epi, class Sched, bool ALIGN_EPI = false, bool SP2 = false>
; __device__ __forceinline__ void gemm_phase(PG8_LAS unsigned char* lds, const Gemm g, const Sched S, const Epi E) {
;     ...
;             PG8_WAIT_V(8); PG8_WAIT_L(0); PG8_BAR; PG8_MMA(1, 0, At, B0); PG8_MMA(1, 1, At, B1); PG8_BAR; PG8_SCHED;
;             PG8_LDB(B0, 1, 0); PG8_LDB(B1, 1, 1); PG8_SCHED; PG8_LDA(At, 1, 0); PG8_STAGE(PG8_SA(0, 1), a2 + hstep, voffA);
;             PG8_WAIT_V(8); PG8_WAIT_L(0); PG8_BAR; PG8_MMA(0, 0, At, B0); PG8_MMA(0, 1, At, B1); PG8_BAR; PG8_SCHED;
	s_setprio 1
	v_mfma_f32_16x16x32_bf16 v[62:65], v[136:139], v[180:183], v[62:65]
	v_mfma_f32_16x16x32_bf16 v[62:65], v[146:149], v[184:187], v[62:65]
	v_mfma_f32_16x16x32_bf16 v[58:61], v[150:153], v[180:183], v[58:61]
	v_mfma_f32_16x16x32_bf16 v[58:61], v[154:157], v[184:187], v[58:61]
	v_mfma_f32_16x16x32_bf16 v[46:49], v[136:139], v[188:191], v[46:49]
	v_mfma_f32_16x16x32_bf16 v[46:49], v[146:149], v[192:195], v[46:49]
	v_mfma_f32_16x16x32_bf16 v[42:45], v[150:153], v[188:191], v[42:45]
	v_mfma_f32_16x16x32_bf16 v[42:45], v[154:157], v[192:195], v[42:45]
	v_mfma_f32_16x16x32_bf16 v[30:33], v[136:139], v[196:199], v[30:33]
	v_mfma_f32_16x16x32_bf16 v[30:33], v[146:149], v[200:203], v[30:33]
	v_mfma_f32_16x16x32_bf16 v[26:29], v[150:153], v[196:199], v[26:29]
	v_mfma_f32_16x16x32_bf16 v[26:29], v[154:157], v[200:203], v[26:29]
	v_mfma_f32_16x16x32_bf16 v[14:17], v[136:139], v[224:227], v[14:17]
	v_mfma_f32_16x16x32_bf16 v[14:17], v[146:149], v[228:231], v[14:17]
	v_mfma_f32_16x16x32_bf16 v[10:13], v[150:153], v[224:227], v[10:13]
	v_mfma_f32_16x16x32_bf16 v[10:13], v[154:157], v[228:231], v[10:13]
	v_mfma_f32_16x16x32_bf16 v[54:57], v[158:161], v[180:183], v[54:57]
	v_mfma_f32_16x16x32_bf16 v[54:57], v[168:171], v[184:187], v[54:57]
	v_mfma_f32_16x16x32_bf16 v[50:53], v[172:175], v[180:183], v[50:53]
	v_mfma_f32_16x16x32_bf16 v[50:53], v[176:179], v[184:187], v[50:53]
	v_mfma_f32_16x16x32_bf16 v[38:41], v[158:161], v[188:191], v[38:41]
	v_mfma_f32_16x16x32_bf16 v[38:41], v[168:171], v[192:195], v[38:41]
	v_mfma_f32_16x16x32_bf16 v[34:37], v[172:175], v[188:191], v[34:37]
	v_mfma_f32_16x16x32_bf16 v[34:37], v[176:179], v[192:195], v[34:37]
	v_mfma_f32_16x16x32_bf16 v[22:25], v[158:161], v[196:199], v[22:25]
	v_mfma_f32_16x16x32_bf16 v[22:25], v[168:171], v[200:203], v[22:25]
	v_mfma_f32_16x16x32_bf16 v[18:21], v[172:175], v[196:199], v[18:21]
	v_mfma_f32_16x16x32_bf16 v[18:21], v[176:179], v[200:203], v[18:21]
	v_mfma_f32_16x16x32_bf16 v[6:9], v[158:161], v[224:227], v[6:9]
	v_mfma_f32_16x16x32_bf16 v[6:9], v[168:171], v[228:231], v[6:9]
	v_mfma_f32_16x16x32_bf16 v[2:5], v[172:175], v[224:227], v[2:5]
	v_mfma_f32_16x16x32_bf16 v[2:5], v[176:179], v[228:231], v[2:5]
	s_setprio 0
	s_barrier
	ds_read_b128 v[180:183], v145 offset:32768
	ds_read_b128 v[184:187], v145 offset:33792
	ds_read_b128 v[188:191], v145 offset:34816
	ds_read_b128 v[192:195], v145 offset:35840
	ds_read_b128 v[196:199], v145 offset:36864
	ds_read_b128 v[200:203], v145 offset:37888
	ds_read_b128 v[224:227], v145 offset:38912
	ds_read_b128 v[228:231], v145 offset:39936
	s_add_i32 s26, 0, 0x18000
	s_add_i32 s27, 0, 0x1c000
	v_add_u32_e32 v154, s26, v143
	v_add_u32_e32 v167, s27, v143
	ds_read_b128 v[136:139], v154
	ds_read_b128 v[146:149], v154 offset:1024
	ds_read_b128 v[150:153], v154 offset:2048
	ds_read_b128 v[154:157], v154 offset:3072
	ds_read_b128 v[158:161], v167
	ds_read_b128 v[168:171], v167 offset:1024
	ds_read_b128 v[172:175], v167 offset:2048
	ds_read_b128 v[176:179], v167 offset:3072
	s_add_u32 s24, s58, 0x160000
	s_addc_u32 s25, s59, 0
	s_mov_b32 m0, s63
	v_lshl_add_u64 v[238:239], s[24:25], 0, v[0:1]
	global_load_lds_dwordx4 v[238:239], off
	v_lshl_add_u64 v[238:239], s[24:25], 0, v[130:131]
	s_mov_b32 m0, s64
	s_nop 0
	global_load_lds_dwordx4 v[238:239], off
	s_waitcnt vmcnt(8)
	s_waitcnt lgkmcnt(0)
	s_barrier
	s_setprio 1
	v_mfma_f32_16x16x32_bf16 v[126:129], v[136:139], v[180:183], v[126:129]
	v_mfma_f32_16x16x32_bf16 v[126:129], v[146:149], v[184:187], v[126:129]
	v_mfma_f32_16x16x32_bf16 v[122:125], v[150:153], v[180:183], v[122:125]
	v_mfma_f32_16x16x32_bf16 v[122:125], v[154:157], v[184:187], v[122:125]
	v_mfma_f32_16x16x32_bf16 v[110:113], v[136:139], v[188:191], v[110:113]
	v_mfma_f32_16x16x32_bf16 v[110:113], v[146:149], v[192:195], v[110:113]
	v_mfma_f32_16x16x32_bf16 v[106:109], v[150:153], v[188:191], v[106:109]
	v_mfma_f32_16x16x32_bf16 v[106:109], v[154:157], v[192:195], v[106:109]
	v_mfma_f32_16x16x32_bf16 v[94:97], v[136:139], v[196:199], v[94:97]
	v_mfma_f32_16x16x32_bf16 v[94:97], v[146:149], v[200:203], v[94:97]
	v_mfma_f32_16x16x32_bf16 v[90:93], v[150:153], v[196:199], v[90:93]
	v_mfma_f32_16x16x32_bf16 v[90:93], v[154:157], v[200:203], v[90:93]
	v_mfma_f32_16x16x32_bf16 v[78:81], v[136:139], v[224:227], v[78:81]
	v_mfma_f32_16x16x32_bf16 v[78:81], v[146:149], v[228:231], v[78:81]
	v_mfma_f32_16x16x32_bf16 v[74:77], v[150:153], v[224:227], v[74:77]
	v_mfma_f32_16x16x32_bf16 v[74:77], v[154:157], v[228:231], v[74:77]
	v_mfma_f32_16x16x32_bf16 v[118:121], v[158:161], v[180:183], v[118:121]
	v_mfma_f32_16x16x32_bf16 v[118:121], v[168:171], v[184:187], v[118:121]
	v_mfma_f32_16x16x32_bf16 v[114:117], v[172:175], v[180:183], v[114:117]
	v_mfma_f32_16x16x32_bf16 v[114:117], v[176:179], v[184:187], v[114:117]
	v_mfma_f32_16x16x32_bf16 v[102:105], v[158:161], v[188:191], v[102:105]
	v_mfma_f32_16x16x32_bf16 v[102:105], v[168:171], v[192:195], v[102:105]
	v_mfma_f32_16x16x32_bf16 v[98:101], v[172:175], v[188:191], v[98:101]
	v_mfma_f32_16x16x32_bf16 v[98:101], v[176:179], v[192:195], v[98:101]
	v_mfma_f32_16x16x32_bf16 v[86:89], v[158:161], v[196:199], v[86:89]
	v_mfma_f32_16x16x32_bf16 v[86:89], v[168:171], v[200:203], v[86:89]
	v_mfma_f32_16x16x32_bf16 v[82:85], v[172:175], v[196:199], v[82:85]
	v_mfma_f32_16x16x32_bf16 v[82:85], v[176:179], v[200:203], v[82:85]
	v_mfma_f32_16x16x32_bf16 v[70:73], v[158:161], v[224:227], v[70:73]
	v_mfma_f32_16x16x32_bf16 v[70:73], v[168:171], v[228:231], v[70:73]
	v_mfma_f32_16x16x32_bf16 v[66:69], v[172:175], v[224:227], v[66:69]
	v_mfma_f32_16x16x32_bf16 v[66:69], v[176:179], v[228:231], v[66:69]
	s_setprio 0
	s_barrier
; #define PG8_STAGE(bufoff, gbase, voff) do { _Pragma("unroll") for (int _i = 0; _i < 2; ++_i) \
;         __builtin_amdgcn_global_load_lds((const unsigned*)((const char*)(gbase) + (voff)[_i]), (PG8_LAS unsigned*)(lds + (bufoff) + ldsw + _i * 8192), 16, 0, 0); } while (0)
; #define PG8_LDA(dst, b, h) do { _Pragma("unroll") for (int m = 0; m < 4; ++m) _Pragma("unroll") for (int k = 0; k < 2; ++k) dst[m][k] = *(const PG8_LAS bf16x8*)(lds + PG8_SA(b, h) + aoff + m * 2048 + k * 1024); } while (0)
; #define PG8_MMA(ai, bj, At, Bt) do { __builtin_amdgcn_s_setprio(1); _Pragma("unroll") for (int m = 0; m < 4; ++m) _Pragma("unroll") for (int n = 0; n < 2; ++n) _Pragma("unroll") for (int k = 0; k < 2; ++k) \
;         acc[ai][bj][m][n] = __builtin_amdgcn_mfma_f32_16x16x32_bf16(Bt[n][k], At[m][k], acc[ai][bj][m][n], 0, 0, 0); __builtin_amdgcn_s_setprio(0); } while (0)
; #define PG8_WAIT_V(n) asm volatile("s_waitcnt vmcnt(" #n ")" ::: "memory")
; #define PG8_WAIT_L(n) asm volatile("s_waitcnt lgkmcnt(" #n ")" ::: "memory")
; #define PG8_BAR __builtin_amdgcn_s_barrier()
; #define PG8_SCHED __builtin_amdgcn_sched_barrier(0)
; template <class Epi, class Sched, bool ALIGN_EPI = false, bool SP2 = false>
; __device__ __forceinline__ void gemm_phase(PG8_LAS unsigned char* lds, const Gemm g, const Sched S, const Epi E) {
;     ...
;         for (int t = 0; t < nt; t += 2) {
;             const bool last = (t == nt - 2);
;             const char* a1 = cA + (size_t)(t + 1) * kstep;
;             const char* a2 = last ? nA : cA + (size_t)(t + 2) * kstep; const char* b2 = last ? nB : cB + (size_t)(t + 2) * kstep;
;             const char* a3 = a2 + kstep; const char* b3 = b2 + kstep;
;             if (last && has_next) S.a_ready(nxt);
;     ...
;             PG8_LDA(At, 1, 1); PG8_STAGE(PG8_SB(1, 0), b3, voffB); PG8_STAGE(PG8_SB(1, 1), b3 + hstep, voffB); PG8_STAGE(PG8_SA(1, 0), a3, voffA);
;             PG8_WAIT_V(8); PG8_WAIT_L(0); PG8_BAR; PG8_MMA(1, 0, At, B0); PG8_MMA(1, 1, At, B1); PG8_BAR; PG8_SCHED;
	ds_read_b128 v[180:183], v145 offset:49152
	ds_read_b128 v[184:187], v145 offset:50176
	ds_read_b128 v[188:191], v145 offset:51200
	ds_read_b128 v[192:195], v145 offset:52224
	ds_read_b128 v[196:199], v145 offset:53248
	ds_read_b128 v[200:203], v145 offset:54272
	ds_read_b128 v[224:227], v145 offset:55296
	ds_read_b128 v[228:231], v145 offset:56320
	s_add_i32 s24, s26, s22
	v_lshl_add_u64 v[140:141], v[140:141], 0, s[28:29]
	s_mov_b32 m0, s24
	s_nop 0
	global_load_lds_dwordx4 v[140:141], off
	s_add_i32 m0, s24, 0x2000
	s_add_u32 s24, s56, 0x160080
	v_lshl_add_u64 v[140:141], v[232:233], 0, s[28:29]
	s_addc_u32 s25, s57, 0
	s_add_i32 s26, s27, s22
	global_load_lds_dwordx4 v[140:141], off
	v_lshl_add_u64 v[140:141], s[24:25], 0, v[0:1]
	s_mov_b32 m0, s26
	s_nop 0
	global_load_lds_dwordx4 v[140:141], off
	v_lshl_add_u64 v[140:141], s[24:25], 0, v[130:131]
	s_add_i32 m0, s26, 0x2000
	s_nop 0
	global_load_lds_dwordx4 v[140:141], off
	v_lshl_add_u64 v[140:141], v[234:235], 0, s[28:29]
	s_mov_b32 m0, s65
	s_nop 0
	global_load_lds_dwordx4 v[140:141], off
	v_lshl_add_u64 v[140:141], v[236:237], 0, s[28:29]
	s_mov_b32 m0, s66
	s_nop 0
	global_load_lds_dwordx4 v[140:141], off
	s_waitcnt vmcnt(8)
	s_waitcnt lgkmcnt(0)
	s_barrier
	s_setprio 1
	v_mfma_f32_16x16x32_bf16 v[62:65], v[136:139], v[180:183], v[62:65]
	v_mfma_f32_16x16x32_bf16 v[62:65], v[146:149], v[184:187], v[62:65]
	v_mfma_f32_16x16x32_bf16 v[58:61], v[150:153], v[180:183], v[58:61]
	v_mfma_f32_16x16x32_bf16 v[58:61], v[154:157], v[184:187], v[58:61]
	v_mfma_f32_16x16x32_bf16 v[46:49], v[136:139], v[188:191], v[46:49]
	v_mfma_f32_16x16x32_bf16 v[46:49], v[146:149], v[192:195], v[46:49]
	v_mfma_f32_16x16x32_bf16 v[42:45], v[150:153], v[188:191], v[42:45]
	v_mfma_f32_16x16x32_bf16 v[42:45], v[154:157], v[192:195], v[42:45]
	v_mfma_f32_16x16x32_bf16 v[30:33], v[136:139], v[196:199], v[30:33]
	v_mfma_f32_16x16x32_bf16 v[30:33], v[146:149], v[200:203], v[30:33]
	v_mfma_f32_16x16x32_bf16 v[26:29], v[150:153], v[196:199], v[26:29]
	v_mfma_f32_16x16x32_bf16 v[26:29], v[154:157], v[200:203], v[26:29]
	v_mfma_f32_16x16x32_bf16 v[14:17], v[136:139], v[224:227], v[14:17]
	v_mfma_f32_16x16x32_bf16 v[14:17], v[146:149], v[228:231], v[14:17]
	v_mfma_f32_16x16x32_bf16 v[10:13], v[150:153], v[224:227], v[10:13]
	v_mfma_f32_16x16x32_bf16 v[10:13], v[154:157], v[228:231], v[10:13]
	v_mfma_f32_16x16x32_bf16 v[54:57], v[158:161], v[180:183], v[54:57]
	v_mfma_f32_16x16x32_bf16 v[54:57], v[168:171], v[184:187], v[54:57]
	v_mfma_f32_16x16x32_bf16 v[50:53], v[172:175], v[180:183], v[50:53]
	v_mfma_f32_16x16x32_bf16 v[50:53], v[176:179], v[184:187], v[50:53]
	v_mfma_f32_16x16x32_bf16 v[38:41], v[158:161], v[188:191], v[38:41]
	v_mfma_f32_16x16x32_bf16 v[38:41], v[168:171], v[192:195], v[38:41]
	v_mfma_f32_16x16x32_bf16 v[34:37], v[172:175], v[188:191], v[34:37]
	v_mfma_f32_16x16x32_bf16 v[34:37], v[176:179], v[192:195], v[34:37]
	v_mfma_f32_16x16x32_bf16 v[22:25], v[158:161], v[196:199], v[22:25]
	v_mfma_f32_16x16x32_bf16 v[22:25], v[168:171], v[200:203], v[22:25]
	v_mfma_f32_16x16x32_bf16 v[18:21], v[172:175], v[196:199], v[18:21]
	v_mfma_f32_16x16x32_bf16 v[18:21], v[176:179], v[200:203], v[18:21]
	v_mfma_f32_16x16x32_bf16 v[6:9], v[158:161], v[224:227], v[6:9]
	v_mfma_f32_16x16x32_bf16 v[6:9], v[168:171], v[228:231], v[6:9]
	v_mfma_f32_16x16x32_bf16 v[2:5], v[172:175], v[224:227], v[2:5]
	v_mfma_f32_16x16x32_bf16 v[2:5], v[176:179], v[228:231], v[2:5]
	s_setprio 0
	s_barrier
	s_add_i32 s15, s15, 2
	s_add_u32 s5, s5, 0x100
	s_addc_u32 s14, s14, 0
	s_cmpk_gt_u32 s15, 0x55
	s_mov_b64 s[50:51], s[52:53]
	s_cbranch_scc0 .LBB0_272
	s_and_b64 vcc, exec, s[42:43]
	s_cbranch_vccz .LBB0_275
	s_barrier

; #define PG8_STAGE(bufoff, gbase, voff) do { _Pragma("unroll") for (int _i = 0; _i < 2; ++_i) \
;         __builtin_amdgcn_global_load_lds((const unsigned*)((const char*)(gbase) + (voff)[_i]), (PG8_LAS unsigned*)(lds + (bufoff) + ldsw + _i * 8192), 16, 0, 0); } while (0)
; #define PG8_LDA(dst, b, h) do { _Pragma("unroll") for (int m = 0; m < 4; ++m) _Pragma("unroll") for (int k = 0; k < 2; ++k) dst[m][k] = *(const PG8_LAS bf16x8*)(lds + PG8_SA(b, h) + aoff + m * 2048 + k * 1024); } while (0)
; #define PG8_LDB(dst, b, h) do { _Pragma("unroll") for (int n = 0; n < 2; ++n) _Pragma("unroll") for (int k = 0; k < 2; ++k) dst[n][k] = *(const PG8_LAS bf16x8*)(lds + PG8_SB(b, h) + boff + n * 2048 + k * 1024); } while (0)
; #define PG8_MMA(ai, bj, At, Bt) do { __builtin_amdgcn_s_setprio(1); _Pragma("unroll") for (int m = 0; m < 4; ++m) _Pragma("unroll") for (int n = 0; n < 2; ++n) _Pragma("unroll") for (int k = 0; k < 2; ++k) \
;         acc[ai][bj][m][n] = __builtin_amdgcn_mfma_f32_16x16x32_bf16(Bt[n][k], At[m][k], acc[ai][bj][m][n], 0, 0, 0); __builtin_amdgcn_s_setprio(0); } while (0)
; #define PG8_WAIT_V(n) asm volatile("s_waitcnt vmcnt(" #n ")" ::: "memory")
; #define PG8_WAIT_L(n) asm volatile("s_waitcnt lgkmcnt(" #n ")" ::: "memory")
; #define PG8_BAR __builtin_amdgcn_s_barrier()
; #define PG8_SCHED __builtin_amdgcn_sched_barrier(0)
; template <class Epi, class Sched, bool ALIGN_EPI = false, bool SP2 = false>
; __device__ __forceinline__ void gemm_phase(PG8_LAS unsigned char* lds, const Gemm g, const Sched S, const Epi E) {
;     ...
;         for (int t = 0; t < nt; t += 2) {
;             const bool last = (t == nt - 2);
;             const char* a1 = cA + (size_t)(t + 1) * kstep;
;             const char* a2 = last ? nA : cA + (size_t)(t + 2) * kstep; const char* b2 = last ? nB : cB + (size_t)(t + 2) * kstep;
;             const char* a3 = a2 + kstep; const char* b3 = b2 + kstep;
;             if (last && has_next) S.a_ready(nxt);
;             if constexpr (SP2) {
;             PG8_LDB(B0, 0, 0); PG8_LDB(B1, 0, 1); PG8_SCHED; PG8_LDA(At, 0, 0); PG8_STAGE(PG8_SA(1, 1), a1 + hstep, voffA);
;             PG8_WAIT_V(8); PG8_WAIT_L(0); PG8_BAR; PG8_MMA(0, 0, At, B0); PG8_MMA(0, 1, At, B1); PG8_BAR; PG8_SCHED;
;             PG8_LDA(At, 0, 1); PG8_STAGE(PG8_SB(0, 0), b2, voffB); PG8_STAGE(PG8_SB(0, 1), b2 + hstep, voffB); PG8_STAGE(PG8_SA(0, 0), a2, voffA);
.LBB0_404:
	ds_read_b128 v[194:197], v171
	ds_read_b128 v[198:201], v171 offset:1024
	ds_read_b128 v[224:227], v171 offset:2048
	ds_read_b128 v[228:231], v171 offset:3072
	ds_read_b128 v[232:235], v171 offset:4096
	ds_read_b128 v[236:239], v171 offset:5120
	ds_read_b128 v[240:243], v171 offset:6144
	ds_read_b128 v[244:247], v171 offset:7168
	s_add_u32 s25, s0, 0xfff80080
	s_addc_u32 s26, s1, -1
	s_add_i32 s27, 0, 0x10000
	s_cmp_eq_u32 s24, 28
	s_cselect_b32 s67, s53, s26
	s_cselect_b32 s66, vcc_lo, s25
	v_add_u32_e32 v152, s27, v155
	s_cselect_b32 s65, s45, s15
	s_cselect_b32 s64, vcc_hi, s14
	s_add_i32 s25, 0, 0x14000
	ds_read_b128 v[130:133], v152
	ds_read_b128 v[134:137], v152 offset:1024
	ds_read_b128 v[148:151], v152 offset:2048
	ds_read_b128 v[174:177], v152 offset:3072
	v_add_u32_e32 v152, s25, v155
	ds_read_b128 v[178:181], v152
	ds_read_b128 v[182:185], v152 offset:1024
	ds_read_b128 v[186:189], v152 offset:2048
	ds_read_b128 v[190:193], v152 offset:3072
	v_lshl_add_u64 v[152:153], s[0:1], 0, v[144:145]
	s_add_i32 m0, s21, 0xc000
	s_nop 0
	global_load_lds_dwordx4 v[152:153], off
	v_lshl_add_u64 v[152:153], s[0:1], 0, v[146:147]
	s_add_i32 m0, s21, 0xe000
	s_nop 0
	global_load_lds_dwordx4 v[152:153], off
	s_waitcnt vmcnt(8)
	s_waitcnt lgkmcnt(0)
	s_barrier
	s_setprio 1
	v_mfma_f32_16x16x32_bf16 v[126:129], v[130:133], v[194:197], v[126:129]
	v_mfma_f32_16x16x32_bf16 v[126:129], v[134:137], v[198:201], v[126:129]
	v_mfma_f32_16x16x32_bf16 v[122:125], v[148:151], v[194:197], v[122:125]
	v_mfma_f32_16x16x32_bf16 v[122:125], v[174:177], v[198:201], v[122:125]
	v_mfma_f32_16x16x32_bf16 v[118:121], v[130:133], v[224:227], v[118:121]
	v_mfma_f32_16x16x32_bf16 v[118:121], v[134:137], v[228:231], v[118:121]
	v_mfma_f32_16x16x32_bf16 v[110:113], v[148:151], v[224:227], v[110:113]
	v_mfma_f32_16x16x32_bf16 v[110:113], v[174:177], v[228:231], v[110:113]
	v_mfma_f32_16x16x32_bf16 v[102:105], v[130:133], v[232:235], v[102:105]
	v_mfma_f32_16x16x32_bf16 v[102:105], v[134:137], v[236:239], v[102:105]
	v_mfma_f32_16x16x32_bf16 v[94:97], v[148:151], v[232:235], v[94:97]
	v_mfma_f32_16x16x32_bf16 v[94:97], v[174:177], v[236:239], v[94:97]
	v_mfma_f32_16x16x32_bf16 v[86:89], v[130:133], v[240:243], v[86:89]
	v_mfma_f32_16x16x32_bf16 v[86:89], v[134:137], v[244:247], v[86:89]
	v_mfma_f32_16x16x32_bf16 v[78:81], v[148:151], v[240:243], v[78:81]
	v_mfma_f32_16x16x32_bf16 v[78:81], v[174:177], v[244:247], v[78:81]
	v_mfma_f32_16x16x32_bf16 v[114:117], v[178:181], v[194:197], v[114:117]
	v_mfma_f32_16x16x32_bf16 v[114:117], v[182:185], v[198:201], v[114:117]
	v_mfma_f32_16x16x32_bf16 v[106:109], v[186:189], v[194:197], v[106:109]
	v_mfma_f32_16x16x32_bf16 v[106:109], v[190:193], v[198:201], v[106:109]
	v_mfma_f32_16x16x32_bf16 v[98:101], v[178:181], v[224:227], v[98:101]
	v_mfma_f32_16x16x32_bf16 v[98:101], v[182:185], v[228:231], v[98:101]
	v_mfma_f32_16x16x32_bf16 v[90:93], v[186:189], v[224:227], v[90:93]
	v_mfma_f32_16x16x32_bf16 v[90:93], v[190:193], v[228:231], v[90:93]
	v_mfma_f32_16x16x32_bf16 v[82:85], v[178:181], v[232:235], v[82:85]
	v_mfma_f32_16x16x32_bf16 v[82:85], v[182:185], v[236:239], v[82:85]
	v_mfma_f32_16x16x32_bf16 v[74:77], v[186:189], v[232:235], v[74:77]
	v_mfma_f32_16x16x32_bf16 v[74:77], v[190:193], v[236:239], v[74:77]
	v_mfma_f32_16x16x32_bf16 v[70:73], v[178:181], v[240:243], v[70:73]
	v_mfma_f32_16x16x32_bf16 v[70:73], v[182:185], v[244:247], v[70:73]
	v_mfma_f32_16x16x32_bf16 v[66:69], v[186:189], v[240:243], v[66:69]
	v_mfma_f32_16x16x32_bf16 v[66:69], v[190:193], v[244:247], v[66:69]
	s_setprio 0
	s_barrier
	ds_read_b128 v[194:197], v171 offset:16384
	ds_read_b128 v[198:201], v171 offset:17408
	ds_read_b128 v[224:227], v171 offset:18432
	ds_read_b128 v[228:231], v171 offset:19456
	ds_read_b128 v[232:235], v171 offset:20480
	ds_read_b128 v[236:239], v171 offset:21504
	ds_read_b128 v[240:243], v171 offset:22528
	ds_read_b128 v[244:247], v171 offset:23552
	s_add_i32 s26, s27, s16
	v_lshl_add_u64 v[152:153], s[64:65], 0, v[0:1]
	s_mov_b32 m0, s26
	s_nop 0
	global_load_lds_dwordx4 v[152:153], off
	s_add_i32 m0, s26, 0x2000
	s_add_u32 s26, s64, 0x80000
	v_lshl_add_u64 v[202:203], s[64:65], 0, v[138:139]
	s_addc_u32 s27, s65, 0
	s_add_i32 s25, s25, s16
	global_load_lds_dwordx4 v[202:203], off
	v_lshl_add_u64 v[248:249], s[26:27], 0, v[0:1]
	s_mov_b32 m0, s25
	v_lshl_add_u64 v[250:251], s[66:67], 0, v[140:141]
	global_load_lds_dwordx4 v[248:249], off
	v_lshl_add_u64 v[248:249], s[26:27], 0, v[138:139]
	s_add_i32 m0, s25, 0x2000
	s_nop 0
	global_load_lds_dwordx4 v[248:249], off
	v_lshl_add_u64 v[248:249], s[66:67], 0, v[142:143]
	s_mov_b32 m0, s21
	s_nop 0
	global_load_lds_dwordx4 v[248:249], off
	s_mov_b32 m0, s22
	s_nop 0
	global_load_lds_dwordx4 v[250:251], off
	s_waitcnt vmcnt(8)
	s_waitcnt lgkmcnt(0)
	s_barrier
; #define PG8_STAGE(bufoff, gbase, voff) do { _Pragma("unroll") for (int _i = 0; _i < 2; ++_i) \
;         __builtin_amdgcn_global_load_lds((const unsigned*)((const char*)(gbase) + (voff)[_i]), (PG8_LAS unsigned*)(lds + (bufoff) + ldsw + _i * 8192), 16, 0, 0); } while (0)
; #define PG8_LDA(dst, b, h) do { _Pragma("unroll") for (int m = 0; m < 4; ++m) _Pragma("unroll") for (int k = 0; k < 2; ++k) dst[m][k] = *(const PG8_LAS bf16x8*)(lds + PG8_SA(b, h) + aoff + m * 2048 + k * 1024); } while (0)
; #define PG8_LDB(dst, b, h) do { _Pragma("unroll") for (int n = 0; n < 2; ++n) _Pragma("unroll") for (int k = 0; k < 2; ++k) dst[n][k] = *(const PG8_LAS bf16x8*)(lds + PG8_SB(b, h) + boff + n * 2048 + k * 1024); } while (0)
; #define PG8_MMA(ai, bj, At, Bt) do { __builtin_amdgcn_s_setprio(1); _Pragma("unroll") for (int m = 0; m < 4; ++m) _Pragma("unroll") for (int n = 0; n < 2; ++n) _Pragma("unroll") for (int k = 0; k < 2; ++k) \
;         acc[ai][bj][m][n] = __builtin_amdgcn_mfma_f32_16x16x32_bf16(Bt[n][k], At[m][k], acc[ai][bj][m][n], 0, 0, 0); __builtin_amdgcn_s_setprio(0); } while (0)
; #define PG8_WAIT_V(n) asm volatile("s_waitcnt vmcnt(" #n ")" ::: "memory")
; #define PG8_WAIT_L(n) asm volatile("s_waitcnt lgkmcnt(" #n ")" ::: "memory")
; #define PG8_BAR __builtin_amdgcn_s_barrier()
; #define PG8_SCHED __builtin_amdgcn_sched_barrier(0)
; template <class Epi, class Sched, bool ALIGN_EPI = false, bool SP2 = false>
; __device__ __forceinline__ void gemm_phase(PG8_LAS unsigned char* lds, const Gemm g, const Sched S, const Epi E) {
;     ...
;             PG8_WAIT_V(8); PG8_WAIT_L(0); PG8_BAR; PG8_MMA(1, 0, At, B0); PG8_MMA(1, 1, At, B1); PG8_BAR; PG8_SCHED;
;             PG8_LDB(B0, 1, 0); PG8_LDB(B1, 1, 1); PG8_SCHED; PG8_LDA(At, 1, 0); PG8_STAGE(PG8_SA(0, 1), a2 + hstep, voffA);
;             PG8_WAIT_V(8); PG8_WAIT_L(0); PG8_BAR; PG8_MMA(0, 0, At, B0); PG8_MMA(0, 1, At, B1); PG8_BAR; PG8_SCHED;
	s_setprio 1
	v_mfma_f32_16x16x32_bf16 v[62:65], v[130:133], v[194:197], v[62:65]
	v_mfma_f32_16x16x32_bf16 v[62:65], v[134:137], v[198:201], v[62:65]
	v_mfma_f32_16x16x32_bf16 v[58:61], v[148:151], v[194:197], v[58:61]
	v_mfma_f32_16x16x32_bf16 v[58:61], v[174:177], v[198:201], v[58:61]
	v_mfma_f32_16x16x32_bf16 v[54:57], v[130:133], v[224:227], v[54:57]
	v_mfma_f32_16x16x32_bf16 v[54:57], v[134:137], v[228:231], v[54:57]
	v_mfma_f32_16x16x32_bf16 v[46:49], v[148:151], v[224:227], v[46:49]
	v_mfma_f32_16x16x32_bf16 v[46:49], v[174:177], v[228:231], v[46:49]
	v_mfma_f32_16x16x32_bf16 v[38:41], v[130:133], v[232:235], v[38:41]
	v_mfma_f32_16x16x32_bf16 v[38:41], v[134:137], v[236:239], v[38:41]
	v_mfma_f32_16x16x32_bf16 v[30:33], v[148:151], v[232:235], v[30:33]
	v_mfma_f32_16x16x32_bf16 v[30:33], v[174:177], v[236:239], v[30:33]
	v_mfma_f32_16x16x32_bf16 v[22:25], v[130:133], v[240:243], v[22:25]
	v_mfma_f32_16x16x32_bf16 v[22:25], v[134:137], v[244:247], v[22:25]
	v_mfma_f32_16x16x32_bf16 v[14:17], v[148:151], v[240:243], v[14:17]
	v_mfma_f32_16x16x32_bf16 v[14:17], v[174:177], v[244:247], v[14:17]
	v_mfma_f32_16x16x32_bf16 v[50:53], v[178:181], v[194:197], v[50:53]
	v_mfma_f32_16x16x32_bf16 v[50:53], v[182:185], v[198:201], v[50:53]
	v_mfma_f32_16x16x32_bf16 v[42:45], v[186:189], v[194:197], v[42:45]
	v_mfma_f32_16x16x32_bf16 v[42:45], v[190:193], v[198:201], v[42:45]
	v_mfma_f32_16x16x32_bf16 v[34:37], v[178:181], v[224:227], v[34:37]
	v_mfma_f32_16x16x32_bf16 v[34:37], v[182:185], v[228:231], v[34:37]
	v_mfma_f32_16x16x32_bf16 v[26:29], v[186:189], v[224:227], v[26:29]
	v_mfma_f32_16x16x32_bf16 v[26:29], v[190:193], v[228:231], v[26:29]
	v_mfma_f32_16x16x32_bf16 v[18:21], v[178:181], v[232:235], v[18:21]
	v_mfma_f32_16x16x32_bf16 v[18:21], v[182:185], v[236:239], v[18:21]
	v_mfma_f32_16x16x32_bf16 v[10:13], v[186:189], v[232:235], v[10:13]
	v_mfma_f32_16x16x32_bf16 v[10:13], v[190:193], v[236:239], v[10:13]
	v_mfma_f32_16x16x32_bf16 v[6:9], v[178:181], v[240:243], v[6:9]
	v_mfma_f32_16x16x32_bf16 v[6:9], v[182:185], v[244:247], v[6:9]
	v_mfma_f32_16x16x32_bf16 v[2:5], v[186:189], v[240:243], v[2:5]
	v_mfma_f32_16x16x32_bf16 v[2:5], v[190:193], v[244:247], v[2:5]
	s_setprio 0
	s_barrier
	ds_read_b128 v[194:197], v171 offset:32768
	ds_read_b128 v[198:201], v171 offset:33792
	ds_read_b128 v[224:227], v171 offset:34816
	ds_read_b128 v[228:231], v171 offset:35840
	ds_read_b128 v[232:235], v171 offset:36864
	ds_read_b128 v[236:239], v171 offset:37888
	ds_read_b128 v[240:243], v171 offset:38912
	ds_read_b128 v[244:247], v171 offset:39936
	s_add_i32 s25, 0, 0x18000
	v_add_u32_e32 v173, s25, v155
	s_add_i32 s30, 0, 0x1c000
	ds_read_b128 v[130:133], v173
	ds_read_b128 v[134:137], v173 offset:1024
	ds_read_b128 v[148:151], v173 offset:2048
	ds_read_b128 v[174:177], v173 offset:3072
	v_add_u32_e32 v173, s30, v155
	ds_read_b128 v[178:181], v173
	ds_read_b128 v[182:185], v173 offset:1024
	ds_read_b128 v[186:189], v173 offset:2048
	ds_read_b128 v[190:193], v173 offset:3072
	s_add_u32 s26, s66, 0x80000
	s_addc_u32 s27, s67, 0
	s_mov_b32 m0, s47
	v_lshl_add_u64 v[214:215], s[26:27], 0, v[142:143]
	global_load_lds_dwordx4 v[214:215], off
	v_lshl_add_u64 v[214:215], s[26:27], 0, v[140:141]
	s_mov_b32 m0, s62
	s_nop 0
	global_load_lds_dwordx4 v[214:215], off
	s_waitcnt vmcnt(8)
	s_waitcnt lgkmcnt(0)
	s_barrier
	s_setprio 1
	v_mfma_f32_16x16x32_bf16 v[126:129], v[130:133], v[194:197], v[126:129]
	v_mfma_f32_16x16x32_bf16 v[126:129], v[134:137], v[198:201], v[126:129]
	v_mfma_f32_16x16x32_bf16 v[122:125], v[148:151], v[194:197], v[122:125]
	v_mfma_f32_16x16x32_bf16 v[122:125], v[174:177], v[198:201], v[122:125]
	v_mfma_f32_16x16x32_bf16 v[118:121], v[130:133], v[224:227], v[118:121]
	v_mfma_f32_16x16x32_bf16 v[118:121], v[134:137], v[228:231], v[118:121]
	v_mfma_f32_16x16x32_bf16 v[110:113], v[148:151], v[224:227], v[110:113]
	v_mfma_f32_16x16x32_bf16 v[110:113], v[174:177], v[228:231], v[110:113]
	v_mfma_f32_16x16x32_bf16 v[102:105], v[130:133], v[232:235], v[102:105]
	v_mfma_f32_16x16x32_bf16 v[102:105], v[134:137], v[236:239], v[102:105]
	v_mfma_f32_16x16x32_bf16 v[94:97], v[148:151], v[232:235], v[94:97]
	v_mfma_f32_16x16x32_bf16 v[94:97], v[174:177], v[236:239], v[94:97]
	v_mfma_f32_16x16x32_bf16 v[86:89], v[130:133], v[240:243], v[86:89]
	v_mfma_f32_16x16x32_bf16 v[86:89], v[134:137], v[244:247], v[86:89]
	v_mfma_f32_16x16x32_bf16 v[78:81], v[148:151], v[240:243], v[78:81]
	v_mfma_f32_16x16x32_bf16 v[78:81], v[174:177], v[244:247], v[78:81]
	v_mfma_f32_16x16x32_bf16 v[114:117], v[178:181], v[194:197], v[114:117]
	v_mfma_f32_16x16x32_bf16 v[114:117], v[182:185], v[198:201], v[114:117]
	v_mfma_f32_16x16x32_bf16 v[106:109], v[186:189], v[194:197], v[106:109]
	v_mfma_f32_16x16x32_bf16 v[106:109], v[190:193], v[198:201], v[106:109]
	v_mfma_f32_16x16x32_bf16 v[98:101], v[178:181], v[224:227], v[98:101]
	v_mfma_f32_16x16x32_bf16 v[98:101], v[182:185], v[228:231], v[98:101]
	v_mfma_f32_16x16x32_bf16 v[90:93], v[186:189], v[224:227], v[90:93]
	v_mfma_f32_16x16x32_bf16 v[90:93], v[190:193], v[228:231], v[90:93]
	v_mfma_f32_16x16x32_bf16 v[82:85], v[178:181], v[232:235], v[82:85]
	v_mfma_f32_16x16x32_bf16 v[82:85], v[182:185], v[236:239], v[82:85]
	v_mfma_f32_16x16x32_bf16 v[74:77], v[186:189], v[232:235], v[74:77]
	v_mfma_f32_16x16x32_bf16 v[74:77], v[190:193], v[236:239], v[74:77]
	v_mfma_f32_16x16x32_bf16 v[70:73], v[178:181], v[240:243], v[70:73]
	v_mfma_f32_16x16x32_bf16 v[70:73], v[182:185], v[244:247], v[70:73]
	v_mfma_f32_16x16x32_bf16 v[66:69], v[186:189], v[240:243], v[66:69]
	v_mfma_f32_16x16x32_bf16 v[66:69], v[190:193], v[244:247], v[66:69]
	s_setprio 0
	s_barrier
; #define PG8_STAGE(bufoff, gbase, voff) do { _Pragma("unroll") for (int _i = 0; _i < 2; ++_i) \
;         __builtin_amdgcn_global_load_lds((const unsigned*)((const char*)(gbase) + (voff)[_i]), (PG8_LAS unsigned*)(lds + (bufoff) + ldsw + _i * 8192), 16, 0, 0); } while (0)
; #define PG8_LDA(dst, b, h) do { _Pragma("unroll") for (int m = 0; m < 4; ++m) _Pragma("unroll") for (int k = 0; k < 2; ++k) dst[m][k] = *(const PG8_LAS bf16x8*)(lds + PG8_SA(b, h) + aoff + m * 2048 + k * 1024); } while (0)
; #define PG8_MMA(ai, bj, At, Bt) do { __builtin_amdgcn_s_setprio(1); _Pragma("unroll") for (int m = 0; m < 4; ++m) _Pragma("unroll") for (int n = 0; n < 2; ++n) _Pragma("unroll") for (int k = 0; k < 2; ++k) \
;         acc[ai][bj][m][n] = __builtin_amdgcn_mfma_f32_16x16x32_bf16(Bt[n][k], At[m][k], acc[ai][bj][m][n], 0, 0, 0); __builtin_amdgcn_s_setprio(0); } while (0)
; #define PG8_WAIT_V(n) asm volatile("s_waitcnt vmcnt(" #n ")" ::: "memory")
; #define PG8_WAIT_L(n) asm volatile("s_waitcnt lgkmcnt(" #n ")" ::: "memory")
; #define PG8_BAR __builtin_amdgcn_s_barrier()
; #define PG8_SCHED __builtin_amdgcn_sched_barrier(0)
; template <class Epi, class Sched, bool ALIGN_EPI = false, bool SP2 = false>
; __device__ __forceinline__ void gemm_phase(PG8_LAS unsigned char* lds, const Gemm g, const Sched S, const Epi E) {
;     ...
;         for (int t = 0; t < nt; t += 2) {
;             const bool last = (t == nt - 2);
;             const char* a1 = cA + (size_t)(t + 1) * kstep;
;             const char* a2 = last ? nA : cA + (size_t)(t + 2) * kstep; const char* b2 = last ? nB : cB + (size_t)(t + 2) * kstep;
;             const char* a3 = a2 + kstep; const char* b3 = b2 + kstep;
;             if (last && has_next) S.a_ready(nxt);
;     ...
;             PG8_LDA(At, 1, 1); PG8_STAGE(PG8_SB(1, 0), b3, voffB); PG8_STAGE(PG8_SB(1, 1), b3 + hstep, voffB); PG8_STAGE(PG8_SA(1, 0), a3, voffA);
;             PG8_WAIT_V(8); PG8_WAIT_L(0); PG8_BAR; PG8_MMA(1, 0, At, B0); PG8_MMA(1, 1, At, B1); PG8_BAR; PG8_SCHED;
	ds_read_b128 v[194:197], v171 offset:49152
	ds_read_b128 v[198:201], v171 offset:50176
	ds_read_b128 v[224:227], v171 offset:51200
	ds_read_b128 v[228:231], v171 offset:52224
	ds_read_b128 v[232:235], v171 offset:53248
	ds_read_b128 v[236:239], v171 offset:54272
	ds_read_b128 v[240:243], v171 offset:55296
	ds_read_b128 v[244:247], v171 offset:56320
	s_add_i32 s25, s25, s16
	v_lshl_add_u64 v[152:153], v[152:153], 0, s[28:29]
	s_mov_b32 m0, s25
	s_nop 0
	global_load_lds_dwordx4 v[152:153], off
	s_add_i32 m0, s25, 0x2000
	s_add_u32 s26, s64, 0x80080
	v_lshl_add_u64 v[152:153], v[202:203], 0, s[28:29]
	s_addc_u32 s27, s65, 0
	s_add_i32 s25, s30, s16
	global_load_lds_dwordx4 v[152:153], off
	v_lshl_add_u64 v[152:153], s[26:27], 0, v[0:1]
	s_mov_b32 m0, s25
	s_nop 0
	global_load_lds_dwordx4 v[152:153], off
	v_lshl_add_u64 v[152:153], s[26:27], 0, v[138:139]
	s_add_i32 m0, s25, 0x2000
	s_nop 0
	global_load_lds_dwordx4 v[152:153], off
	v_lshl_add_u64 v[152:153], v[248:249], 0, s[28:29]
	s_mov_b32 m0, s63
	s_nop 0
	global_load_lds_dwordx4 v[152:153], off
	v_lshl_add_u64 v[152:153], v[250:251], 0, s[28:29]
	s_mov_b32 m0, s74
	s_nop 0
	global_load_lds_dwordx4 v[152:153], off
	s_waitcnt vmcnt(8)
	s_waitcnt lgkmcnt(0)
	s_barrier
	s_setprio 1
	v_mfma_f32_16x16x32_bf16 v[62:65], v[130:133], v[194:197], v[62:65]
	v_mfma_f32_16x16x32_bf16 v[62:65], v[134:137], v[198:201], v[62:65]
	v_mfma_f32_16x16x32_bf16 v[58:61], v[148:151], v[194:197], v[58:61]
	v_mfma_f32_16x16x32_bf16 v[58:61], v[174:177], v[198:201], v[58:61]
	v_mfma_f32_16x16x32_bf16 v[54:57], v[130:133], v[224:227], v[54:57]
	v_mfma_f32_16x16x32_bf16 v[54:57], v[134:137], v[228:231], v[54:57]
	v_mfma_f32_16x16x32_bf16 v[46:49], v[148:151], v[224:227], v[46:49]
	v_mfma_f32_16x16x32_bf16 v[46:49], v[174:177], v[228:231], v[46:49]
	v_mfma_f32_16x16x32_bf16 v[38:41], v[130:133], v[232:235], v[38:41]
	v_mfma_f32_16x16x32_bf16 v[38:41], v[134:137], v[236:239], v[38:41]
	v_mfma_f32_16x16x32_bf16 v[30:33], v[148:151], v[232:235], v[30:33]
	v_mfma_f32_16x16x32_bf16 v[30:33], v[174:177], v[236:239], v[30:33]
	v_mfma_f32_16x16x32_bf16 v[22:25], v[130:133], v[240:243], v[22:25]
	v_mfma_f32_16x16x32_bf16 v[22:25], v[134:137], v[244:247], v[22:25]
	v_mfma_f32_16x16x32_bf16 v[14:17], v[148:151], v[240:243], v[14:17]
	v_mfma_f32_16x16x32_bf16 v[14:17], v[174:177], v[244:247], v[14:17]
	v_mfma_f32_16x16x32_bf16 v[50:53], v[178:181], v[194:197], v[50:53]
	v_mfma_f32_16x16x32_bf16 v[50:53], v[182:185], v[198:201], v[50:53]
	v_mfma_f32_16x16x32_bf16 v[42:45], v[186:189], v[194:197], v[42:45]
	v_mfma_f32_16x16x32_bf16 v[42:45], v[190:193], v[198:201], v[42:45]
	v_mfma_f32_16x16x32_bf16 v[34:37], v[178:181], v[224:227], v[34:37]
	v_mfma_f32_16x16x32_bf16 v[34:37], v[182:185], v[228:231], v[34:37]
	v_mfma_f32_16x16x32_bf16 v[26:29], v[186:189], v[224:227], v[26:29]
	v_mfma_f32_16x16x32_bf16 v[26:29], v[190:193], v[228:231], v[26:29]
	v_mfma_f32_16x16x32_bf16 v[18:21], v[178:181], v[232:235], v[18:21]
	v_mfma_f32_16x16x32_bf16 v[18:21], v[182:185], v[236:239], v[18:21]
	v_mfma_f32_16x16x32_bf16 v[10:13], v[186:189], v[232:235], v[10:13]
	v_mfma_f32_16x16x32_bf16 v[10:13], v[190:193], v[236:239], v[10:13]
	v_mfma_f32_16x16x32_bf16 v[6:9], v[178:181], v[240:243], v[6:9]
	v_mfma_f32_16x16x32_bf16 v[6:9], v[182:185], v[244:247], v[6:9]
	v_mfma_f32_16x16x32_bf16 v[2:5], v[186:189], v[240:243], v[2:5]
	v_mfma_f32_16x16x32_bf16 v[2:5], v[190:193], v[244:247], v[2:5]
	s_setprio 0
	s_barrier
	s_add_i32 s24, s24, 2
	s_add_u32 s0, s0, 0x100
	s_addc_u32 s1, s1, 0
	s_add_u32 s14, s14, 0x100
	s_addc_u32 s15, s15, 0
	s_cmp_gt_u32 s24, 29
	s_cbranch_scc0 .LBB0_404
	s_and_b64 vcc, exec, s[8:9]
	s_cbranch_vccz .LBB0_407
	s_barrier

; #define PG8_STAGE(bufoff, gbase, voff) do { _Pragma("unroll") for (int _i = 0; _i < 2; ++_i) \
;         __builtin_amdgcn_global_load_lds((const unsigned*)((const char*)(gbase) + (voff)[_i]), (PG8_LAS unsigned*)(lds + (bufoff) + ldsw + _i * 8192), 16, 0, 0); } while (0)
; #define PG8_LDA(dst, b, h) do { _Pragma("unroll") for (int m = 0; m < 4; ++m) _Pragma("unroll") for (int k = 0; k < 2; ++k) dst[m][k] = *(const PG8_LAS bf16x8*)(lds + PG8_SA(b, h) + aoff + m * 2048 + k * 1024); } while (0)
; #define PG8_LDB(dst, b, h) do { _Pragma("unroll") for (int n = 0; n < 2; ++n) _Pragma("unroll") for (int k = 0; k < 2; ++k) dst[n][k] = *(const PG8_LAS bf16x8*)(lds + PG8_SB(b, h) + boff + n * 2048 + k * 1024); } while (0)
; #define PG8_MMA(ai, bj, At, Bt) do { __builtin_amdgcn_s_setprio(1); _Pragma("unroll") for (int m = 0; m < 4; ++m) _Pragma("unroll") for (int n = 0; n < 2; ++n) _Pragma("unroll") for (int k = 0; k < 2; ++k) \
;         acc[ai][bj][m][n] = __builtin_amdgcn_mfma_f32_16x16x32_bf16(Bt[n][k], At[m][k], acc[ai][bj][m][n], 0, 0, 0); __builtin_amdgcn_s_setprio(0); } while (0)
; #define PG8_WAIT_V(n) asm volatile("s_waitcnt vmcnt(" #n ")" ::: "memory")
; #define PG8_WAIT_L(n) asm volatile("s_waitcnt lgkmcnt(" #n ")" ::: "memory")
; #define PG8_BAR __builtin_amdgcn_s_barrier()
; #define PG8_SCHED __builtin_amdgcn_sched_barrier(0)
; template <class Epi, class Sched, bool ALIGN_EPI = false, bool SP2 = false>
; __device__ __forceinline__ void gemm_phase(PG8_LAS unsigned char* lds, const Gemm g, const Sched S, const Epi E) {
;     ...
;         for (int t = 0; t < nt; t += 2) {
;             const bool last = (t == nt - 2);
;             const char* a1 = cA + (size_t)(t + 1) * kstep;
;             const char* a2 = last ? nA : cA + (size_t)(t + 2) * kstep; const char* b2 = last ? nB : cB + (size_t)(t + 2) * kstep;
;             const char* a3 = a2 + kstep; const char* b3 = b2 + kstep;
;             if (last && has_next) S.a_ready(nxt);
;             if constexpr (SP2) {
;             PG8_LDB(B0, 0, 0); PG8_LDB(B1, 0, 1); PG8_SCHED; PG8_LDA(At, 0, 0); PG8_STAGE(PG8_SA(1, 1), a1 + hstep, voffA);
;             PG8_WAIT_V(8); PG8_WAIT_L(0); PG8_BAR; PG8_MMA(0, 0, At, B0); PG8_MMA(0, 1, At, B1); PG8_BAR; PG8_SCHED;
;             PG8_LDA(At, 0, 1); PG8_STAGE(PG8_SB(0, 0), b2, voffB); PG8_STAGE(PG8_SB(0, 1), b2 + hstep, voffB); PG8_STAGE(PG8_SA(0, 0), a2, voffA);
.LBB0_654:
	ds_read_b128 v[180:183], v145
	ds_read_b128 v[184:187], v145 offset:1024
	ds_read_b128 v[188:191], v145 offset:2048
	ds_read_b128 v[192:195], v145 offset:3072
	ds_read_b128 v[196:199], v145 offset:4096
	ds_read_b128 v[200:203], v145 offset:5120
	ds_read_b128 v[224:227], v145 offset:6144
	ds_read_b128 v[228:231], v145 offset:7168
	s_add_u32 s64, s58, 0x100
	s_addc_u32 s65, s59, 0
	s_add_i32 s25, 0, 0x10000
	s_cmp_eq_u32 s24, 12
	s_cselect_b32 vcc_hi, s45, s65
	s_cselect_b32 vcc_lo, s77, s64
	v_add_u32_e32 v140, s25, v143
	s_cselect_b32 s67, s43, s15
	s_cselect_b32 s66, s36, s14
	s_add_i32 s30, 0, 0x14000
	ds_read_b128 v[136:139], v140
	ds_read_b128 v[146:149], v140 offset:1024
	ds_read_b128 v[150:153], v140 offset:2048
	ds_read_b128 v[154:157], v140 offset:3072
	v_add_u32_e32 v140, s30, v143
	ds_read_b128 v[158:161], v140
	ds_read_b128 v[168:171], v140 offset:1024
	ds_read_b128 v[172:175], v140 offset:2048
	ds_read_b128 v[176:179], v140 offset:3072
	v_lshl_add_u64 v[140:141], s[58:59], 0, v[132:133]
	s_add_i32 m0, s21, 0xc000
	s_nop 0
	global_load_lds_dwordx4 v[140:141], off
	v_lshl_add_u64 v[140:141], s[58:59], 0, v[134:135]
	s_add_i32 m0, s21, 0xe000
	s_nop 0
	global_load_lds_dwordx4 v[140:141], off
	s_waitcnt vmcnt(8)
	s_waitcnt lgkmcnt(0)
	s_barrier
	s_setprio 1
	v_mfma_f32_16x16x32_bf16 v[126:129], v[136:139], v[180:183], v[126:129]
	v_mfma_f32_16x16x32_bf16 v[126:129], v[146:149], v[184:187], v[126:129]
	v_mfma_f32_16x16x32_bf16 v[122:125], v[150:153], v[180:183], v[122:125]
	v_mfma_f32_16x16x32_bf16 v[122:125], v[154:157], v[184:187], v[122:125]
	v_mfma_f32_16x16x32_bf16 v[110:113], v[136:139], v[188:191], v[110:113]
	v_mfma_f32_16x16x32_bf16 v[110:113], v[146:149], v[192:195], v[110:113]
	v_mfma_f32_16x16x32_bf16 v[106:109], v[150:153], v[188:191], v[106:109]
	v_mfma_f32_16x16x32_bf16 v[106:109], v[154:157], v[192:195], v[106:109]
	v_mfma_f32_16x16x32_bf16 v[94:97], v[136:139], v[196:199], v[94:97]
	v_mfma_f32_16x16x32_bf16 v[94:97], v[146:149], v[200:203], v[94:97]
	v_mfma_f32_16x16x32_bf16 v[90:93], v[150:153], v[196:199], v[90:93]
	v_mfma_f32_16x16x32_bf16 v[90:93], v[154:157], v[200:203], v[90:93]
	v_mfma_f32_16x16x32_bf16 v[78:81], v[136:139], v[224:227], v[78:81]
	v_mfma_f32_16x16x32_bf16 v[78:81], v[146:149], v[228:231], v[78:81]
	v_mfma_f32_16x16x32_bf16 v[74:77], v[150:153], v[224:227], v[74:77]
	v_mfma_f32_16x16x32_bf16 v[74:77], v[154:157], v[228:231], v[74:77]
	v_mfma_f32_16x16x32_bf16 v[118:121], v[158:161], v[180:183], v[118:121]
	v_mfma_f32_16x16x32_bf16 v[118:121], v[168:171], v[184:187], v[118:121]
	v_mfma_f32_16x16x32_bf16 v[114:117], v[172:175], v[180:183], v[114:117]
	v_mfma_f32_16x16x32_bf16 v[114:117], v[176:179], v[184:187], v[114:117]
	v_mfma_f32_16x16x32_bf16 v[102:105], v[158:161], v[188:191], v[102:105]
	v_mfma_f32_16x16x32_bf16 v[102:105], v[168:171], v[192:195], v[102:105]
	v_mfma_f32_16x16x32_bf16 v[98:101], v[172:175], v[188:191], v[98:101]
	v_mfma_f32_16x16x32_bf16 v[98:101], v[176:179], v[192:195], v[98:101]
	v_mfma_f32_16x16x32_bf16 v[86:89], v[158:161], v[196:199], v[86:89]
	v_mfma_f32_16x16x32_bf16 v[86:89], v[168:171], v[200:203], v[86:89]
	v_mfma_f32_16x16x32_bf16 v[82:85], v[172:175], v[196:199], v[82:85]
	v_mfma_f32_16x16x32_bf16 v[82:85], v[176:179], v[200:203], v[82:85]
	v_mfma_f32_16x16x32_bf16 v[70:73], v[158:161], v[224:227], v[70:73]
	v_mfma_f32_16x16x32_bf16 v[70:73], v[168:171], v[228:231], v[70:73]
	v_mfma_f32_16x16x32_bf16 v[66:69], v[172:175], v[224:227], v[66:69]
	v_mfma_f32_16x16x32_bf16 v[66:69], v[176:179], v[228:231], v[66:69]
	s_setprio 0
	s_barrier
	ds_read_b128 v[180:183], v145 offset:16384
	ds_read_b128 v[184:187], v145 offset:17408
	ds_read_b128 v[188:191], v145 offset:18432
	ds_read_b128 v[192:195], v145 offset:19456
	ds_read_b128 v[196:199], v145 offset:20480
	ds_read_b128 v[200:203], v145 offset:21504
	ds_read_b128 v[224:227], v145 offset:22528
	ds_read_b128 v[228:231], v145 offset:23552
	s_add_i32 s25, s25, s16
	v_lshl_add_u64 v[140:141], s[66:67], 0, v[0:1]
	s_mov_b32 m0, s25
	s_nop 0
	global_load_lds_dwordx4 v[140:141], off
	s_add_i32 m0, s25, 0x2000
	s_add_u32 s26, s66, 0x40000
	v_lshl_add_u64 v[214:215], s[66:67], 0, v[130:131]
	s_addc_u32 s27, s67, 0
	s_add_i32 s25, s30, s16
	global_load_lds_dwordx4 v[214:215], off
	v_lshl_add_u64 v[232:233], s[26:27], 0, v[0:1]
	s_mov_b32 m0, s25
	v_lshl_add_u64 v[234:235], vcc, 0, v[130:131]
	global_load_lds_dwordx4 v[232:233], off
	v_lshl_add_u64 v[232:233], s[26:27], 0, v[130:131]
	s_add_i32 m0, s25, 0x2000
	s_nop 0
	global_load_lds_dwordx4 v[232:233], off
	v_lshl_add_u64 v[232:233], vcc, 0, v[0:1]
	s_mov_b32 m0, s21
	s_nop 0
	global_load_lds_dwordx4 v[232:233], off
	s_mov_b32 m0, s22
	s_nop 0
	global_load_lds_dwordx4 v[234:235], off
	s_waitcnt vmcnt(8)
	s_waitcnt lgkmcnt(0)
	s_barrier
; #define PG8_STAGE(bufoff, gbase, voff) do { _Pragma("unroll") for (int _i = 0; _i < 2; ++_i) \
;         __builtin_amdgcn_global_load_lds((const unsigned*)((const char*)(gbase) + (voff)[_i]), (PG8_LAS unsigned*)(lds + (bufoff) + ldsw + _i * 8192), 16, 0, 0); } while (0)
; #define PG8_LDA(dst, b, h) do { _Pragma("unroll") for (int m = 0; m < 4; ++m) _Pragma("unroll") for (int k = 0; k < 2; ++k) dst[m][k] = *(const PG8_LAS bf16x8*)(lds + PG8_SA(b, h) + aoff + m * 2048 + k * 1024); } while (0)
; #define PG8_LDB(dst, b, h) do { _Pragma("unroll") for (int n = 0; n < 2; ++n) _Pragma("unroll") for (int k = 0; k < 2; ++k) dst[n][k] = *(const PG8_LAS bf16x8*)(lds + PG8_SB(b, h) + boff + n * 2048 + k * 1024); } while (0)
; #define PG8_MMA(ai, bj, At, Bt) do { __builtin_amdgcn_s_setprio(1); _Pragma("unroll") for (int m = 0; m < 4; ++m) _Pragma("unroll") for (int n = 0; n < 2; ++n) _Pragma("unroll") for (int k = 0; k < 2; ++k) \
;         acc[ai][bj][m][n] = __builtin_amdgcn_mfma_f32_16x16x32_bf16(Bt[n][k], At[m][k], acc[ai][bj][m][n], 0, 0, 0); __builtin_amdgcn_s_setprio(0); } while (0)
; #define PG8_WAIT_V(n) asm volatile("s_waitcnt vmcnt(" #n ")" ::: "memory")
; #define PG8_WAIT_L(n) asm volatile("s_waitcnt lgkmcnt(" #n ")" ::: "memory")
; #define PG8_BAR __builtin_amdgcn_s_barrier()
; #define PG8_SCHED __builtin_amdgcn_sched_barrier(0)
; template <class Epi, class Sched, bool ALIGN_EPI = false, bool SP2 = false>
; __device__ __forceinline__ void gemm_phase(PG8_LAS unsigned char* lds, const Gemm g, const Sched S, const Epi E) {
;     ...
;             PG8_WAIT_V(8); PG8_WAIT_L(0); PG8_BAR; PG8_MMA(1, 0, At, B0); PG8_MMA(1, 1, At, B1); PG8_BAR; PG8_SCHED;
;             PG8_LDB(B0, 1, 0); PG8_LDB(B1, 1, 1); PG8_SCHED; PG8_LDA(At, 1, 0); PG8_STAGE(PG8_SA(0, 1), a2 + hstep, voffA);
;             PG8_WAIT_V(8); PG8_WAIT_L(0); PG8_BAR; PG8_MMA(0, 0, At, B0); PG8_MMA(0, 1, At, B1); PG8_BAR; PG8_SCHED;
	s_setprio 1
	v_mfma_f32_16x16x32_bf16 v[62:65], v[136:139], v[180:183], v[62:65]
	v_mfma_f32_16x16x32_bf16 v[62:65], v[146:149], v[184:187], v[62:65]
	v_mfma_f32_16x16x32_bf16 v[58:61], v[150:153], v[180:183], v[58:61]
	v_mfma_f32_16x16x32_bf16 v[58:61], v[154:157], v[184:187], v[58:61]
	v_mfma_f32_16x16x32_bf16 v[46:49], v[136:139], v[188:191], v[46:49]
	v_mfma_f32_16x16x32_bf16 v[46:49], v[146:149], v[192:195], v[46:49]
	v_mfma_f32_16x16x32_bf16 v[42:45], v[150:153], v[188:191], v[42:45]
	v_mfma_f32_16x16x32_bf16 v[42:45], v[154:157], v[192:195], v[42:45]
	v_mfma_f32_16x16x32_bf16 v[30:33], v[136:139], v[196:199], v[30:33]
	v_mfma_f32_16x16x32_bf16 v[30:33], v[146:149], v[200:203], v[30:33]
	v_mfma_f32_16x16x32_bf16 v[26:29], v[150:153], v[196:199], v[26:29]
	v_mfma_f32_16x16x32_bf16 v[26:29], v[154:157], v[200:203], v[26:29]
	v_mfma_f32_16x16x32_bf16 v[14:17], v[136:139], v[224:227], v[14:17]
	v_mfma_f32_16x16x32_bf16 v[14:17], v[146:149], v[228:231], v[14:17]
	v_mfma_f32_16x16x32_bf16 v[10:13], v[150:153], v[224:227], v[10:13]
	v_mfma_f32_16x16x32_bf16 v[10:13], v[154:157], v[228:231], v[10:13]
	v_mfma_f32_16x16x32_bf16 v[54:57], v[158:161], v[180:183], v[54:57]
	v_mfma_f32_16x16x32_bf16 v[54:57], v[168:171], v[184:187], v[54:57]
	v_mfma_f32_16x16x32_bf16 v[50:53], v[172:175], v[180:183], v[50:53]
	v_mfma_f32_16x16x32_bf16 v[50:53], v[176:179], v[184:187], v[50:53]
	v_mfma_f32_16x16x32_bf16 v[38:41], v[158:161], v[188:191], v[38:41]
	v_mfma_f32_16x16x32_bf16 v[38:41], v[168:171], v[192:195], v[38:41]
	v_mfma_f32_16x16x32_bf16 v[34:37], v[172:175], v[188:191], v[34:37]
	v_mfma_f32_16x16x32_bf16 v[34:37], v[176:179], v[192:195], v[34:37]
	v_mfma_f32_16x16x32_bf16 v[22:25], v[158:161], v[196:199], v[22:25]
	v_mfma_f32_16x16x32_bf16 v[22:25], v[168:171], v[200:203], v[22:25]
	v_mfma_f32_16x16x32_bf16 v[18:21], v[172:175], v[196:199], v[18:21]
	v_mfma_f32_16x16x32_bf16 v[18:21], v[176:179], v[200:203], v[18:21]
	v_mfma_f32_16x16x32_bf16 v[6:9], v[158:161], v[224:227], v[6:9]
	v_mfma_f32_16x16x32_bf16 v[6:9], v[168:171], v[228:231], v[6:9]
	v_mfma_f32_16x16x32_bf16 v[2:5], v[172:175], v[224:227], v[2:5]
	v_mfma_f32_16x16x32_bf16 v[2:5], v[176:179], v[228:231], v[2:5]
	s_setprio 0
	s_barrier
	ds_read_b128 v[180:183], v145 offset:32768
	ds_read_b128 v[184:187], v145 offset:33792
	ds_read_b128 v[188:191], v145 offset:34816
	ds_read_b128 v[192:195], v145 offset:35840
	ds_read_b128 v[196:199], v145 offset:36864
	ds_read_b128 v[200:203], v145 offset:37888
	ds_read_b128 v[224:227], v145 offset:38912
	ds_read_b128 v[228:231], v145 offset:39936
	s_add_i32 s25, 0, 0x18000
	s_add_i32 s30, 0, 0x1c000
	v_add_u32_e32 v154, s25, v143
	v_add_u32_e32 v167, s30, v143
	ds_read_b128 v[136:139], v154
	ds_read_b128 v[146:149], v154 offset:1024
	ds_read_b128 v[150:153], v154 offset:2048
	ds_read_b128 v[154:157], v154 offset:3072
	ds_read_b128 v[158:161], v167
	ds_read_b128 v[168:171], v167 offset:1024
	ds_read_b128 v[172:175], v167 offset:2048
	ds_read_b128 v[176:179], v167 offset:3072
	s_add_u32 s26, vcc_lo, 0x40000
	s_addc_u32 s27, vcc_hi, 0
	s_mov_b32 m0, s47
	v_lshl_add_u64 v[236:237], s[26:27], 0, v[0:1]
	global_load_lds_dwordx4 v[236:237], off
	v_lshl_add_u64 v[236:237], s[26:27], 0, v[130:131]
	s_mov_b32 m0, s62
	s_nop 0
	global_load_lds_dwordx4 v[236:237], off
	s_waitcnt vmcnt(8)
	s_waitcnt lgkmcnt(0)
	s_barrier
	s_setprio 1
	v_mfma_f32_16x16x32_bf16 v[126:129], v[136:139], v[180:183], v[126:129]
	v_mfma_f32_16x16x32_bf16 v[126:129], v[146:149], v[184:187], v[126:129]
	v_mfma_f32_16x16x32_bf16 v[122:125], v[150:153], v[180:183], v[122:125]
	v_mfma_f32_16x16x32_bf16 v[122:125], v[154:157], v[184:187], v[122:125]
	v_mfma_f32_16x16x32_bf16 v[110:113], v[136:139], v[188:191], v[110:113]
	v_mfma_f32_16x16x32_bf16 v[110:113], v[146:149], v[192:195], v[110:113]
	v_mfma_f32_16x16x32_bf16 v[106:109], v[150:153], v[188:191], v[106:109]
	v_mfma_f32_16x16x32_bf16 v[106:109], v[154:157], v[192:195], v[106:109]
	v_mfma_f32_16x16x32_bf16 v[94:97], v[136:139], v[196:199], v[94:97]
	v_mfma_f32_16x16x32_bf16 v[94:97], v[146:149], v[200:203], v[94:97]
	v_mfma_f32_16x16x32_bf16 v[90:93], v[150:153], v[196:199], v[90:93]
	v_mfma_f32_16x16x32_bf16 v[90:93], v[154:157], v[200:203], v[90:93]
	v_mfma_f32_16x16x32_bf16 v[78:81], v[136:139], v[224:227], v[78:81]
	v_mfma_f32_16x16x32_bf16 v[78:81], v[146:149], v[228:231], v[78:81]
	v_mfma_f32_16x16x32_bf16 v[74:77], v[150:153], v[224:227], v[74:77]
	v_mfma_f32_16x16x32_bf16 v[74:77], v[154:157], v[228:231], v[74:77]
	v_mfma_f32_16x16x32_bf16 v[118:121], v[158:161], v[180:183], v[118:121]
	v_mfma_f32_16x16x32_bf16 v[118:121], v[168:171], v[184:187], v[118:121]
	v_mfma_f32_16x16x32_bf16 v[114:117], v[172:175], v[180:183], v[114:117]
	v_mfma_f32_16x16x32_bf16 v[114:117], v[176:179], v[184:187], v[114:117]
	v_mfma_f32_16x16x32_bf16 v[102:105], v[158:161], v[188:191], v[102:105]
	v_mfma_f32_16x16x32_bf16 v[102:105], v[168:171], v[192:195], v[102:105]
	v_mfma_f32_16x16x32_bf16 v[98:101], v[172:175], v[188:191], v[98:101]
	v_mfma_f32_16x16x32_bf16 v[98:101], v[176:179], v[192:195], v[98:101]
	v_mfma_f32_16x16x32_bf16 v[86:89], v[158:161], v[196:199], v[86:89]
	v_mfma_f32_16x16x32_bf16 v[86:89], v[168:171], v[200:203], v[86:89]
	v_mfma_f32_16x16x32_bf16 v[82:85], v[172:175], v[196:199], v[82:85]
	v_mfma_f32_16x16x32_bf16 v[82:85], v[176:179], v[200:203], v[82:85]
	v_mfma_f32_16x16x32_bf16 v[70:73], v[158:161], v[224:227], v[70:73]
	v_mfma_f32_16x16x32_bf16 v[70:73], v[168:171], v[228:231], v[70:73]
	v_mfma_f32_16x16x32_bf16 v[66:69], v[172:175], v[224:227], v[66:69]
	v_mfma_f32_16x16x32_bf16 v[66:69], v[176:179], v[228:231], v[66:69]
	s_setprio 0
	s_barrier
; #define PG8_STAGE(bufoff, gbase, voff) do { _Pragma("unroll") for (int _i = 0; _i < 2; ++_i) \
;         __builtin_amdgcn_global_load_lds((const unsigned*)((const char*)(gbase) + (voff)[_i]), (PG8_LAS unsigned*)(lds + (bufoff) + ldsw + _i * 8192), 16, 0, 0); } while (0)
; #define PG8_LDA(dst, b, h) do { _Pragma("unroll") for (int m = 0; m < 4; ++m) _Pragma("unroll") for (int k = 0; k < 2; ++k) dst[m][k] = *(const PG8_LAS bf16x8*)(lds + PG8_SA(b, h) + aoff + m * 2048 + k * 1024); } while (0)
; #define PG8_MMA(ai, bj, At, Bt) do { __builtin_amdgcn_s_setprio(1); _Pragma("unroll") for (int m = 0; m < 4; ++m) _Pragma("unroll") for (int n = 0; n < 2; ++n) _Pragma("unroll") for (int k = 0; k < 2; ++k) \
;         acc[ai][bj][m][n] = __builtin_amdgcn_mfma_f32_16x16x32_bf16(Bt[n][k], At[m][k], acc[ai][bj][m][n], 0, 0, 0); __builtin_amdgcn_s_setprio(0); } while (0)
; #define PG8_WAIT_V(n) asm volatile("s_waitcnt vmcnt(" #n ")" ::: "memory")
; #define PG8_WAIT_L(n) asm volatile("s_waitcnt lgkmcnt(" #n ")" ::: "memory")
; #define PG8_BAR __builtin_amdgcn_s_barrier()
; #define PG8_SCHED __builtin_amdgcn_sched_barrier(0)
; template <class Epi, class Sched, bool ALIGN_EPI = false, bool SP2 = false>
; __device__ __forceinline__ void gemm_phase(PG8_LAS unsigned char* lds, const Gemm g, const Sched S, const Epi E) {
;     ...
;         for (int t = 0; t < nt; t += 2) {
;             const bool last = (t == nt - 2);
;             const char* a1 = cA + (size_t)(t + 1) * kstep;
;             const char* a2 = last ? nA : cA + (size_t)(t + 2) * kstep; const char* b2 = last ? nB : cB + (size_t)(t + 2) * kstep;
;             const char* a3 = a2 + kstep; const char* b3 = b2 + kstep;
;             if (last && has_next) S.a_ready(nxt);
;     ...
;             PG8_LDA(At, 1, 1); PG8_STAGE(PG8_SB(1, 0), b3, voffB); PG8_STAGE(PG8_SB(1, 1), b3 + hstep, voffB); PG8_STAGE(PG8_SA(1, 0), a3, voffA);
;             PG8_WAIT_V(8); PG8_WAIT_L(0); PG8_BAR; PG8_MMA(1, 0, At, B0); PG8_MMA(1, 1, At, B1); PG8_BAR; PG8_SCHED;
	ds_read_b128 v[180:183], v145 offset:49152
	ds_read_b128 v[184:187], v145 offset:50176
	ds_read_b128 v[188:191], v145 offset:51200
	ds_read_b128 v[192:195], v145 offset:52224
	ds_read_b128 v[196:199], v145 offset:53248
	ds_read_b128 v[200:203], v145 offset:54272
	ds_read_b128 v[224:227], v145 offset:55296
	ds_read_b128 v[228:231], v145 offset:56320
	s_add_i32 s25, s25, s16
	v_lshl_add_u64 v[140:141], v[140:141], 0, s[28:29]
	s_mov_b32 m0, s25
	s_nop 0
	global_load_lds_dwordx4 v[140:141], off
	s_add_i32 m0, s25, 0x2000
	s_add_u32 s26, s66, 0x40080
	v_lshl_add_u64 v[140:141], v[214:215], 0, s[28:29]
	s_addc_u32 s27, s67, 0
	s_add_i32 s25, s30, s16
	global_load_lds_dwordx4 v[140:141], off
	v_lshl_add_u64 v[140:141], s[26:27], 0, v[0:1]
	s_mov_b32 m0, s25
	s_nop 0
	global_load_lds_dwordx4 v[140:141], off
	v_lshl_add_u64 v[140:141], s[26:27], 0, v[130:131]
	s_add_i32 m0, s25, 0x2000
	s_nop 0
	global_load_lds_dwordx4 v[140:141], off
	v_lshl_add_u64 v[140:141], v[232:233], 0, s[28:29]
	s_mov_b32 m0, s63
	s_nop 0
	global_load_lds_dwordx4 v[140:141], off
	v_lshl_add_u64 v[140:141], v[234:235], 0, s[28:29]
	s_mov_b32 m0, s74
	s_nop 0
	global_load_lds_dwordx4 v[140:141], off
	s_waitcnt vmcnt(8)
	s_waitcnt lgkmcnt(0)
	s_barrier
	s_setprio 1
	v_mfma_f32_16x16x32_bf16 v[62:65], v[136:139], v[180:183], v[62:65]
	v_mfma_f32_16x16x32_bf16 v[62:65], v[146:149], v[184:187], v[62:65]
	v_mfma_f32_16x16x32_bf16 v[58:61], v[150:153], v[180:183], v[58:61]
	v_mfma_f32_16x16x32_bf16 v[58:61], v[154:157], v[184:187], v[58:61]
	v_mfma_f32_16x16x32_bf16 v[46:49], v[136:139], v[188:191], v[46:49]
	v_mfma_f32_16x16x32_bf16 v[46:49], v[146:149], v[192:195], v[46:49]
	v_mfma_f32_16x16x32_bf16 v[42:45], v[150:153], v[188:191], v[42:45]
	v_mfma_f32_16x16x32_bf16 v[42:45], v[154:157], v[192:195], v[42:45]
	v_mfma_f32_16x16x32_bf16 v[30:33], v[136:139], v[196:199], v[30:33]
	v_mfma_f32_16x16x32_bf16 v[30:33], v[146:149], v[200:203], v[30:33]
	v_mfma_f32_16x16x32_bf16 v[26:29], v[150:153], v[196:199], v[26:29]
	v_mfma_f32_16x16x32_bf16 v[26:29], v[154:157], v[200:203], v[26:29]
	v_mfma_f32_16x16x32_bf16 v[14:17], v[136:139], v[224:227], v[14:17]
	v_mfma_f32_16x16x32_bf16 v[14:17], v[146:149], v[228:231], v[14:17]
	v_mfma_f32_16x16x32_bf16 v[10:13], v[150:153], v[224:227], v[10:13]
	v_mfma_f32_16x16x32_bf16 v[10:13], v[154:157], v[228:231], v[10:13]
	v_mfma_f32_16x16x32_bf16 v[54:57], v[158:161], v[180:183], v[54:57]
	v_mfma_f32_16x16x32_bf16 v[54:57], v[168:171], v[184:187], v[54:57]
	v_mfma_f32_16x16x32_bf16 v[50:53], v[172:175], v[180:183], v[50:53]
	v_mfma_f32_16x16x32_bf16 v[50:53], v[176:179], v[184:187], v[50:53]
	v_mfma_f32_16x16x32_bf16 v[38:41], v[158:161], v[188:191], v[38:41]
	v_mfma_f32_16x16x32_bf16 v[38:41], v[168:171], v[192:195], v[38:41]
	v_mfma_f32_16x16x32_bf16 v[34:37], v[172:175], v[188:191], v[34:37]
	v_mfma_f32_16x16x32_bf16 v[34:37], v[176:179], v[192:195], v[34:37]
	v_mfma_f32_16x16x32_bf16 v[22:25], v[158:161], v[196:199], v[22:25]
	v_mfma_f32_16x16x32_bf16 v[22:25], v[168:171], v[200:203], v[22:25]
	v_mfma_f32_16x16x32_bf16 v[18:21], v[172:175], v[196:199], v[18:21]
	v_mfma_f32_16x16x32_bf16 v[18:21], v[176:179], v[200:203], v[18:21]
	v_mfma_f32_16x16x32_bf16 v[6:9], v[158:161], v[224:227], v[6:9]
	v_mfma_f32_16x16x32_bf16 v[6:9], v[168:171], v[228:231], v[6:9]
	v_mfma_f32_16x16x32_bf16 v[2:5], v[172:175], v[224:227], v[2:5]
	v_mfma_f32_16x16x32_bf16 v[2:5], v[176:179], v[228:231], v[2:5]
	s_setprio 0
	s_barrier
	s_add_i32 s24, s24, 2
	s_add_u32 s14, s14, 0x100
	s_addc_u32 s15, s15, 0
	s_cmp_gt_u32 s24, 13
	s_mov_b64 s[58:59], s[64:65]
	s_cbranch_scc0 .LBB0_654
	s_and_b64 vcc, exec, s[8:9]
	s_cbranch_vccz .LBB0_657
	s_barrier

; #define PG8_STAGE(bufoff, gbase, voff) do { _Pragma("unroll") for (int _i = 0; _i < 2; ++_i) \
;         __builtin_amdgcn_global_load_lds((const unsigned*)((const char*)(gbase) + (voff)[_i]), (PG8_LAS unsigned*)(lds + (bufoff) + ldsw + _i * 8192), 16, 0, 0); } while (0)
; #define PG8_LDA(dst, b, h) do { _Pragma("unroll") for (int m = 0; m < 4; ++m) _Pragma("unroll") for (int k = 0; k < 2; ++k) dst[m][k] = *(const PG8_LAS bf16x8*)(lds + PG8_SA(b, h) + aoff + m * 2048 + k * 1024); } while (0)
; #define PG8_LDB(dst, b, h) do { _Pragma("unroll") for (int n = 0; n < 2; ++n) _Pragma("unroll") for (int k = 0; k < 2; ++k) dst[n][k] = *(const PG8_LAS bf16x8*)(lds + PG8_SB(b, h) + boff + n * 2048 + k * 1024); } while (0)
; #define PG8_MMA(ai, bj, At, Bt) do { __builtin_amdgcn_s_setprio(1); _Pragma("unroll") for (int m = 0; m < 4; ++m) _Pragma("unroll") for (int n = 0; n < 2; ++n) _Pragma("unroll") for (int k = 0; k < 2; ++k) \
;         acc[ai][bj][m][n] = __builtin_amdgcn_mfma_f32_16x16x32_bf16(Bt[n][k], At[m][k], acc[ai][bj][m][n], 0, 0, 0); __builtin_amdgcn_s_setprio(0); } while (0)
; #define PG8_WAIT_V(n) asm volatile("s_waitcnt vmcnt(" #n ")" ::: "memory")
; #define PG8_WAIT_L(n) asm volatile("s_waitcnt lgkmcnt(" #n ")" ::: "memory")
; #define PG8_BAR __builtin_amdgcn_s_barrier()
; #define PG8_SCHED __builtin_amdgcn_sched_barrier(0)
; template <class Epi, class Sched, bool ALIGN_EPI = false, bool SP2 = false>
; __device__ __forceinline__ void gemm_phase(PG8_LAS unsigned char* lds, const Gemm g, const Sched S, const Epi E) {
;     ...
;         for (int t = 0; t < nt; t += 2) {
;             const bool last = (t == nt - 2);
;             const char* a1 = cA + (size_t)(t + 1) * kstep;
;             const char* a2 = last ? nA : cA + (size_t)(t + 2) * kstep; const char* b2 = last ? nB : cB + (size_t)(t + 2) * kstep;
;             const char* a3 = a2 + kstep; const char* b3 = b2 + kstep;
;             if (last && has_next) S.a_ready(nxt);
;             if constexpr (SP2) {
;             PG8_LDB(B0, 0, 0); PG8_LDB(B1, 0, 1); PG8_SCHED; PG8_LDA(At, 0, 0); PG8_STAGE(PG8_SA(1, 1), a1 + hstep, voffA);
;             PG8_WAIT_V(8); PG8_WAIT_L(0); PG8_BAR; PG8_MMA(0, 0, At, B0); PG8_MMA(0, 1, At, B1); PG8_BAR; PG8_SCHED;
;             PG8_LDA(At, 0, 1); PG8_STAGE(PG8_SB(0, 0), b2, voffB); PG8_STAGE(PG8_SB(0, 1), b2 + hstep, voffB); PG8_STAGE(PG8_SA(0, 0), a2, voffA);
.LBB0_726:
	ds_read_b128 v[180:183], v143
	ds_read_b128 v[184:187], v143 offset:1024
	ds_read_b128 v[188:191], v143 offset:2048
	ds_read_b128 v[192:195], v143 offset:3072
	ds_read_b128 v[196:199], v143 offset:4096
	ds_read_b128 v[200:203], v143 offset:5120
	ds_read_b128 v[224:227], v143 offset:6144
	ds_read_b128 v[228:231], v143 offset:7168
	s_add_u32 s25, s40, 0xfff80080
	s_addc_u32 s26, s41, -1
	s_add_i32 s27, 0, 0x10000
	s_cmp_eq_u32 s24, 28
	s_cselect_b32 s45, s57, s26
	s_cselect_b32 s44, s66, s25
	s_cselect_b32 s43, s53, s15
	s_cselect_b32 s42, s67, s14
	s_add_i32 s25, 0, 0x14000
	v_add_u32_e32 v152, s27, v141
	v_add_u32_e32 v160, s25, v141
	ds_read_b128 v[136:139], v152
	ds_read_b128 v[144:147], v152 offset:1024
	ds_read_b128 v[148:151], v152 offset:2048
	ds_read_b128 v[152:155], v152 offset:3072
	ds_read_b128 v[156:159], v160
	ds_read_b128 v[168:171], v160 offset:1024
	ds_read_b128 v[172:175], v160 offset:2048
	ds_read_b128 v[176:179], v160 offset:3072
	v_lshl_add_u64 v[160:161], s[40:41], 0, v[132:133]
	s_add_i32 m0, s21, 0xc000
	s_nop 0
	global_load_lds_dwordx4 v[160:161], off
	v_lshl_add_u64 v[160:161], s[40:41], 0, v[134:135]
	s_add_i32 m0, s21, 0xe000
	s_nop 0
	global_load_lds_dwordx4 v[160:161], off
	s_waitcnt vmcnt(8)
	s_waitcnt lgkmcnt(0)
	s_barrier
	s_setprio 1
	v_mfma_f32_16x16x32_bf16 v[126:129], v[136:139], v[180:183], v[126:129]
	v_mfma_f32_16x16x32_bf16 v[126:129], v[144:147], v[184:187], v[126:129]
	v_mfma_f32_16x16x32_bf16 v[122:125], v[148:151], v[180:183], v[122:125]
	v_mfma_f32_16x16x32_bf16 v[122:125], v[152:155], v[184:187], v[122:125]
	v_mfma_f32_16x16x32_bf16 v[114:117], v[136:139], v[188:191], v[114:117]
	v_mfma_f32_16x16x32_bf16 v[114:117], v[144:147], v[192:195], v[114:117]
	v_mfma_f32_16x16x32_bf16 v[106:109], v[148:151], v[188:191], v[106:109]
	v_mfma_f32_16x16x32_bf16 v[106:109], v[152:155], v[192:195], v[106:109]
	v_mfma_f32_16x16x32_bf16 v[98:101], v[136:139], v[196:199], v[98:101]
	v_mfma_f32_16x16x32_bf16 v[98:101], v[144:147], v[200:203], v[98:101]
	v_mfma_f32_16x16x32_bf16 v[90:93], v[148:151], v[196:199], v[90:93]
	v_mfma_f32_16x16x32_bf16 v[90:93], v[152:155], v[200:203], v[90:93]
	v_mfma_f32_16x16x32_bf16 v[82:85], v[136:139], v[224:227], v[82:85]
	v_mfma_f32_16x16x32_bf16 v[82:85], v[144:147], v[228:231], v[82:85]
	v_mfma_f32_16x16x32_bf16 v[74:77], v[148:151], v[224:227], v[74:77]
	v_mfma_f32_16x16x32_bf16 v[74:77], v[152:155], v[228:231], v[74:77]
	v_mfma_f32_16x16x32_bf16 v[118:121], v[156:159], v[180:183], v[118:121]
	v_mfma_f32_16x16x32_bf16 v[118:121], v[168:171], v[184:187], v[118:121]
	v_mfma_f32_16x16x32_bf16 v[110:113], v[172:175], v[180:183], v[110:113]
	v_mfma_f32_16x16x32_bf16 v[110:113], v[176:179], v[184:187], v[110:113]
	v_mfma_f32_16x16x32_bf16 v[102:105], v[156:159], v[188:191], v[102:105]
	v_mfma_f32_16x16x32_bf16 v[102:105], v[168:171], v[192:195], v[102:105]
	v_mfma_f32_16x16x32_bf16 v[94:97], v[172:175], v[188:191], v[94:97]
	v_mfma_f32_16x16x32_bf16 v[94:97], v[176:179], v[192:195], v[94:97]
	v_mfma_f32_16x16x32_bf16 v[86:89], v[156:159], v[196:199], v[86:89]
	v_mfma_f32_16x16x32_bf16 v[86:89], v[168:171], v[200:203], v[86:89]
	v_mfma_f32_16x16x32_bf16 v[78:81], v[172:175], v[196:199], v[78:81]
	v_mfma_f32_16x16x32_bf16 v[78:81], v[176:179], v[200:203], v[78:81]
	v_mfma_f32_16x16x32_bf16 v[70:73], v[156:159], v[224:227], v[70:73]
	v_mfma_f32_16x16x32_bf16 v[70:73], v[168:171], v[228:231], v[70:73]
	v_mfma_f32_16x16x32_bf16 v[66:69], v[172:175], v[224:227], v[66:69]
	v_mfma_f32_16x16x32_bf16 v[66:69], v[176:179], v[228:231], v[66:69]
	s_setprio 0
	s_barrier
	ds_read_b128 v[180:183], v143 offset:16384
	ds_read_b128 v[184:187], v143 offset:17408
	ds_read_b128 v[188:191], v143 offset:18432
	ds_read_b128 v[192:195], v143 offset:19456
	ds_read_b128 v[196:199], v143 offset:20480
	ds_read_b128 v[200:203], v143 offset:21504
	ds_read_b128 v[224:227], v143 offset:22528
	ds_read_b128 v[228:231], v143 offset:23552
	s_add_i32 s26, s27, s16
	v_lshl_add_u64 v[160:161], s[42:43], 0, v[0:1]
	s_mov_b32 m0, s26
	s_nop 0
	global_load_lds_dwordx4 v[160:161], off
	s_add_i32 m0, s26, 0x2000
	s_add_u32 s26, s42, 0x80000
	v_lshl_add_u64 v[232:233], s[42:43], 0, v[130:131]
	s_addc_u32 s27, s43, 0
	s_add_i32 s25, s25, s16
	global_load_lds_dwordx4 v[232:233], off
	v_lshl_add_u64 v[234:235], s[26:27], 0, v[0:1]
	s_mov_b32 m0, s25
	v_lshl_add_u64 v[236:237], s[44:45], 0, v[130:131]
	global_load_lds_dwordx4 v[234:235], off
	v_lshl_add_u64 v[234:235], s[26:27], 0, v[130:131]
	s_add_i32 m0, s25, 0x2000
	s_nop 0
	global_load_lds_dwordx4 v[234:235], off
	v_lshl_add_u64 v[234:235], s[44:45], 0, v[0:1]
	s_mov_b32 m0, s21
	s_nop 0
	global_load_lds_dwordx4 v[234:235], off
	s_mov_b32 m0, s22
	s_nop 0
	global_load_lds_dwordx4 v[236:237], off
	s_waitcnt vmcnt(8)
	s_waitcnt lgkmcnt(0)
	s_barrier
; #define PG8_STAGE(bufoff, gbase, voff) do { _Pragma("unroll") for (int _i = 0; _i < 2; ++_i) \
;         __builtin_amdgcn_global_load_lds((const unsigned*)((const char*)(gbase) + (voff)[_i]), (PG8_LAS unsigned*)(lds + (bufoff) + ldsw + _i * 8192), 16, 0, 0); } while (0)
; #define PG8_LDA(dst, b, h) do { _Pragma("unroll") for (int m = 0; m < 4; ++m) _Pragma("unroll") for (int k = 0; k < 2; ++k) dst[m][k] = *(const PG8_LAS bf16x8*)(lds + PG8_SA(b, h) + aoff + m * 2048 + k * 1024); } while (0)
; #define PG8_LDB(dst, b, h) do { _Pragma("unroll") for (int n = 0; n < 2; ++n) _Pragma("unroll") for (int k = 0; k < 2; ++k) dst[n][k] = *(const PG8_LAS bf16x8*)(lds + PG8_SB(b, h) + boff + n * 2048 + k * 1024); } while (0)
; #define PG8_MMA(ai, bj, At, Bt) do { __builtin_amdgcn_s_setprio(1); _Pragma("unroll") for (int m = 0; m < 4; ++m) _Pragma("unroll") for (int n = 0; n < 2; ++n) _Pragma("unroll") for (int k = 0; k < 2; ++k) \
;         acc[ai][bj][m][n] = __builtin_amdgcn_mfma_f32_16x16x32_bf16(Bt[n][k], At[m][k], acc[ai][bj][m][n], 0, 0, 0); __builtin_amdgcn_s_setprio(0); } while (0)
; #define PG8_WAIT_V(n) asm volatile("s_waitcnt vmcnt(" #n ")" ::: "memory")
; #define PG8_WAIT_L(n) asm volatile("s_waitcnt lgkmcnt(" #n ")" ::: "memory")
; #define PG8_BAR __builtin_amdgcn_s_barrier()
; #define PG8_SCHED __builtin_amdgcn_sched_barrier(0)
; template <class Epi, class Sched, bool ALIGN_EPI = false, bool SP2 = false>
; __device__ __forceinline__ void gemm_phase(PG8_LAS unsigned char* lds, const Gemm g, const Sched S, const Epi E) {
;     ...
;             PG8_WAIT_V(8); PG8_WAIT_L(0); PG8_BAR; PG8_MMA(1, 0, At, B0); PG8_MMA(1, 1, At, B1); PG8_BAR; PG8_SCHED;
;             PG8_LDB(B0, 1, 0); PG8_LDB(B1, 1, 1); PG8_SCHED; PG8_LDA(At, 1, 0); PG8_STAGE(PG8_SA(0, 1), a2 + hstep, voffA);
;             PG8_WAIT_V(8); PG8_WAIT_L(0); PG8_BAR; PG8_MMA(0, 0, At, B0); PG8_MMA(0, 1, At, B1); PG8_BAR; PG8_SCHED;
	s_setprio 1
	v_mfma_f32_16x16x32_bf16 v[62:65], v[136:139], v[180:183], v[62:65]
	v_mfma_f32_16x16x32_bf16 v[62:65], v[144:147], v[184:187], v[62:65]
	v_mfma_f32_16x16x32_bf16 v[58:61], v[148:151], v[180:183], v[58:61]
	v_mfma_f32_16x16x32_bf16 v[58:61], v[152:155], v[184:187], v[58:61]
	v_mfma_f32_16x16x32_bf16 v[50:53], v[136:139], v[188:191], v[50:53]
	v_mfma_f32_16x16x32_bf16 v[50:53], v[144:147], v[192:195], v[50:53]
	v_mfma_f32_16x16x32_bf16 v[42:45], v[148:151], v[188:191], v[42:45]
	v_mfma_f32_16x16x32_bf16 v[42:45], v[152:155], v[192:195], v[42:45]
	v_mfma_f32_16x16x32_bf16 v[34:37], v[136:139], v[196:199], v[34:37]
	v_mfma_f32_16x16x32_bf16 v[34:37], v[144:147], v[200:203], v[34:37]
	v_mfma_f32_16x16x32_bf16 v[26:29], v[148:151], v[196:199], v[26:29]
	v_mfma_f32_16x16x32_bf16 v[26:29], v[152:155], v[200:203], v[26:29]
	v_mfma_f32_16x16x32_bf16 v[18:21], v[136:139], v[224:227], v[18:21]
	v_mfma_f32_16x16x32_bf16 v[18:21], v[144:147], v[228:231], v[18:21]
	v_mfma_f32_16x16x32_bf16 v[10:13], v[148:151], v[224:227], v[10:13]
	v_mfma_f32_16x16x32_bf16 v[10:13], v[152:155], v[228:231], v[10:13]
	v_mfma_f32_16x16x32_bf16 v[54:57], v[156:159], v[180:183], v[54:57]
	v_mfma_f32_16x16x32_bf16 v[54:57], v[168:171], v[184:187], v[54:57]
	v_mfma_f32_16x16x32_bf16 v[46:49], v[172:175], v[180:183], v[46:49]
	v_mfma_f32_16x16x32_bf16 v[46:49], v[176:179], v[184:187], v[46:49]
	v_mfma_f32_16x16x32_bf16 v[38:41], v[156:159], v[188:191], v[38:41]
	v_mfma_f32_16x16x32_bf16 v[38:41], v[168:171], v[192:195], v[38:41]
	v_mfma_f32_16x16x32_bf16 v[30:33], v[172:175], v[188:191], v[30:33]
	v_mfma_f32_16x16x32_bf16 v[30:33], v[176:179], v[192:195], v[30:33]
	v_mfma_f32_16x16x32_bf16 v[22:25], v[156:159], v[196:199], v[22:25]
	v_mfma_f32_16x16x32_bf16 v[22:25], v[168:171], v[200:203], v[22:25]
	v_mfma_f32_16x16x32_bf16 v[14:17], v[172:175], v[196:199], v[14:17]
	v_mfma_f32_16x16x32_bf16 v[14:17], v[176:179], v[200:203], v[14:17]
	v_mfma_f32_16x16x32_bf16 v[6:9], v[156:159], v[224:227], v[6:9]
	v_mfma_f32_16x16x32_bf16 v[6:9], v[168:171], v[228:231], v[6:9]
	v_mfma_f32_16x16x32_bf16 v[2:5], v[172:175], v[224:227], v[2:5]
	v_mfma_f32_16x16x32_bf16 v[2:5], v[176:179], v[228:231], v[2:5]
	s_setprio 0
	s_barrier
	ds_read_b128 v[180:183], v143 offset:32768
	ds_read_b128 v[184:187], v143 offset:33792
	ds_read_b128 v[188:191], v143 offset:34816
	ds_read_b128 v[192:195], v143 offset:35840
	ds_read_b128 v[196:199], v143 offset:36864
	ds_read_b128 v[200:203], v143 offset:37888
	ds_read_b128 v[224:227], v143 offset:38912
	ds_read_b128 v[228:231], v143 offset:39936
	s_add_i32 s25, 0, 0x18000
	s_add_i32 s30, 0, 0x1c000
	v_add_u32_e32 v152, s25, v141
	v_add_u32_e32 v167, s30, v141
	ds_read_b128 v[136:139], v152
	ds_read_b128 v[144:147], v152 offset:1024
	ds_read_b128 v[148:151], v152 offset:2048
	ds_read_b128 v[152:155], v152 offset:3072
	ds_read_b128 v[156:159], v167
	ds_read_b128 v[168:171], v167 offset:1024
	ds_read_b128 v[172:175], v167 offset:2048
	ds_read_b128 v[176:179], v167 offset:3072
	s_add_u32 s26, s44, 0x80000
	s_addc_u32 s27, s45, 0
	s_mov_b32 m0, s47
	v_lshl_add_u64 v[238:239], s[26:27], 0, v[0:1]
	global_load_lds_dwordx4 v[238:239], off
	v_lshl_add_u64 v[238:239], s[26:27], 0, v[130:131]
	s_mov_b32 m0, s62
	s_nop 0
	global_load_lds_dwordx4 v[238:239], off
	s_waitcnt vmcnt(8)
	s_waitcnt lgkmcnt(0)
	s_barrier
	s_setprio 1
	v_mfma_f32_16x16x32_bf16 v[126:129], v[136:139], v[180:183], v[126:129]
	v_mfma_f32_16x16x32_bf16 v[126:129], v[144:147], v[184:187], v[126:129]
	v_mfma_f32_16x16x32_bf16 v[122:125], v[148:151], v[180:183], v[122:125]
	v_mfma_f32_16x16x32_bf16 v[122:125], v[152:155], v[184:187], v[122:125]
	v_mfma_f32_16x16x32_bf16 v[114:117], v[136:139], v[188:191], v[114:117]
	v_mfma_f32_16x16x32_bf16 v[114:117], v[144:147], v[192:195], v[114:117]
	v_mfma_f32_16x16x32_bf16 v[106:109], v[148:151], v[188:191], v[106:109]
	v_mfma_f32_16x16x32_bf16 v[106:109], v[152:155], v[192:195], v[106:109]
	v_mfma_f32_16x16x32_bf16 v[98:101], v[136:139], v[196:199], v[98:101]
	v_mfma_f32_16x16x32_bf16 v[98:101], v[144:147], v[200:203], v[98:101]
	v_mfma_f32_16x16x32_bf16 v[90:93], v[148:151], v[196:199], v[90:93]
	v_mfma_f32_16x16x32_bf16 v[90:93], v[152:155], v[200:203], v[90:93]
	v_mfma_f32_16x16x32_bf16 v[82:85], v[136:139], v[224:227], v[82:85]
	v_mfma_f32_16x16x32_bf16 v[82:85], v[144:147], v[228:231], v[82:85]
	v_mfma_f32_16x16x32_bf16 v[74:77], v[148:151], v[224:227], v[74:77]
	v_mfma_f32_16x16x32_bf16 v[74:77], v[152:155], v[228:231], v[74:77]
	v_mfma_f32_16x16x32_bf16 v[118:121], v[156:159], v[180:183], v[118:121]
	v_mfma_f32_16x16x32_bf16 v[118:121], v[168:171], v[184:187], v[118:121]
	v_mfma_f32_16x16x32_bf16 v[110:113], v[172:175], v[180:183], v[110:113]
	v_mfma_f32_16x16x32_bf16 v[110:113], v[176:179], v[184:187], v[110:113]
	v_mfma_f32_16x16x32_bf16 v[102:105], v[156:159], v[188:191], v[102:105]
	v_mfma_f32_16x16x32_bf16 v[102:105], v[168:171], v[192:195], v[102:105]
	v_mfma_f32_16x16x32_bf16 v[94:97], v[172:175], v[188:191], v[94:97]
	v_mfma_f32_16x16x32_bf16 v[94:97], v[176:179], v[192:195], v[94:97]
	v_mfma_f32_16x16x32_bf16 v[86:89], v[156:159], v[196:199], v[86:89]
	v_mfma_f32_16x16x32_bf16 v[86:89], v[168:171], v[200:203], v[86:89]
	v_mfma_f32_16x16x32_bf16 v[78:81], v[172:175], v[196:199], v[78:81]
	v_mfma_f32_16x16x32_bf16 v[78:81], v[176:179], v[200:203], v[78:81]
	v_mfma_f32_16x16x32_bf16 v[70:73], v[156:159], v[224:227], v[70:73]
	v_mfma_f32_16x16x32_bf16 v[70:73], v[168:171], v[228:231], v[70:73]
	v_mfma_f32_16x16x32_bf16 v[66:69], v[172:175], v[224:227], v[66:69]
	v_mfma_f32_16x16x32_bf16 v[66:69], v[176:179], v[228:231], v[66:69]
	s_setprio 0
	s_barrier
; #define PG8_STAGE(bufoff, gbase, voff) do { _Pragma("unroll") for (int _i = 0; _i < 2; ++_i) \
;         __builtin_amdgcn_global_load_lds((const unsigned*)((const char*)(gbase) + (voff)[_i]), (PG8_LAS unsigned*)(lds + (bufoff) + ldsw + _i * 8192), 16, 0, 0); } while (0)
; #define PG8_LDA(dst, b, h) do { _Pragma("unroll") for (int m = 0; m < 4; ++m) _Pragma("unroll") for (int k = 0; k < 2; ++k) dst[m][k] = *(const PG8_LAS bf16x8*)(lds + PG8_SA(b, h) + aoff + m * 2048 + k * 1024); } while (0)
; #define PG8_MMA(ai, bj, At, Bt) do { __builtin_amdgcn_s_setprio(1); _Pragma("unroll") for (int m = 0; m < 4; ++m) _Pragma("unroll") for (int n = 0; n < 2; ++n) _Pragma("unroll") for (int k = 0; k < 2; ++k) \
;         acc[ai][bj][m][n] = __builtin_amdgcn_mfma_f32_16x16x32_bf16(Bt[n][k], At[m][k], acc[ai][bj][m][n], 0, 0, 0); __builtin_amdgcn_s_setprio(0); } while (0)
; #define PG8_WAIT_V(n) asm volatile("s_waitcnt vmcnt(" #n ")" ::: "memory")
; #define PG8_WAIT_L(n) asm volatile("s_waitcnt lgkmcnt(" #n ")" ::: "memory")
; #define PG8_BAR __builtin_amdgcn_s_barrier()
; #define PG8_SCHED __builtin_amdgcn_sched_barrier(0)
; template <class Epi, class Sched, bool ALIGN_EPI = false, bool SP2 = false>
; __device__ __forceinline__ void gemm_phase(PG8_LAS unsigned char* lds, const Gemm g, const Sched S, const Epi E) {
;     ...
;         for (int t = 0; t < nt; t += 2) {
;             const bool last = (t == nt - 2);
;             const char* a1 = cA + (size_t)(t + 1) * kstep;
;             const char* a2 = last ? nA : cA + (size_t)(t + 2) * kstep; const char* b2 = last ? nB : cB + (size_t)(t + 2) * kstep;
;             const char* a3 = a2 + kstep; const char* b3 = b2 + kstep;
;             if (last && has_next) S.a_ready(nxt);
;     ...
;             PG8_LDA(At, 1, 1); PG8_STAGE(PG8_SB(1, 0), b3, voffB); PG8_STAGE(PG8_SB(1, 1), b3 + hstep, voffB); PG8_STAGE(PG8_SA(1, 0), a3, voffA);
;             PG8_WAIT_V(8); PG8_WAIT_L(0); PG8_BAR; PG8_MMA(1, 0, At, B0); PG8_MMA(1, 1, At, B1); PG8_BAR; PG8_SCHED;
	ds_read_b128 v[180:183], v143 offset:49152
	ds_read_b128 v[184:187], v143 offset:50176
	ds_read_b128 v[188:191], v143 offset:51200
	ds_read_b128 v[192:195], v143 offset:52224
	ds_read_b128 v[196:199], v143 offset:53248
	ds_read_b128 v[200:203], v143 offset:54272
	ds_read_b128 v[224:227], v143 offset:55296
	ds_read_b128 v[228:231], v143 offset:56320
	s_add_i32 s25, s25, s16
	v_lshl_add_u64 v[160:161], v[160:161], 0, s[28:29]
	s_mov_b32 m0, s25
	s_nop 0
	global_load_lds_dwordx4 v[160:161], off
	s_add_i32 m0, s25, 0x2000
	s_add_u32 s26, s42, 0x80080
	v_lshl_add_u64 v[160:161], v[232:233], 0, s[28:29]
	s_addc_u32 s27, s43, 0
	s_add_i32 s25, s30, s16
	global_load_lds_dwordx4 v[160:161], off
	v_lshl_add_u64 v[160:161], s[26:27], 0, v[0:1]
	s_mov_b32 m0, s25
	s_nop 0
	global_load_lds_dwordx4 v[160:161], off
	v_lshl_add_u64 v[160:161], s[26:27], 0, v[130:131]
	s_add_i32 m0, s25, 0x2000
	s_nop 0
	global_load_lds_dwordx4 v[160:161], off
	v_lshl_add_u64 v[160:161], v[234:235], 0, s[28:29]
	s_mov_b32 m0, s63
	s_nop 0
	global_load_lds_dwordx4 v[160:161], off
	v_lshl_add_u64 v[160:161], v[236:237], 0, s[28:29]
	s_mov_b32 m0, s74
	s_nop 0
	global_load_lds_dwordx4 v[160:161], off
	s_waitcnt vmcnt(8)
	s_waitcnt lgkmcnt(0)
	s_barrier
	s_setprio 1
	v_mfma_f32_16x16x32_bf16 v[62:65], v[136:139], v[180:183], v[62:65]
	v_mfma_f32_16x16x32_bf16 v[62:65], v[144:147], v[184:187], v[62:65]
	v_mfma_f32_16x16x32_bf16 v[58:61], v[148:151], v[180:183], v[58:61]
	v_mfma_f32_16x16x32_bf16 v[58:61], v[152:155], v[184:187], v[58:61]
	v_mfma_f32_16x16x32_bf16 v[50:53], v[136:139], v[188:191], v[50:53]
	v_mfma_f32_16x16x32_bf16 v[50:53], v[144:147], v[192:195], v[50:53]
	v_mfma_f32_16x16x32_bf16 v[42:45], v[148:151], v[188:191], v[42:45]
	v_mfma_f32_16x16x32_bf16 v[42:45], v[152:155], v[192:195], v[42:45]
	v_mfma_f32_16x16x32_bf16 v[34:37], v[136:139], v[196:199], v[34:37]
	v_mfma_f32_16x16x32_bf16 v[34:37], v[144:147], v[200:203], v[34:37]
	v_mfma_f32_16x16x32_bf16 v[26:29], v[148:151], v[196:199], v[26:29]
	v_mfma_f32_16x16x32_bf16 v[26:29], v[152:155], v[200:203], v[26:29]
	v_mfma_f32_16x16x32_bf16 v[18:21], v[136:139], v[224:227], v[18:21]
	v_mfma_f32_16x16x32_bf16 v[18:21], v[144:147], v[228:231], v[18:21]
	v_mfma_f32_16x16x32_bf16 v[10:13], v[148:151], v[224:227], v[10:13]
	v_mfma_f32_16x16x32_bf16 v[10:13], v[152:155], v[228:231], v[10:13]
	v_mfma_f32_16x16x32_bf16 v[54:57], v[156:159], v[180:183], v[54:57]
	v_mfma_f32_16x16x32_bf16 v[54:57], v[168:171], v[184:187], v[54:57]
	v_mfma_f32_16x16x32_bf16 v[46:49], v[172:175], v[180:183], v[46:49]
	v_mfma_f32_16x16x32_bf16 v[46:49], v[176:179], v[184:187], v[46:49]
	v_mfma_f32_16x16x32_bf16 v[38:41], v[156:159], v[188:191], v[38:41]
	v_mfma_f32_16x16x32_bf16 v[38:41], v[168:171], v[192:195], v[38:41]
	v_mfma_f32_16x16x32_bf16 v[30:33], v[172:175], v[188:191], v[30:33]
	v_mfma_f32_16x16x32_bf16 v[30:33], v[176:179], v[192:195], v[30:33]
	v_mfma_f32_16x16x32_bf16 v[22:25], v[156:159], v[196:199], v[22:25]
	v_mfma_f32_16x16x32_bf16 v[22:25], v[168:171], v[200:203], v[22:25]
	v_mfma_f32_16x16x32_bf16 v[14:17], v[172:175], v[196:199], v[14:17]
	v_mfma_f32_16x16x32_bf16 v[14:17], v[176:179], v[200:203], v[14:17]
	v_mfma_f32_16x16x32_bf16 v[6:9], v[156:159], v[224:227], v[6:9]
	v_mfma_f32_16x16x32_bf16 v[6:9], v[168:171], v[228:231], v[6:9]
	v_mfma_f32_16x16x32_bf16 v[2:5], v[172:175], v[224:227], v[2:5]
	v_mfma_f32_16x16x32_bf16 v[2:5], v[176:179], v[228:231], v[2:5]
	s_setprio 0
	s_barrier
	s_add_i32 s24, s24, 2
	s_add_u32 s40, s40, 0x100
	s_addc_u32 s41, s41, 0
	s_add_u32 s14, s14, 0x100
	s_addc_u32 s15, s15, 0
	s_cmp_gt_u32 s24, 29
	s_cbranch_scc0 .LBB0_726
	s_and_b64 vcc, exec, s[8:9]
	s_cbranch_vccz .LBB0_729
	s_barrier

; #define PG8_STAGE(bufoff, gbase, voff) do { _Pragma("unroll") for (int _i = 0; _i < 2; ++_i) \
;         __builtin_amdgcn_global_load_lds((const unsigned*)((const char*)(gbase) + (voff)[_i]), (PG8_LAS unsigned*)(lds + (bufoff) + ldsw + _i * 8192), 16, 0, 0); } while (0)
; #define PG8_LDA(dst, b, h) do { _Pragma("unroll") for (int m = 0; m < 4; ++m) _Pragma("unroll") for (int k = 0; k < 2; ++k) dst[m][k] = *(const PG8_LAS bf16x8*)(lds + PG8_SA(b, h) + aoff + m * 2048 + k * 1024); } while (0)
; #define PG8_LDB(dst, b, h) do { _Pragma("unroll") for (int n = 0; n < 2; ++n) _Pragma("unroll") for (int k = 0; k < 2; ++k) dst[n][k] = *(const PG8_LAS bf16x8*)(lds + PG8_SB(b, h) + boff + n * 2048 + k * 1024); } while (0)
; #define PG8_MMA(ai, bj, At, Bt) do { __builtin_amdgcn_s_setprio(1); _Pragma("unroll") for (int m = 0; m < 4; ++m) _Pragma("unroll") for (int n = 0; n < 2; ++n) _Pragma("unroll") for (int k = 0; k < 2; ++k) \
;         acc[ai][bj][m][n] = __builtin_amdgcn_mfma_f32_16x16x32_bf16(Bt[n][k], At[m][k], acc[ai][bj][m][n], 0, 0, 0); __builtin_amdgcn_s_setprio(0); } while (0)
; #define PG8_WAIT_V(n) asm volatile("s_waitcnt vmcnt(" #n ")" ::: "memory")
; #define PG8_WAIT_L(n) asm volatile("s_waitcnt lgkmcnt(" #n ")" ::: "memory")
; template <class Epi, class Sched, bool ALIGN_EPI = false, bool SP2 = false>
; __device__ __forceinline__ void gemm_phase(PG8_LAS unsigned char* lds, const Gemm g, const Sched S, const Epi E) {
;     ...
;             const bool last = (t == nt - 2);
;             const char* a1 = cA + (size_t)(t + 1) * kstep;
;             const char* a2 = last ? nA : cA + (size_t)(t + 2) * kstep; const char* b2 = last ? nB : cB + (size_t)(t + 2) * kstep;
;             const char* a3 = a2 + kstep; const char* b3 = b2 + kstep;
;             if (last && has_next) S.a_ready(nxt);
;             if constexpr (SP2) {
;             PG8_LDB(B0, 0, 0); PG8_LDB(B1, 0, 1); PG8_SCHED; PG8_LDA(At, 0, 0); PG8_STAGE(PG8_SA(1, 1), a1 + hstep, voffA);
;             PG8_WAIT_V(8); PG8_WAIT_L(0); PG8_BAR; PG8_MMA(0, 0, At, B0); PG8_MMA(0, 1, At, B1); PG8_BAR; PG8_SCHED;
;             PG8_LDA(At, 0, 1); PG8_STAGE(PG8_SB(0, 0), b2, voffB); PG8_STAGE(PG8_SB(0, 1), b2 + hstep, voffB); PG8_STAGE(PG8_SA(0, 0), a2, voffA);
;             PG8_WAIT_V(8); PG8_WAIT_L(0); PG8_BAR; PG8_MMA(1, 0, At, B0); PG8_MMA(1, 1, At, B1); PG8_BAR; PG8_SCHED;
.LBB0_922:
	ds_read_b128 v[184:187], v145
	ds_read_b128 v[188:191], v145 offset:1024
	ds_read_b128 v[192:195], v145 offset:2048
	ds_read_b128 v[196:199], v145 offset:3072
	ds_read_b128 v[200:203], v145 offset:4096
	ds_read_b128 v[224:227], v145 offset:5120
	ds_read_b128 v[228:231], v145 offset:6144
	ds_read_b128 v[232:235], v145 offset:7168
	s_add_u32 s25, s56, 0xfffe0080
	s_addc_u32 s26, s57, -1
	s_add_i32 s27, 0, 0x10000
	s_cmp_eq_u32 s24, 4
	s_cselect_b32 s65, s5, s26
	s_cselect_b32 s64, s41, s25
	v_add_u32_e32 v140, s27, v143
	s_cselect_b32 s59, s43, s15
	s_cselect_b32 s58, s75, s14
	s_add_i32 s25, 0, 0x14000
	ds_read_b128 v[146:149], v140
	ds_read_b128 v[150:153], v140 offset:1024
	ds_read_b128 v[154:157], v140 offset:2048
	ds_read_b128 v[158:161], v140 offset:3072
	v_add_u32_e32 v140, s25, v143
	ds_read_b128 v[168:171], v140
	ds_read_b128 v[172:175], v140 offset:1024
	ds_read_b128 v[176:179], v140 offset:2048
	ds_read_b128 v[180:183], v140 offset:3072
	v_lshl_add_u64 v[140:141], s[56:57], 0, v[136:137]
	s_add_i32 m0, s21, 0xc000
	s_nop 0
	global_load_lds_dwordx4 v[140:141], off
	v_lshl_add_u64 v[140:141], s[56:57], 0, v[138:139]
	s_add_i32 m0, s21, 0xe000
	s_nop 0
	global_load_lds_dwordx4 v[140:141], off
	s_waitcnt vmcnt(8)
	s_waitcnt lgkmcnt(0)
	s_barrier
	s_setprio 1
	v_mfma_f32_16x16x32_bf16 v[126:129], v[146:149], v[184:187], v[126:129]
	v_mfma_f32_16x16x32_bf16 v[126:129], v[150:153], v[188:191], v[126:129]
	v_mfma_f32_16x16x32_bf16 v[122:125], v[154:157], v[184:187], v[122:125]
	v_mfma_f32_16x16x32_bf16 v[122:125], v[158:161], v[188:191], v[122:125]
	v_mfma_f32_16x16x32_bf16 v[118:121], v[146:149], v[192:195], v[118:121]
	v_mfma_f32_16x16x32_bf16 v[118:121], v[150:153], v[196:199], v[118:121]
	v_mfma_f32_16x16x32_bf16 v[110:113], v[154:157], v[192:195], v[110:113]
	v_mfma_f32_16x16x32_bf16 v[110:113], v[158:161], v[196:199], v[110:113]
	v_mfma_f32_16x16x32_bf16 v[102:105], v[146:149], v[200:203], v[102:105]
	v_mfma_f32_16x16x32_bf16 v[102:105], v[150:153], v[224:227], v[102:105]
	v_mfma_f32_16x16x32_bf16 v[94:97], v[154:157], v[200:203], v[94:97]
	v_mfma_f32_16x16x32_bf16 v[94:97], v[158:161], v[224:227], v[94:97]
	v_mfma_f32_16x16x32_bf16 v[86:89], v[146:149], v[228:231], v[86:89]
	v_mfma_f32_16x16x32_bf16 v[86:89], v[150:153], v[232:235], v[86:89]
	v_mfma_f32_16x16x32_bf16 v[78:81], v[154:157], v[228:231], v[78:81]
	v_mfma_f32_16x16x32_bf16 v[78:81], v[158:161], v[232:235], v[78:81]
	v_mfma_f32_16x16x32_bf16 v[114:117], v[168:171], v[184:187], v[114:117]
	v_mfma_f32_16x16x32_bf16 v[114:117], v[172:175], v[188:191], v[114:117]
	v_mfma_f32_16x16x32_bf16 v[106:109], v[176:179], v[184:187], v[106:109]
	v_mfma_f32_16x16x32_bf16 v[106:109], v[180:183], v[188:191], v[106:109]
	v_mfma_f32_16x16x32_bf16 v[98:101], v[168:171], v[192:195], v[98:101]
	v_mfma_f32_16x16x32_bf16 v[98:101], v[172:175], v[196:199], v[98:101]
	v_mfma_f32_16x16x32_bf16 v[90:93], v[176:179], v[192:195], v[90:93]
	v_mfma_f32_16x16x32_bf16 v[90:93], v[180:183], v[196:199], v[90:93]
	v_mfma_f32_16x16x32_bf16 v[82:85], v[168:171], v[200:203], v[82:85]
	v_mfma_f32_16x16x32_bf16 v[82:85], v[172:175], v[224:227], v[82:85]
	v_mfma_f32_16x16x32_bf16 v[74:77], v[176:179], v[200:203], v[74:77]
	v_mfma_f32_16x16x32_bf16 v[74:77], v[180:183], v[224:227], v[74:77]
	v_mfma_f32_16x16x32_bf16 v[70:73], v[168:171], v[228:231], v[70:73]
	v_mfma_f32_16x16x32_bf16 v[70:73], v[172:175], v[232:235], v[70:73]
	v_mfma_f32_16x16x32_bf16 v[66:69], v[176:179], v[228:231], v[66:69]
	v_mfma_f32_16x16x32_bf16 v[66:69], v[180:183], v[232:235], v[66:69]
	s_setprio 0
	s_barrier
	ds_read_b128 v[184:187], v145 offset:16384
	ds_read_b128 v[188:191], v145 offset:17408
	ds_read_b128 v[192:195], v145 offset:18432
	ds_read_b128 v[196:199], v145 offset:19456
	ds_read_b128 v[200:203], v145 offset:20480
	ds_read_b128 v[224:227], v145 offset:21504
	ds_read_b128 v[228:231], v145 offset:22528
	ds_read_b128 v[232:235], v145 offset:23552
	s_add_i32 s26, s27, s16
	v_lshl_add_u64 v[140:141], s[58:59], 0, v[0:1]
	s_mov_b32 m0, s26
	s_nop 0
	global_load_lds_dwordx4 v[140:141], off
	s_add_i32 m0, s26, 0x2000
	s_add_u32 s26, s58, 0x20000
	v_lshl_add_u64 v[236:237], s[58:59], 0, v[130:131]
	s_addc_u32 s27, s59, 0
	s_add_i32 s25, s25, s16
	global_load_lds_dwordx4 v[236:237], off
	v_lshl_add_u64 v[238:239], s[26:27], 0, v[0:1]
	s_mov_b32 m0, s25
	v_lshl_add_u64 v[240:241], s[64:65], 0, v[132:133]
	global_load_lds_dwordx4 v[238:239], off
	v_lshl_add_u64 v[238:239], s[26:27], 0, v[130:131]
	s_add_i32 m0, s25, 0x2000
	s_nop 0
	global_load_lds_dwordx4 v[238:239], off
	v_lshl_add_u64 v[238:239], s[64:65], 0, v[134:135]
	s_mov_b32 m0, s21
	s_nop 0
	global_load_lds_dwordx4 v[238:239], off
	s_mov_b32 m0, s22
	s_nop 0
	global_load_lds_dwordx4 v[240:241], off
	s_waitcnt vmcnt(8)
	s_waitcnt lgkmcnt(0)
	s_barrier
; #define PG8_STAGE(bufoff, gbase, voff) do { _Pragma("unroll") for (int _i = 0; _i < 2; ++_i) \
;         __builtin_amdgcn_global_load_lds((const unsigned*)((const char*)(gbase) + (voff)[_i]), (PG8_LAS unsigned*)(lds + (bufoff) + ldsw + _i * 8192), 16, 0, 0); } while (0)
; #define PG8_LDA(dst, b, h) do { _Pragma("unroll") for (int m = 0; m < 4; ++m) _Pragma("unroll") for (int k = 0; k < 2; ++k) dst[m][k] = *(const PG8_LAS bf16x8*)(lds + PG8_SA(b, h) + aoff + m * 2048 + k * 1024); } while (0)
; #define PG8_LDB(dst, b, h) do { _Pragma("unroll") for (int n = 0; n < 2; ++n) _Pragma("unroll") for (int k = 0; k < 2; ++k) dst[n][k] = *(const PG8_LAS bf16x8*)(lds + PG8_SB(b, h) + boff + n * 2048 + k * 1024); } while (0)
; #define PG8_MMA(ai, bj, At, Bt) do { __builtin_amdgcn_s_setprio(1); _Pragma("unroll") for (int m = 0; m < 4; ++m) _Pragma("unroll") for (int n = 0; n < 2; ++n) _Pragma("unroll") for (int k = 0; k < 2; ++k) \
;         acc[ai][bj][m][n] = __builtin_amdgcn_mfma_f32_16x16x32_bf16(Bt[n][k], At[m][k], acc[ai][bj][m][n], 0, 0, 0); __builtin_amdgcn_s_setprio(0); } while (0)
; #define PG8_WAIT_V(n) asm volatile("s_waitcnt vmcnt(" #n ")" ::: "memory")
; #define PG8_WAIT_L(n) asm volatile("s_waitcnt lgkmcnt(" #n ")" ::: "memory")
; #define PG8_BAR __builtin_amdgcn_s_barrier()
; #define PG8_SCHED __builtin_amdgcn_sched_barrier(0)
; template <class Epi, class Sched, bool ALIGN_EPI = false, bool SP2 = false>
; __device__ __forceinline__ void gemm_phase(PG8_LAS unsigned char* lds, const Gemm g, const Sched S, const Epi E) {
;     ...
;             PG8_WAIT_V(8); PG8_WAIT_L(0); PG8_BAR; PG8_MMA(1, 0, At, B0); PG8_MMA(1, 1, At, B1); PG8_BAR; PG8_SCHED;
;             PG8_LDB(B0, 1, 0); PG8_LDB(B1, 1, 1); PG8_SCHED; PG8_LDA(At, 1, 0); PG8_STAGE(PG8_SA(0, 1), a2 + hstep, voffA);
;             PG8_WAIT_V(8); PG8_WAIT_L(0); PG8_BAR; PG8_MMA(0, 0, At, B0); PG8_MMA(0, 1, At, B1); PG8_BAR; PG8_SCHED;
	s_setprio 1
	v_mfma_f32_16x16x32_bf16 v[62:65], v[146:149], v[184:187], v[62:65]
	v_mfma_f32_16x16x32_bf16 v[62:65], v[150:153], v[188:191], v[62:65]
	v_mfma_f32_16x16x32_bf16 v[58:61], v[154:157], v[184:187], v[58:61]
	v_mfma_f32_16x16x32_bf16 v[58:61], v[158:161], v[188:191], v[58:61]
	v_mfma_f32_16x16x32_bf16 v[54:57], v[146:149], v[192:195], v[54:57]
	v_mfma_f32_16x16x32_bf16 v[54:57], v[150:153], v[196:199], v[54:57]
	v_mfma_f32_16x16x32_bf16 v[46:49], v[154:157], v[192:195], v[46:49]
	v_mfma_f32_16x16x32_bf16 v[46:49], v[158:161], v[196:199], v[46:49]
	v_mfma_f32_16x16x32_bf16 v[38:41], v[146:149], v[200:203], v[38:41]
	v_mfma_f32_16x16x32_bf16 v[38:41], v[150:153], v[224:227], v[38:41]
	v_mfma_f32_16x16x32_bf16 v[30:33], v[154:157], v[200:203], v[30:33]
	v_mfma_f32_16x16x32_bf16 v[30:33], v[158:161], v[224:227], v[30:33]
	v_mfma_f32_16x16x32_bf16 v[22:25], v[146:149], v[228:231], v[22:25]
	v_mfma_f32_16x16x32_bf16 v[22:25], v[150:153], v[232:235], v[22:25]
	v_mfma_f32_16x16x32_bf16 v[14:17], v[154:157], v[228:231], v[14:17]
	v_mfma_f32_16x16x32_bf16 v[14:17], v[158:161], v[232:235], v[14:17]
	v_mfma_f32_16x16x32_bf16 v[50:53], v[168:171], v[184:187], v[50:53]
	v_mfma_f32_16x16x32_bf16 v[50:53], v[172:175], v[188:191], v[50:53]
	v_mfma_f32_16x16x32_bf16 v[42:45], v[176:179], v[184:187], v[42:45]
	v_mfma_f32_16x16x32_bf16 v[42:45], v[180:183], v[188:191], v[42:45]
	v_mfma_f32_16x16x32_bf16 v[34:37], v[168:171], v[192:195], v[34:37]
	v_mfma_f32_16x16x32_bf16 v[34:37], v[172:175], v[196:199], v[34:37]
	v_mfma_f32_16x16x32_bf16 v[26:29], v[176:179], v[192:195], v[26:29]
	v_mfma_f32_16x16x32_bf16 v[26:29], v[180:183], v[196:199], v[26:29]
	v_mfma_f32_16x16x32_bf16 v[18:21], v[168:171], v[200:203], v[18:21]
	v_mfma_f32_16x16x32_bf16 v[18:21], v[172:175], v[224:227], v[18:21]
	v_mfma_f32_16x16x32_bf16 v[10:13], v[176:179], v[200:203], v[10:13]
	v_mfma_f32_16x16x32_bf16 v[10:13], v[180:183], v[224:227], v[10:13]
	v_mfma_f32_16x16x32_bf16 v[6:9], v[168:171], v[228:231], v[6:9]
	v_mfma_f32_16x16x32_bf16 v[6:9], v[172:175], v[232:235], v[6:9]
	v_mfma_f32_16x16x32_bf16 v[2:5], v[176:179], v[228:231], v[2:5]
	v_mfma_f32_16x16x32_bf16 v[2:5], v[180:183], v[232:235], v[2:5]
	s_setprio 0
	s_barrier
	ds_read_b128 v[184:187], v145 offset:32768
	ds_read_b128 v[188:191], v145 offset:33792
	ds_read_b128 v[192:195], v145 offset:34816
	ds_read_b128 v[196:199], v145 offset:35840
	ds_read_b128 v[200:203], v145 offset:36864
	ds_read_b128 v[224:227], v145 offset:37888
	ds_read_b128 v[228:231], v145 offset:38912
	ds_read_b128 v[232:235], v145 offset:39936
	s_add_i32 s25, 0, 0x18000
	s_add_i32 s30, 0, 0x1c000
	v_add_u32_e32 v158, s25, v143
	v_add_u32_e32 v167, s30, v143
	ds_read_b128 v[146:149], v158
	ds_read_b128 v[150:153], v158 offset:1024
	ds_read_b128 v[154:157], v158 offset:2048
	ds_read_b128 v[158:161], v158 offset:3072
	ds_read_b128 v[168:171], v167
	ds_read_b128 v[172:175], v167 offset:1024
	ds_read_b128 v[176:179], v167 offset:2048
	ds_read_b128 v[180:183], v167 offset:3072
	s_add_u32 s26, s64, 0x20000
	s_addc_u32 s27, s65, 0
	s_mov_b32 m0, s47
	v_lshl_add_u64 v[242:243], s[26:27], 0, v[134:135]
	global_load_lds_dwordx4 v[242:243], off
	v_lshl_add_u64 v[242:243], s[26:27], 0, v[132:133]
	s_mov_b32 m0, s62
	s_nop 0
	global_load_lds_dwordx4 v[242:243], off
	s_waitcnt vmcnt(8)
	s_waitcnt lgkmcnt(0)
	s_barrier
	s_setprio 1
	v_mfma_f32_16x16x32_bf16 v[126:129], v[146:149], v[184:187], v[126:129]
	v_mfma_f32_16x16x32_bf16 v[126:129], v[150:153], v[188:191], v[126:129]
	v_mfma_f32_16x16x32_bf16 v[122:125], v[154:157], v[184:187], v[122:125]
	v_mfma_f32_16x16x32_bf16 v[122:125], v[158:161], v[188:191], v[122:125]
	v_mfma_f32_16x16x32_bf16 v[118:121], v[146:149], v[192:195], v[118:121]
	v_mfma_f32_16x16x32_bf16 v[118:121], v[150:153], v[196:199], v[118:121]
	v_mfma_f32_16x16x32_bf16 v[110:113], v[154:157], v[192:195], v[110:113]
	v_mfma_f32_16x16x32_bf16 v[110:113], v[158:161], v[196:199], v[110:113]
	v_mfma_f32_16x16x32_bf16 v[102:105], v[146:149], v[200:203], v[102:105]
	v_mfma_f32_16x16x32_bf16 v[102:105], v[150:153], v[224:227], v[102:105]
	v_mfma_f32_16x16x32_bf16 v[94:97], v[154:157], v[200:203], v[94:97]
	v_mfma_f32_16x16x32_bf16 v[94:97], v[158:161], v[224:227], v[94:97]
	v_mfma_f32_16x16x32_bf16 v[86:89], v[146:149], v[228:231], v[86:89]
	v_mfma_f32_16x16x32_bf16 v[86:89], v[150:153], v[232:235], v[86:89]
	v_mfma_f32_16x16x32_bf16 v[78:81], v[154:157], v[228:231], v[78:81]
	v_mfma_f32_16x16x32_bf16 v[78:81], v[158:161], v[232:235], v[78:81]
	v_mfma_f32_16x16x32_bf16 v[114:117], v[168:171], v[184:187], v[114:117]
	v_mfma_f32_16x16x32_bf16 v[114:117], v[172:175], v[188:191], v[114:117]
	v_mfma_f32_16x16x32_bf16 v[106:109], v[176:179], v[184:187], v[106:109]
	v_mfma_f32_16x16x32_bf16 v[106:109], v[180:183], v[188:191], v[106:109]
	v_mfma_f32_16x16x32_bf16 v[98:101], v[168:171], v[192:195], v[98:101]
	v_mfma_f32_16x16x32_bf16 v[98:101], v[172:175], v[196:199], v[98:101]
	v_mfma_f32_16x16x32_bf16 v[90:93], v[176:179], v[192:195], v[90:93]
	v_mfma_f32_16x16x32_bf16 v[90:93], v[180:183], v[196:199], v[90:93]
	v_mfma_f32_16x16x32_bf16 v[82:85], v[168:171], v[200:203], v[82:85]
	v_mfma_f32_16x16x32_bf16 v[82:85], v[172:175], v[224:227], v[82:85]
	v_mfma_f32_16x16x32_bf16 v[74:77], v[176:179], v[200:203], v[74:77]
	v_mfma_f32_16x16x32_bf16 v[74:77], v[180:183], v[224:227], v[74:77]
	v_mfma_f32_16x16x32_bf16 v[70:73], v[168:171], v[228:231], v[70:73]
	v_mfma_f32_16x16x32_bf16 v[70:73], v[172:175], v[232:235], v[70:73]
	v_mfma_f32_16x16x32_bf16 v[66:69], v[176:179], v[228:231], v[66:69]
	v_mfma_f32_16x16x32_bf16 v[66:69], v[180:183], v[232:235], v[66:69]
	s_setprio 0
	s_barrier
; #define PG8_STAGE(bufoff, gbase, voff) do { _Pragma("unroll") for (int _i = 0; _i < 2; ++_i) \
;         __builtin_amdgcn_global_load_lds((const unsigned*)((const char*)(gbase) + (voff)[_i]), (PG8_LAS unsigned*)(lds + (bufoff) + ldsw + _i * 8192), 16, 0, 0); } while (0)
; #define PG8_LDA(dst, b, h) do { _Pragma("unroll") for (int m = 0; m < 4; ++m) _Pragma("unroll") for (int k = 0; k < 2; ++k) dst[m][k] = *(const PG8_LAS bf16x8*)(lds + PG8_SA(b, h) + aoff + m * 2048 + k * 1024); } while (0)
; #define PG8_MMA(ai, bj, At, Bt) do { __builtin_amdgcn_s_setprio(1); _Pragma("unroll") for (int m = 0; m < 4; ++m) _Pragma("unroll") for (int n = 0; n < 2; ++n) _Pragma("unroll") for (int k = 0; k < 2; ++k) \
;         acc[ai][bj][m][n] = __builtin_amdgcn_mfma_f32_16x16x32_bf16(Bt[n][k], At[m][k], acc[ai][bj][m][n], 0, 0, 0); __builtin_amdgcn_s_setprio(0); } while (0)
; #define PG8_WAIT_V(n) asm volatile("s_waitcnt vmcnt(" #n ")" ::: "memory")
; #define PG8_WAIT_L(n) asm volatile("s_waitcnt lgkmcnt(" #n ")" ::: "memory")
; #define PG8_BAR __builtin_amdgcn_s_barrier()
; #define PG8_SCHED __builtin_amdgcn_sched_barrier(0)
; template <class Epi, class Sched, bool ALIGN_EPI = false, bool SP2 = false>
; __device__ __forceinline__ void gemm_phase(PG8_LAS unsigned char* lds, const Gemm g, const Sched S, const Epi E) {
;     ...
;             PG8_LDA(At, 1, 1); PG8_STAGE(PG8_SB(1, 0), b3, voffB); PG8_STAGE(PG8_SB(1, 1), b3 + hstep, voffB); PG8_STAGE(PG8_SA(1, 0), a3, voffA);
;             PG8_WAIT_V(8); PG8_WAIT_L(0); PG8_BAR; PG8_MMA(1, 0, At, B0); PG8_MMA(1, 1, At, B1); PG8_BAR; PG8_SCHED;
;     ...
;         if constexpr (ALIGN_EPI) { if (wr == 0) PG8_BAR; }
	ds_read_b128 v[184:187], v145 offset:49152
	ds_read_b128 v[188:191], v145 offset:50176
	ds_read_b128 v[192:195], v145 offset:51200
	ds_read_b128 v[196:199], v145 offset:52224
	ds_read_b128 v[200:203], v145 offset:53248
	ds_read_b128 v[224:227], v145 offset:54272
	ds_read_b128 v[228:231], v145 offset:55296
	ds_read_b128 v[232:235], v145 offset:56320
	s_add_i32 s25, s25, s16
	v_lshl_add_u64 v[140:141], v[140:141], 0, s[28:29]
	s_mov_b32 m0, s25
	s_nop 0
	global_load_lds_dwordx4 v[140:141], off
	s_add_i32 m0, s25, 0x2000
	s_add_u32 s26, s58, 0x20080
	v_lshl_add_u64 v[140:141], v[236:237], 0, s[28:29]
	s_addc_u32 s27, s59, 0
	s_add_i32 s25, s30, s16
	global_load_lds_dwordx4 v[140:141], off
	v_lshl_add_u64 v[140:141], s[26:27], 0, v[0:1]
	s_mov_b32 m0, s25
	s_nop 0
	global_load_lds_dwordx4 v[140:141], off
	v_lshl_add_u64 v[140:141], s[26:27], 0, v[130:131]
	s_add_i32 m0, s25, 0x2000
	s_nop 0
	global_load_lds_dwordx4 v[140:141], off
	v_lshl_add_u64 v[140:141], v[238:239], 0, s[28:29]
	s_mov_b32 m0, s63
	s_nop 0
	global_load_lds_dwordx4 v[140:141], off
	v_lshl_add_u64 v[140:141], v[240:241], 0, s[28:29]
	s_mov_b32 m0, s66
	s_nop 0
	global_load_lds_dwordx4 v[140:141], off
	s_waitcnt vmcnt(8)
	s_waitcnt lgkmcnt(0)
	s_barrier
	s_setprio 1
	v_mfma_f32_16x16x32_bf16 v[62:65], v[146:149], v[184:187], v[62:65]
	v_mfma_f32_16x16x32_bf16 v[62:65], v[150:153], v[188:191], v[62:65]
	v_mfma_f32_16x16x32_bf16 v[58:61], v[154:157], v[184:187], v[58:61]
	v_mfma_f32_16x16x32_bf16 v[58:61], v[158:161], v[188:191], v[58:61]
	v_mfma_f32_16x16x32_bf16 v[54:57], v[146:149], v[192:195], v[54:57]
	v_mfma_f32_16x16x32_bf16 v[54:57], v[150:153], v[196:199], v[54:57]
	v_mfma_f32_16x16x32_bf16 v[46:49], v[154:157], v[192:195], v[46:49]
	v_mfma_f32_16x16x32_bf16 v[46:49], v[158:161], v[196:199], v[46:49]
	v_mfma_f32_16x16x32_bf16 v[38:41], v[146:149], v[200:203], v[38:41]
	v_mfma_f32_16x16x32_bf16 v[38:41], v[150:153], v[224:227], v[38:41]
	v_mfma_f32_16x16x32_bf16 v[30:33], v[154:157], v[200:203], v[30:33]
	v_mfma_f32_16x16x32_bf16 v[30:33], v[158:161], v[224:227], v[30:33]
	v_mfma_f32_16x16x32_bf16 v[22:25], v[146:149], v[228:231], v[22:25]
	v_mfma_f32_16x16x32_bf16 v[22:25], v[150:153], v[232:235], v[22:25]
	v_mfma_f32_16x16x32_bf16 v[14:17], v[154:157], v[228:231], v[14:17]
	v_mfma_f32_16x16x32_bf16 v[14:17], v[158:161], v[232:235], v[14:17]
	v_mfma_f32_16x16x32_bf16 v[50:53], v[168:171], v[184:187], v[50:53]
	v_mfma_f32_16x16x32_bf16 v[50:53], v[172:175], v[188:191], v[50:53]
	v_mfma_f32_16x16x32_bf16 v[42:45], v[176:179], v[184:187], v[42:45]
	v_mfma_f32_16x16x32_bf16 v[42:45], v[180:183], v[188:191], v[42:45]
	v_mfma_f32_16x16x32_bf16 v[34:37], v[168:171], v[192:195], v[34:37]
	v_mfma_f32_16x16x32_bf16 v[34:37], v[172:175], v[196:199], v[34:37]
	v_mfma_f32_16x16x32_bf16 v[26:29], v[176:179], v[192:195], v[26:29]
	v_mfma_f32_16x16x32_bf16 v[26:29], v[180:183], v[196:199], v[26:29]
	v_mfma_f32_16x16x32_bf16 v[18:21], v[168:171], v[200:203], v[18:21]
	v_mfma_f32_16x16x32_bf16 v[18:21], v[172:175], v[224:227], v[18:21]
	v_mfma_f32_16x16x32_bf16 v[10:13], v[176:179], v[200:203], v[10:13]
	v_mfma_f32_16x16x32_bf16 v[10:13], v[180:183], v[224:227], v[10:13]
	v_mfma_f32_16x16x32_bf16 v[6:9], v[168:171], v[228:231], v[6:9]
	v_mfma_f32_16x16x32_bf16 v[6:9], v[172:175], v[232:235], v[6:9]
	v_mfma_f32_16x16x32_bf16 v[2:5], v[176:179], v[228:231], v[2:5]
	v_mfma_f32_16x16x32_bf16 v[2:5], v[180:183], v[232:235], v[2:5]
	s_setprio 0
	s_barrier
	s_add_i32 s24, s24, 2
	s_add_u32 s56, s56, 0x100
	s_addc_u32 s57, s57, 0
	s_add_u32 s14, s14, 0x100
	s_addc_u32 s15, s15, 0
	s_cmp_gt_u32 s24, 5
	s_cbranch_scc0 .LBB0_922
	s_and_b64 vcc, exec, s[38:39]
	s_cbranch_vccz .LBB0_925
	s_barrier

; #define PG8_STAGE(bufoff, gbase, voff) do { _Pragma("unroll") for (int _i = 0; _i < 2; ++_i) \
;         __builtin_amdgcn_global_load_lds((const unsigned*)((const char*)(gbase) + (voff)[_i]), (PG8_LAS unsigned*)(lds + (bufoff) + ldsw + _i * 8192), 16, 0, 0); } while (0)
; #define PG8_LDA(dst, b, h) do { _Pragma("unroll") for (int m = 0; m < 4; ++m) _Pragma("unroll") for (int k = 0; k < 2; ++k) dst[m][k] = *(const PG8_LAS bf16x8*)(lds + PG8_SA(b, h) + aoff + m * 2048 + k * 1024); } while (0)
; #define PG8_LDB(dst, b, h) do { _Pragma("unroll") for (int n = 0; n < 2; ++n) _Pragma("unroll") for (int k = 0; k < 2; ++k) dst[n][k] = *(const PG8_LAS bf16x8*)(lds + PG8_SB(b, h) + boff + n * 2048 + k * 1024); } while (0)
; #define PG8_MMA(ai, bj, At, Bt) do { __builtin_amdgcn_s_setprio(1); _Pragma("unroll") for (int m = 0; m < 4; ++m) _Pragma("unroll") for (int n = 0; n < 2; ++n) _Pragma("unroll") for (int k = 0; k < 2; ++k) \
;         acc[ai][bj][m][n] = __builtin_amdgcn_mfma_f32_16x16x32_bf16(Bt[n][k], At[m][k], acc[ai][bj][m][n], 0, 0, 0); __builtin_amdgcn_s_setprio(0); } while (0)
; #define PG8_WAIT_V(n) asm volatile("s_waitcnt vmcnt(" #n ")" ::: "memory")
; #define PG8_WAIT_L(n) asm volatile("s_waitcnt lgkmcnt(" #n ")" ::: "memory")
; template <class Epi, class Sched, bool ALIGN_EPI = false, bool SP2 = false>
; __device__ __forceinline__ void gemm_phase(PG8_LAS unsigned char* lds, const Gemm g, const Sched S, const Epi E) {
;     ...
;             const bool last = (t == nt - 2);
;             const char* a1 = cA + (size_t)(t + 1) * kstep;
;             const char* a2 = last ? nA : cA + (size_t)(t + 2) * kstep; const char* b2 = last ? nB : cB + (size_t)(t + 2) * kstep;
;             const char* a3 = a2 + kstep; const char* b3 = b2 + kstep;
;             if (last && has_next) S.a_ready(nxt);
;             if constexpr (SP2) {
;             PG8_LDB(B0, 0, 0); PG8_LDB(B1, 0, 1); PG8_SCHED; PG8_LDA(At, 0, 0); PG8_STAGE(PG8_SA(1, 1), a1 + hstep, voffA);
;             PG8_WAIT_V(8); PG8_WAIT_L(0); PG8_BAR; PG8_MMA(0, 0, At, B0); PG8_MMA(0, 1, At, B1); PG8_BAR; PG8_SCHED;
;             PG8_LDA(At, 0, 1); PG8_STAGE(PG8_SB(0, 0), b2, voffB); PG8_STAGE(PG8_SB(0, 1), b2 + hstep, voffB); PG8_STAGE(PG8_SA(0, 0), a2, voffA);
;             PG8_WAIT_V(8); PG8_WAIT_L(0); PG8_BAR; PG8_MMA(1, 0, At, B0); PG8_MMA(1, 1, At, B1); PG8_BAR; PG8_SCHED;
.LBB0_2074:
	ds_read_b128 v[180:183], v145
	ds_read_b128 v[184:187], v145 offset:1024
	ds_read_b128 v[188:191], v145 offset:2048
	ds_read_b128 v[192:195], v145 offset:3072
	ds_read_b128 v[196:199], v145 offset:4096
	ds_read_b128 v[200:203], v145 offset:5120
	ds_read_b128 v[224:227], v145 offset:6144
	ds_read_b128 v[228:231], v145 offset:7168
	s_add_u32 s56, s52, 0x100
	s_addc_u32 s57, s53, 0
	s_add_i32 s25, 0, 0x10000
	s_cmp_eq_u32 s24, 28
	s_cselect_b32 s65, s43, s57
	s_cselect_b32 s64, s74, s56
	v_add_u32_e32 v140, s25, v143
	s_cselect_b32 s59, s41, s15
	s_cselect_b32 s58, s75, s14
	s_add_i32 s30, 0, 0x14000
	ds_read_b128 v[136:139], v140
	ds_read_b128 v[146:149], v140 offset:1024
	ds_read_b128 v[150:153], v140 offset:2048
	ds_read_b128 v[154:157], v140 offset:3072
	v_add_u32_e32 v140, s30, v143
	ds_read_b128 v[158:161], v140
	ds_read_b128 v[168:171], v140 offset:1024
	ds_read_b128 v[172:175], v140 offset:2048
	ds_read_b128 v[176:179], v140 offset:3072
	v_lshl_add_u64 v[140:141], s[52:53], 0, v[132:133]
	s_add_i32 m0, s21, 0xc000
	s_nop 0
	global_load_lds_dwordx4 v[140:141], off
	v_lshl_add_u64 v[140:141], s[52:53], 0, v[134:135]
	s_add_i32 m0, s21, 0xe000
	s_nop 0
	global_load_lds_dwordx4 v[140:141], off
	s_waitcnt vmcnt(8)
	s_waitcnt lgkmcnt(0)
	s_barrier
	s_setprio 1
	v_mfma_f32_16x16x32_bf16 v[126:129], v[136:139], v[180:183], v[126:129]
	v_mfma_f32_16x16x32_bf16 v[126:129], v[146:149], v[184:187], v[126:129]
	v_mfma_f32_16x16x32_bf16 v[122:125], v[150:153], v[180:183], v[122:125]
	v_mfma_f32_16x16x32_bf16 v[122:125], v[154:157], v[184:187], v[122:125]
	v_mfma_f32_16x16x32_bf16 v[110:113], v[136:139], v[188:191], v[110:113]
	v_mfma_f32_16x16x32_bf16 v[110:113], v[146:149], v[192:195], v[110:113]
	v_mfma_f32_16x16x32_bf16 v[106:109], v[150:153], v[188:191], v[106:109]
	v_mfma_f32_16x16x32_bf16 v[106:109], v[154:157], v[192:195], v[106:109]
	v_mfma_f32_16x16x32_bf16 v[94:97], v[136:139], v[196:199], v[94:97]
	v_mfma_f32_16x16x32_bf16 v[94:97], v[146:149], v[200:203], v[94:97]
	v_mfma_f32_16x16x32_bf16 v[90:93], v[150:153], v[196:199], v[90:93]
	v_mfma_f32_16x16x32_bf16 v[90:93], v[154:157], v[200:203], v[90:93]
	v_mfma_f32_16x16x32_bf16 v[78:81], v[136:139], v[224:227], v[78:81]
	v_mfma_f32_16x16x32_bf16 v[78:81], v[146:149], v[228:231], v[78:81]
	v_mfma_f32_16x16x32_bf16 v[74:77], v[150:153], v[224:227], v[74:77]
	v_mfma_f32_16x16x32_bf16 v[74:77], v[154:157], v[228:231], v[74:77]
	v_mfma_f32_16x16x32_bf16 v[118:121], v[158:161], v[180:183], v[118:121]
	v_mfma_f32_16x16x32_bf16 v[118:121], v[168:171], v[184:187], v[118:121]
	v_mfma_f32_16x16x32_bf16 v[114:117], v[172:175], v[180:183], v[114:117]
	v_mfma_f32_16x16x32_bf16 v[114:117], v[176:179], v[184:187], v[114:117]
	v_mfma_f32_16x16x32_bf16 v[102:105], v[158:161], v[188:191], v[102:105]
	v_mfma_f32_16x16x32_bf16 v[102:105], v[168:171], v[192:195], v[102:105]
	v_mfma_f32_16x16x32_bf16 v[98:101], v[172:175], v[188:191], v[98:101]
	v_mfma_f32_16x16x32_bf16 v[98:101], v[176:179], v[192:195], v[98:101]
	v_mfma_f32_16x16x32_bf16 v[86:89], v[158:161], v[196:199], v[86:89]
	v_mfma_f32_16x16x32_bf16 v[86:89], v[168:171], v[200:203], v[86:89]
	v_mfma_f32_16x16x32_bf16 v[82:85], v[172:175], v[196:199], v[82:85]
	v_mfma_f32_16x16x32_bf16 v[82:85], v[176:179], v[200:203], v[82:85]
	v_mfma_f32_16x16x32_bf16 v[70:73], v[158:161], v[224:227], v[70:73]
	v_mfma_f32_16x16x32_bf16 v[70:73], v[168:171], v[228:231], v[70:73]
	v_mfma_f32_16x16x32_bf16 v[66:69], v[172:175], v[224:227], v[66:69]
	v_mfma_f32_16x16x32_bf16 v[66:69], v[176:179], v[228:231], v[66:69]
	s_setprio 0
	s_barrier
	ds_read_b128 v[180:183], v145 offset:16384
	ds_read_b128 v[184:187], v145 offset:17408
	ds_read_b128 v[188:191], v145 offset:18432
	ds_read_b128 v[192:195], v145 offset:19456
	ds_read_b128 v[196:199], v145 offset:20480
	ds_read_b128 v[200:203], v145 offset:21504
	ds_read_b128 v[224:227], v145 offset:22528
	ds_read_b128 v[228:231], v145 offset:23552
	s_add_i32 s25, s25, s16
	v_lshl_add_u64 v[140:141], s[58:59], 0, v[0:1]
	s_mov_b32 m0, s25
	s_nop 0
	global_load_lds_dwordx4 v[140:141], off
	s_add_i32 m0, s25, 0x2000
	s_add_u32 s26, s58, 0x80000
	v_lshl_add_u64 v[232:233], s[58:59], 0, v[130:131]
	s_addc_u32 s27, s59, 0
	s_add_i32 s25, s30, s16
	global_load_lds_dwordx4 v[232:233], off
	v_lshl_add_u64 v[234:235], s[26:27], 0, v[0:1]
	s_mov_b32 m0, s25
	v_lshl_add_u64 v[236:237], s[64:65], 0, v[130:131]
	global_load_lds_dwordx4 v[234:235], off
	v_lshl_add_u64 v[234:235], s[26:27], 0, v[130:131]
	s_add_i32 m0, s25, 0x2000
	s_nop 0
	global_load_lds_dwordx4 v[234:235], off
	v_lshl_add_u64 v[234:235], s[64:65], 0, v[0:1]
	s_mov_b32 m0, s21
	s_nop 0
	global_load_lds_dwordx4 v[234:235], off
	s_mov_b32 m0, s22
	s_nop 0
	global_load_lds_dwordx4 v[236:237], off
	s_waitcnt vmcnt(8)
	s_waitcnt lgkmcnt(0)
	s_barrier
; #define PG8_STAGE(bufoff, gbase, voff) do { _Pragma("unroll") for (int _i = 0; _i < 2; ++_i) \
;         __builtin_amdgcn_global_load_lds((const unsigned*)((const char*)(gbase) + (voff)[_i]), (PG8_LAS unsigned*)(lds + (bufoff) + ldsw + _i * 8192), 16, 0, 0); } while (0)
; #define PG8_LDA(dst, b, h) do { _Pragma("unroll") for (int m = 0; m < 4; ++m) _Pragma("unroll") for (int k = 0; k < 2; ++k) dst[m][k] = *(const PG8_LAS bf16x8*)(lds + PG8_SA(b, h) + aoff + m * 2048 + k * 1024); } while (0)
; #define PG8_LDB(dst, b, h) do { _Pragma("unroll") for (int n = 0; n < 2; ++n) _Pragma("unroll") for (int k = 0; k < 2; ++k) dst[n][k] = *(const PG8_LAS bf16x8*)(lds + PG8_SB(b, h) + boff + n * 2048 + k * 1024); } while (0)
; #define PG8_MMA(ai, bj, At, Bt) do { __builtin_amdgcn_s_setprio(1); _Pragma("unroll") for (int m = 0; m < 4; ++m) _Pragma("unroll") for (int n = 0; n < 2; ++n) _Pragma("unroll") for (int k = 0; k < 2; ++k) \
;         acc[ai][bj][m][n] = __builtin_amdgcn_mfma_f32_16x16x32_bf16(Bt[n][k], At[m][k], acc[ai][bj][m][n], 0, 0, 0); __builtin_amdgcn_s_setprio(0); } while (0)
; #define PG8_WAIT_V(n) asm volatile("s_waitcnt vmcnt(" #n ")" ::: "memory")
; #define PG8_WAIT_L(n) asm volatile("s_waitcnt lgkmcnt(" #n ")" ::: "memory")
; #define PG8_BAR __builtin_amdgcn_s_barrier()
; #define PG8_SCHED __builtin_amdgcn_sched_barrier(0)
; template <class Epi, class Sched, bool ALIGN_EPI = false, bool SP2 = false>
; __device__ __forceinline__ void gemm_phase(PG8_LAS unsigned char* lds, const Gemm g, const Sched S, const Epi E) {
;     ...
;             PG8_WAIT_V(8); PG8_WAIT_L(0); PG8_BAR; PG8_MMA(1, 0, At, B0); PG8_MMA(1, 1, At, B1); PG8_BAR; PG8_SCHED;
;             PG8_LDB(B0, 1, 0); PG8_LDB(B1, 1, 1); PG8_SCHED; PG8_LDA(At, 1, 0); PG8_STAGE(PG8_SA(0, 1), a2 + hstep, voffA);
;             PG8_WAIT_V(8); PG8_WAIT_L(0); PG8_BAR; PG8_MMA(0, 0, At, B0); PG8_MMA(0, 1, At, B1); PG8_BAR; PG8_SCHED;
	s_setprio 1
	v_mfma_f32_16x16x32_bf16 v[62:65], v[136:139], v[180:183], v[62:65]
	v_mfma_f32_16x16x32_bf16 v[62:65], v[146:149], v[184:187], v[62:65]
	v_mfma_f32_16x16x32_bf16 v[58:61], v[150:153], v[180:183], v[58:61]
	v_mfma_f32_16x16x32_bf16 v[58:61], v[154:157], v[184:187], v[58:61]
	v_mfma_f32_16x16x32_bf16 v[46:49], v[136:139], v[188:191], v[46:49]
	v_mfma_f32_16x16x32_bf16 v[46:49], v[146:149], v[192:195], v[46:49]
	v_mfma_f32_16x16x32_bf16 v[42:45], v[150:153], v[188:191], v[42:45]
	v_mfma_f32_16x16x32_bf16 v[42:45], v[154:157], v[192:195], v[42:45]
	v_mfma_f32_16x16x32_bf16 v[30:33], v[136:139], v[196:199], v[30:33]
	v_mfma_f32_16x16x32_bf16 v[30:33], v[146:149], v[200:203], v[30:33]
	v_mfma_f32_16x16x32_bf16 v[26:29], v[150:153], v[196:199], v[26:29]
	v_mfma_f32_16x16x32_bf16 v[26:29], v[154:157], v[200:203], v[26:29]
	v_mfma_f32_16x16x32_bf16 v[14:17], v[136:139], v[224:227], v[14:17]
	v_mfma_f32_16x16x32_bf16 v[14:17], v[146:149], v[228:231], v[14:17]
	v_mfma_f32_16x16x32_bf16 v[10:13], v[150:153], v[224:227], v[10:13]
	v_mfma_f32_16x16x32_bf16 v[10:13], v[154:157], v[228:231], v[10:13]
	v_mfma_f32_16x16x32_bf16 v[54:57], v[158:161], v[180:183], v[54:57]
	v_mfma_f32_16x16x32_bf16 v[54:57], v[168:171], v[184:187], v[54:57]
	v_mfma_f32_16x16x32_bf16 v[50:53], v[172:175], v[180:183], v[50:53]
	v_mfma_f32_16x16x32_bf16 v[50:53], v[176:179], v[184:187], v[50:53]
	v_mfma_f32_16x16x32_bf16 v[38:41], v[158:161], v[188:191], v[38:41]
	v_mfma_f32_16x16x32_bf16 v[38:41], v[168:171], v[192:195], v[38:41]
	v_mfma_f32_16x16x32_bf16 v[34:37], v[172:175], v[188:191], v[34:37]
	v_mfma_f32_16x16x32_bf16 v[34:37], v[176:179], v[192:195], v[34:37]
	v_mfma_f32_16x16x32_bf16 v[22:25], v[158:161], v[196:199], v[22:25]
	v_mfma_f32_16x16x32_bf16 v[22:25], v[168:171], v[200:203], v[22:25]
	v_mfma_f32_16x16x32_bf16 v[18:21], v[172:175], v[196:199], v[18:21]
	v_mfma_f32_16x16x32_bf16 v[18:21], v[176:179], v[200:203], v[18:21]
	v_mfma_f32_16x16x32_bf16 v[6:9], v[158:161], v[224:227], v[6:9]
	v_mfma_f32_16x16x32_bf16 v[6:9], v[168:171], v[228:231], v[6:9]
	v_mfma_f32_16x16x32_bf16 v[2:5], v[172:175], v[224:227], v[2:5]
	v_mfma_f32_16x16x32_bf16 v[2:5], v[176:179], v[228:231], v[2:5]
	s_setprio 0
	s_barrier
	ds_read_b128 v[180:183], v145 offset:32768
	ds_read_b128 v[184:187], v145 offset:33792
	ds_read_b128 v[188:191], v145 offset:34816
	ds_read_b128 v[192:195], v145 offset:35840
	ds_read_b128 v[196:199], v145 offset:36864
	ds_read_b128 v[200:203], v145 offset:37888
	ds_read_b128 v[224:227], v145 offset:38912
	ds_read_b128 v[228:231], v145 offset:39936
	s_add_i32 s25, 0, 0x18000
	s_add_i32 s30, 0, 0x1c000
	v_add_u32_e32 v154, s25, v143
	v_add_u32_e32 v167, s30, v143
	ds_read_b128 v[136:139], v154
	ds_read_b128 v[146:149], v154 offset:1024
	ds_read_b128 v[150:153], v154 offset:2048
	ds_read_b128 v[154:157], v154 offset:3072
	ds_read_b128 v[158:161], v167
	ds_read_b128 v[168:171], v167 offset:1024
	ds_read_b128 v[172:175], v167 offset:2048
	ds_read_b128 v[176:179], v167 offset:3072
	s_add_u32 s26, s64, 0x80000
	s_addc_u32 s27, s65, 0
	s_mov_b32 m0, s47
	v_lshl_add_u64 v[238:239], s[26:27], 0, v[0:1]
	global_load_lds_dwordx4 v[238:239], off
	v_lshl_add_u64 v[238:239], s[26:27], 0, v[130:131]
	s_mov_b32 m0, s62
	s_nop 0
	global_load_lds_dwordx4 v[238:239], off
	s_waitcnt vmcnt(8)
	s_waitcnt lgkmcnt(0)
	s_barrier
	s_setprio 1
	v_mfma_f32_16x16x32_bf16 v[126:129], v[136:139], v[180:183], v[126:129]
	v_mfma_f32_16x16x32_bf16 v[126:129], v[146:149], v[184:187], v[126:129]
	v_mfma_f32_16x16x32_bf16 v[122:125], v[150:153], v[180:183], v[122:125]
	v_mfma_f32_16x16x32_bf16 v[122:125], v[154:157], v[184:187], v[122:125]
	v_mfma_f32_16x16x32_bf16 v[110:113], v[136:139], v[188:191], v[110:113]
	v_mfma_f32_16x16x32_bf16 v[110:113], v[146:149], v[192:195], v[110:113]
	v_mfma_f32_16x16x32_bf16 v[106:109], v[150:153], v[188:191], v[106:109]
	v_mfma_f32_16x16x32_bf16 v[106:109], v[154:157], v[192:195], v[106:109]
	v_mfma_f32_16x16x32_bf16 v[94:97], v[136:139], v[196:199], v[94:97]
	v_mfma_f32_16x16x32_bf16 v[94:97], v[146:149], v[200:203], v[94:97]
	v_mfma_f32_16x16x32_bf16 v[90:93], v[150:153], v[196:199], v[90:93]
	v_mfma_f32_16x16x32_bf16 v[90:93], v[154:157], v[200:203], v[90:93]
	v_mfma_f32_16x16x32_bf16 v[78:81], v[136:139], v[224:227], v[78:81]
	v_mfma_f32_16x16x32_bf16 v[78:81], v[146:149], v[228:231], v[78:81]
	v_mfma_f32_16x16x32_bf16 v[74:77], v[150:153], v[224:227], v[74:77]
	v_mfma_f32_16x16x32_bf16 v[74:77], v[154:157], v[228:231], v[74:77]
	v_mfma_f32_16x16x32_bf16 v[118:121], v[158:161], v[180:183], v[118:121]
	v_mfma_f32_16x16x32_bf16 v[118:121], v[168:171], v[184:187], v[118:121]
	v_mfma_f32_16x16x32_bf16 v[114:117], v[172:175], v[180:183], v[114:117]
	v_mfma_f32_16x16x32_bf16 v[114:117], v[176:179], v[184:187], v[114:117]
	v_mfma_f32_16x16x32_bf16 v[102:105], v[158:161], v[188:191], v[102:105]
	v_mfma_f32_16x16x32_bf16 v[102:105], v[168:171], v[192:195], v[102:105]
	v_mfma_f32_16x16x32_bf16 v[98:101], v[172:175], v[188:191], v[98:101]
	v_mfma_f32_16x16x32_bf16 v[98:101], v[176:179], v[192:195], v[98:101]
	v_mfma_f32_16x16x32_bf16 v[86:89], v[158:161], v[196:199], v[86:89]
	v_mfma_f32_16x16x32_bf16 v[86:89], v[168:171], v[200:203], v[86:89]
	v_mfma_f32_16x16x32_bf16 v[82:85], v[172:175], v[196:199], v[82:85]
	v_mfma_f32_16x16x32_bf16 v[82:85], v[176:179], v[200:203], v[82:85]
	v_mfma_f32_16x16x32_bf16 v[70:73], v[158:161], v[224:227], v[70:73]
	v_mfma_f32_16x16x32_bf16 v[70:73], v[168:171], v[228:231], v[70:73]
	v_mfma_f32_16x16x32_bf16 v[66:69], v[172:175], v[224:227], v[66:69]
	v_mfma_f32_16x16x32_bf16 v[66:69], v[176:179], v[228:231], v[66:69]
	s_setprio 0
	s_barrier
; #define PG8_STAGE(bufoff, gbase, voff) do { _Pragma("unroll") for (int _i = 0; _i < 2; ++_i) \
;         __builtin_amdgcn_global_load_lds((const unsigned*)((const char*)(gbase) + (voff)[_i]), (PG8_LAS unsigned*)(lds + (bufoff) + ldsw + _i * 8192), 16, 0, 0); } while (0)
; #define PG8_LDA(dst, b, h) do { _Pragma("unroll") for (int m = 0; m < 4; ++m) _Pragma("unroll") for (int k = 0; k < 2; ++k) dst[m][k] = *(const PG8_LAS bf16x8*)(lds + PG8_SA(b, h) + aoff + m * 2048 + k * 1024); } while (0)
; #define PG8_MMA(ai, bj, At, Bt) do { __builtin_amdgcn_s_setprio(1); _Pragma("unroll") for (int m = 0; m < 4; ++m) _Pragma("unroll") for (int n = 0; n < 2; ++n) _Pragma("unroll") for (int k = 0; k < 2; ++k) \
;         acc[ai][bj][m][n] = __builtin_amdgcn_mfma_f32_16x16x32_bf16(Bt[n][k], At[m][k], acc[ai][bj][m][n], 0, 0, 0); __builtin_amdgcn_s_setprio(0); } while (0)
; #define PG8_WAIT_V(n) asm volatile("s_waitcnt vmcnt(" #n ")" ::: "memory")
; #define PG8_WAIT_L(n) asm volatile("s_waitcnt lgkmcnt(" #n ")" ::: "memory")
; #define PG8_BAR __builtin_amdgcn_s_barrier()
; #define PG8_SCHED __builtin_amdgcn_sched_barrier(0)
; template <class Epi, class Sched, bool ALIGN_EPI = false, bool SP2 = false>
; __device__ __forceinline__ void gemm_phase(PG8_LAS unsigned char* lds, const Gemm g, const Sched S, const Epi E) {
;     ...
;             PG8_LDA(At, 1, 1); PG8_STAGE(PG8_SB(1, 0), b3, voffB); PG8_STAGE(PG8_SB(1, 1), b3 + hstep, voffB); PG8_STAGE(PG8_SA(1, 0), a3, voffA);
;             PG8_WAIT_V(8); PG8_WAIT_L(0); PG8_BAR; PG8_MMA(1, 0, At, B0); PG8_MMA(1, 1, At, B1); PG8_BAR; PG8_SCHED;
;     ...
;         if constexpr (ALIGN_EPI) { if (wr == 0) PG8_BAR; }
	ds_read_b128 v[180:183], v145 offset:49152
	ds_read_b128 v[184:187], v145 offset:50176
	ds_read_b128 v[188:191], v145 offset:51200
	ds_read_b128 v[192:195], v145 offset:52224
	ds_read_b128 v[196:199], v145 offset:53248
	ds_read_b128 v[200:203], v145 offset:54272
	ds_read_b128 v[224:227], v145 offset:55296
	ds_read_b128 v[228:231], v145 offset:56320
	s_add_i32 s25, s25, s16
	v_lshl_add_u64 v[140:141], v[140:141], 0, s[28:29]
	s_mov_b32 m0, s25
	s_nop 0
	global_load_lds_dwordx4 v[140:141], off
	s_add_i32 m0, s25, 0x2000
	s_add_u32 s26, s58, 0x80080
	v_lshl_add_u64 v[140:141], v[232:233], 0, s[28:29]
	s_addc_u32 s27, s59, 0
	s_add_i32 s25, s30, s16
	global_load_lds_dwordx4 v[140:141], off
	v_lshl_add_u64 v[140:141], s[26:27], 0, v[0:1]
	s_mov_b32 m0, s25
	s_nop 0
	global_load_lds_dwordx4 v[140:141], off
	v_lshl_add_u64 v[140:141], s[26:27], 0, v[130:131]
	s_add_i32 m0, s25, 0x2000
	s_nop 0
	global_load_lds_dwordx4 v[140:141], off
	v_lshl_add_u64 v[140:141], v[234:235], 0, s[28:29]
	s_mov_b32 m0, s63
	s_nop 0
	global_load_lds_dwordx4 v[140:141], off
	v_lshl_add_u64 v[140:141], v[236:237], 0, s[28:29]
	s_mov_b32 m0, s66
	s_nop 0
	global_load_lds_dwordx4 v[140:141], off
	s_waitcnt vmcnt(8)
	s_waitcnt lgkmcnt(0)
	s_barrier
	s_setprio 1
	v_mfma_f32_16x16x32_bf16 v[62:65], v[136:139], v[180:183], v[62:65]
	v_mfma_f32_16x16x32_bf16 v[62:65], v[146:149], v[184:187], v[62:65]
	v_mfma_f32_16x16x32_bf16 v[58:61], v[150:153], v[180:183], v[58:61]
	v_mfma_f32_16x16x32_bf16 v[58:61], v[154:157], v[184:187], v[58:61]
	v_mfma_f32_16x16x32_bf16 v[46:49], v[136:139], v[188:191], v[46:49]
	v_mfma_f32_16x16x32_bf16 v[46:49], v[146:149], v[192:195], v[46:49]
	v_mfma_f32_16x16x32_bf16 v[42:45], v[150:153], v[188:191], v[42:45]
	v_mfma_f32_16x16x32_bf16 v[42:45], v[154:157], v[192:195], v[42:45]
	v_mfma_f32_16x16x32_bf16 v[30:33], v[136:139], v[196:199], v[30:33]
	v_mfma_f32_16x16x32_bf16 v[30:33], v[146:149], v[200:203], v[30:33]
	v_mfma_f32_16x16x32_bf16 v[26:29], v[150:153], v[196:199], v[26:29]
	v_mfma_f32_16x16x32_bf16 v[26:29], v[154:157], v[200:203], v[26:29]
	v_mfma_f32_16x16x32_bf16 v[14:17], v[136:139], v[224:227], v[14:17]
	v_mfma_f32_16x16x32_bf16 v[14:17], v[146:149], v[228:231], v[14:17]
	v_mfma_f32_16x16x32_bf16 v[10:13], v[150:153], v[224:227], v[10:13]
	v_mfma_f32_16x16x32_bf16 v[10:13], v[154:157], v[228:231], v[10:13]
	v_mfma_f32_16x16x32_bf16 v[54:57], v[158:161], v[180:183], v[54:57]
	v_mfma_f32_16x16x32_bf16 v[54:57], v[168:171], v[184:187], v[54:57]
	v_mfma_f32_16x16x32_bf16 v[50:53], v[172:175], v[180:183], v[50:53]
	v_mfma_f32_16x16x32_bf16 v[50:53], v[176:179], v[184:187], v[50:53]
	v_mfma_f32_16x16x32_bf16 v[38:41], v[158:161], v[188:191], v[38:41]
	v_mfma_f32_16x16x32_bf16 v[38:41], v[168:171], v[192:195], v[38:41]
	v_mfma_f32_16x16x32_bf16 v[34:37], v[172:175], v[188:191], v[34:37]
	v_mfma_f32_16x16x32_bf16 v[34:37], v[176:179], v[192:195], v[34:37]
	v_mfma_f32_16x16x32_bf16 v[22:25], v[158:161], v[196:199], v[22:25]
	v_mfma_f32_16x16x32_bf16 v[22:25], v[168:171], v[200:203], v[22:25]
	v_mfma_f32_16x16x32_bf16 v[18:21], v[172:175], v[196:199], v[18:21]
	v_mfma_f32_16x16x32_bf16 v[18:21], v[176:179], v[200:203], v[18:21]
	v_mfma_f32_16x16x32_bf16 v[6:9], v[158:161], v[224:227], v[6:9]
	v_mfma_f32_16x16x32_bf16 v[6:9], v[168:171], v[228:231], v[6:9]
	v_mfma_f32_16x16x32_bf16 v[2:5], v[172:175], v[224:227], v[2:5]
	v_mfma_f32_16x16x32_bf16 v[2:5], v[176:179], v[228:231], v[2:5]
	s_setprio 0
	s_barrier
	s_add_i32 s24, s24, 2
	s_add_u32 s14, s14, 0x100
	s_addc_u32 s15, s15, 0
	s_cmp_gt_u32 s24, 29
	s_mov_b64 s[52:53], s[56:57]
	s_cbranch_scc0 .LBB0_2074
	s_and_b64 vcc, exec, s[38:39]
	s_cbranch_vccz .LBB0_2077
	s_barrier
